# sample retention units: first 16 state-row loads issued right after the q/k/v loads, before the LDS prologue
# speedup vs baseline: 1.0159x; 1.0132x over previous
; #define LAS __attribute__((address_space(3)))
; __device__ __forceinline__ int launder(int v) { asm volatile("" : "+v"(v)); return v; }
; __device__ __forceinline__ float lg2gamma(int h) { return log1pf(-exp2f(-5.0f - (float)h)) * 1.4426950408889634f; }
; __device__ void sample_ret_unit(const Params& p, int l, int unit, LAS unsigned char* lds, const int tid_in) {
;     ...
;     const float lg = lg2gamma(h);
;     LAS float* sq = (LAS float*)lds; LAS float* sk = sq + 2048; LAS float* sv = sk + 2048; LAS float* sqT = sv + 2048; LAS float* skdT = sqT + 2048; LAS float* sc = skdT + 2048; LAS float* red = (LAS float*)(lds + 49152);
;     const bf16_t* zb = (const bf16_t*)(pws(p) + OFF_ZB);
;     { const int i = tid >> 6, d = (tid & 63) * 4; const bf16_t* zr = zb + (size_t)(r0 + i) * ZW + h * 256 + d;
;         const u32x2 a = *(const u32x2*)(zr + ZC_Q), kk = *(const u32x2*)(zr + ZC_K), vv = *(const u32x2*)(zr + ZC_V);
;     ...
;     for (int u = 0; u < 8; ++u) S4[u] = __builtin_nontemporal_load((const f32x4*)(Sin + (size_t)(wid * 32 + u) * 256 + e4));
; #pragma unroll
;     for (int dd = 0; dd < 32; dd += 8) {
;         const int d0 = launder(wid * 32 + dd);
;         const int dn = dd + 8 < 32 ? d0 + 8 : d0;
; #pragma unroll
;         for (int u = 0; u < 8; ++u) N4[u] = __builtin_nontemporal_load((const f32x4*)(Sin + (size_t)(dn + u) * 256 + e4));
.LBB0_522:
	s_and_b64 vcc, exec, s[0:1]
	s_cbranch_vccz .LBB0_544
	v_mov_b32_e32 v0, v244
	s_and_b32 s9, s38, 7
	v_ashrrev_i32_e32 v138, 6, v0
	v_and_b32_e32 v139, 63, v0
	v_cvt_f32_ubyte0_e32 v0, s9
	v_sub_f32_e32 v0, 0xc0a00000, v0
	v_cmp_gt_f32_e32 vcc, s75, v0
	s_and_b32 s8, s38, -8
	s_and_b64 s[0:1], vcc, exec
	s_waitcnt vmcnt(0)
	v_cndmask_b32_e32 v2, 0, v237, vcc
	v_add_f32_e32 v0, v0, v2
	v_exp_f32_e32 v0, v0
	s_cselect_b32 s0, 0xffffffc0, 0
	s_lshl_b32 s90, s9, 9
	v_ldexp_f32 v10, v0, s0
	v_sub_f32_e32 v0, 1.0, v10
	v_add_f32_e32 v2, -1.0, v0
	v_sub_f32_e32 v3, v2, v0
	v_add_f32_e32 v3, 1.0, v3
	v_sub_f32_e64 v2, -v10, v2
	v_add_f32_e32 v4, v2, v3
	v_frexp_mant_f32_e32 v5, v0
	v_cvt_f64_f32_e32 v[2:3], v0
	s_mov_b32 s0, 0x3f2aaaab
	v_frexp_exp_i32_f64_e32 v2, v[2:3]
	v_cmp_gt_f32_e32 vcc, s0, v5
	v_readlane_b32 s0, v253, 19
	v_readlane_b32 s1, v253, 20
	v_subbrev_co_u32_e32 v11, vcc, 0, v2, vcc
	v_sub_u32_e32 v2, 0, v11
	v_ldexp_f32 v0, v0, v2
	v_add_f32_e32 v3, -1.0, v0
	v_add_f32_e32 v6, 1.0, v0
	v_ldexp_f32 v2, v4, v2
	v_add_f32_e32 v4, 1.0, v3
	v_add_f32_e32 v7, -1.0, v6
	v_sub_f32_e32 v4, v0, v4
	v_sub_f32_e32 v0, v0, v7
	v_add_f32_e32 v0, v2, v0
	v_add_f32_e32 v12, v6, v0
	v_rcp_f32_e32 v14, v12
	v_add_f32_e32 v4, v2, v4
	v_add_f32_e32 v5, v3, v4
	v_sub_f32_e32 v2, v12, v6
	v_mul_f32_e32 v15, v5, v14
	v_sub_f32_e32 v13, v0, v2
	v_mul_f32_e32 v0, v12, v15
	v_fma_f32 v9, v15, v12, -v0
	v_fmac_f32_e32 v9, v15, v13
	v_add_f32_e32 v2, v0, v9
	v_sub_f32_e32 v17, v5, v2
	v_sub_f32_e32 v3, v5, v3
	v_sub_f32_e32 v16, v2, v0
	v_sub_f32_e32 v0, v5, v17
	v_sub_f32_e32 v8, v4, v3
	v_sub_f32_e32 v18, v0, v2
	v_add_u32_e32 v0, s8, v138
	v_mov_b64_e32 v[2:3], s[0:1]
	v_mad_i64_i32 v[140:141], s[0:1], v0, s74, v[2:3]
	v_lshl_add_u64 v[2:3], v[140:141], 0, s[90:91]
	v_lshlrev_b32_e32 v0, 3, v139
	v_lshl_add_u64 v[2:3], v[2:3], 0, v[0:1]
	s_movk_i32 s0, 0x2000
	v_add_f32_e32 v0, v8, v18
	v_sub_f32_e32 v8, v16, v9
	v_add_co_u32_e32 v4, vcc, s0, v2
	v_add_f32_e32 v0, v8, v0
	s_nop 0
	v_addc_co_u32_e32 v5, vcc, 0, v3, vcc
	v_add_f32_e32 v16, v17, v0
	global_load_dwordx2 v[6:7], v[4:5], off offset:-4096
	global_load_dwordx2 v[8:9], v[4:5], off
	v_mul_f32_e32 v18, v14, v16
	v_mul_f32_e32 v4, v12, v18
	v_fma_f32 v5, v18, v12, -v4
	v_fmac_f32_e32 v5, v18, v13
	v_sub_f32_e32 v12, v17, v16
	v_add_f32_e32 v0, v0, v12
	v_add_f32_e32 v12, v4, v5
	v_sub_f32_e32 v17, v16, v12
	s_movk_i32 s0, 0x3000
	v_sub_f32_e32 v13, v16, v17
	v_add_co_u32_e32 v2, vcc, s0, v2
	v_sub_f32_e32 v4, v12, v4
	v_sub_f32_e32 v12, v13, v12
	v_addc_co_u32_e32 v3, vcc, 0, v3, vcc
	v_add_f32_e32 v0, v0, v12
	global_load_dwordx2 v[12:13], v[2:3], off
	s_ashr_i32 s12, s38, 3
	s_ashr_i32 s13, s12, 31
	s_lshl_b64 s[12:13], s[12:13], 3
	s_add_u32 s12, s12, s26
	s_addc_u32 s13, s13, s27
	s_or_b32 s12, s12, s9
	s_lshl_b64 s[12:13], s[12:13], 18
	s_add_u32 s12, s50, s12
	s_addc_u32 s13, s51, s13
	v_lshlrev_b32_e32 v102, 4, v139
	v_lshl_add_u32 v102, v138, 15, v102
	s_add_u32 s14, s12, 0x1000
	s_addc_u32 s15, s13, 0
	s_add_u32 s16, s12, 0x2000
	s_addc_u32 s17, s13, 0
	s_add_u32 s18, s12, 0x3000
	s_addc_u32 s19, s13, 0
	global_load_dwordx4 v[86:89], v102, s[12:13] nt
	global_load_dwordx4 v[78:81], v102, s[12:13] offset:1024 nt
	global_load_dwordx4 v[74:77], v102, s[12:13] offset:2048 nt
	global_load_dwordx4 v[62:65], v102, s[12:13] offset:3072 nt
	global_load_dwordx4 v[54:57], v102, s[14:15] nt
	global_load_dwordx4 v[38:41], v102, s[14:15] offset:1024 nt
	global_load_dwordx4 v[46:49], v102, s[14:15] offset:2048 nt
	global_load_dwordx4 v[98:101], v102, s[14:15] offset:3072 nt
	global_load_dwordx4 v[90:93], v102, s[16:17] nt
	global_load_dwordx4 v[82:85], v102, s[16:17] offset:1024 nt
	global_load_dwordx4 v[70:73], v102, s[16:17] offset:2048 nt
	global_load_dwordx4 v[66:69], v102, s[16:17] offset:3072 nt
	global_load_dwordx4 v[58:61], v102, s[18:19] nt
	global_load_dwordx4 v[50:53], v102, s[18:19] offset:1024 nt
	global_load_dwordx4 v[42:45], v102, s[18:19] offset:2048 nt
	global_load_dwordx4 v[34:37], v102, s[18:19] offset:3072 nt
	v_sub_f32_e32 v2, v4, v5
	v_cvt_f32_i32_e32 v4, v11
	v_add_f32_e32 v0, v2, v0
	v_add_f32_e32 v2, v15, v18
	v_add_f32_e32 v0, v17, v0
	v_sub_f32_e32 v3, v2, v15
	v_mul_f32_e32 v0, v14, v0
	v_sub_f32_e32 v3, v18, v3
	v_add_f32_e32 v0, v3, v0
	v_mul_f32_e32 v14, 0x3f317218, v4
	s_mov_b32 s0, 0x3f317218
	v_add_f32_e32 v3, v2, v0
	v_fma_f32 v15, v4, s0, -v14
	v_mul_f32_e32 v5, v3, v3
	v_fmac_f32_e32 v15, 0xb102e308, v4
	v_sub_f32_e32 v2, v3, v2
	v_fmamk_f32 v11, v5, 0x3e9b6dac, v234
	v_sub_f32_e32 v0, v0, v2
	v_add_f32_e32 v2, v14, v15
	v_fmaak_f32 v11, v5, v11, 0x3f2aaada
	v_sub_f32_e32 v4, v2, v14
	v_ldexp_f32 v14, v3, 1
	v_mul_f32_e32 v3, v3, v5
	v_mul_f32_e32 v3, v3, v11
	v_add_f32_e32 v5, v14, v3
	v_sub_f32_e32 v11, v5, v14
	v_ldexp_f32 v0, v0, 1
	v_sub_f32_e32 v3, v3, v11
	v_add_f32_e32 v0, v0, v3
	v_add_f32_e32 v3, v5, v0
	v_sub_f32_e32 v5, v3, v5
	v_sub_f32_e32 v0, v0, v5
	v_add_f32_e32 v5, v2, v3
	v_sub_f32_e32 v11, v5, v2
	v_sub_f32_e32 v14, v5, v11
	v_sub_f32_e32 v4, v15, v4
	v_sub_f32_e32 v2, v2, v14
	v_sub_f32_e32 v3, v3, v11
	v_add_f32_e32 v2, v3, v2
	v_add_f32_e32 v3, v4, v0
	v_sub_f32_e32 v11, v3, v4
	v_sub_f32_e32 v14, v3, v11
	v_add_f32_e32 v2, v3, v2
	v_sub_f32_e32 v4, v4, v14
	v_sub_f32_e32 v0, v0, v11
	v_add_f32_e32 v3, v5, v2
	v_add_f32_e32 v0, v0, v4
	v_sub_f32_e32 v4, v3, v5
	v_sub_f32_e32 v2, v2, v4
	v_add_f32_e32 v0, v0, v2
	v_add_f32_e32 v0, v3, v0
	v_cmp_nlt_f32_e32 vcc, 1.0, v10
	s_mov_b32 s0, 0x33800000
	v_lshl_add_u32 v14, v138, 10, 0
	v_cndmask_b32_e32 v0, v238, v0, vcc
	v_cmp_neq_f32_e32 vcc, 1.0, v10
	v_lshlrev_b32_e32 v15, 4, v139
	v_add_u32_e32 v16, v14, v15
	v_cndmask_b32_e32 v0, v239, v0, vcc
	v_cmp_gt_f32_e32 vcc, s0, v10
	s_waitcnt vmcnt(16)
; #define LAS __attribute__((address_space(3)))
; __device__ __forceinline__ float bf_lo(unsigned u) { return __uint_as_float(u << 16); }
; __device__ __forceinline__ float bf_hi(unsigned u) { return __uint_as_float(u & 0xffff0000u); }
; __device__ void sample_ret_unit(const Params& p, int l, int unit, LAS unsigned char* lds, const int tid_in) {
;     ...
;         const float qf[4] = {bf_lo(a.x), bf_hi(a.x), bf_lo(a.y), bf_hi(a.y)}, kf[4] = {bf_lo(kk.x), bf_hi(kk.x), bf_lo(kk.y), bf_hi(kk.y)};
;         const float dk = exp2f(lg * (float)(7 - i));
;         *(LAS f32x4*)(sq + i * 256 + d) = (f32x4){qf[0], qf[1], qf[2], qf[3]};
;         *(LAS f32x4*)(sk + i * 256 + d) = (f32x4){kf[0], kf[1], kf[2], kf[3]};
;         *(LAS f32x4*)(sv + i * 256 + d) = (f32x4){bf_lo(vv.x), bf_hi(vv.x), bf_lo(vv.y), bf_hi(vv.y)};
; #pragma unroll
;         for (int j = 0; j < 4; ++j) { sqT[(d + j) * 8 + i] = qf[j]; skdT[(d + j) * 8 + i] = kf[j] * dk; } }
;     __syncthreads();
;     { const int i = wid; const f32x4 qv = *(const LAS f32x4*)(sq + i * 256 + lane * 4);
;         for (int j = 0; j < 8; ++j) { const f32x4 kv = *(const LAS f32x4*)(sk + j * 256 + lane * 4);
;             float s = wave_sum(qv[0] * kv[0] + qv[1] * kv[1] + qv[2] * kv[2] + qv[3] * kv[3]);
;             if (lane == 0) sc[i * 8 + j] = j <= i ? s * exp2f(lg * (float)(i - j)) : 0.f; } }
	v_lshlrev_b32_e32 v2, 16, v6
	v_and_b32_e32 v3, 0xffff0000, v6
	v_cndmask_b32_e64 v0, v0, -v10, vcc
	v_mul_f32_e32 v145, 0x3fb8aa3b, v0
	v_sub_u32_e32 v0, 7, v138
	v_cvt_f32_i32_e32 v0, v0
	v_lshlrev_b32_e32 v4, 16, v7
	v_and_b32_e32 v5, 0xffff0000, v7
	v_lshlrev_b32_e32 v6, 16, v8
	v_and_b32_e32 v7, 0xffff0000, v8
	v_mul_f32_e32 v8, v145, v0
	v_cmp_gt_f32_e32 vcc, s75, v8
	v_add_u32_e32 v18, 0, v15
	s_movk_i32 s0, 0xfc20
	v_cndmask_b32_e32 v8, 0, v237, vcc
	v_fmac_f32_e32 v8, v145, v0
	v_exp_f32_e32 v0, v8
	v_cndmask_b32_e32 v10, 0, v240, vcc
	v_lshlrev_b32_e32 v8, 16, v9
	v_and_b32_e32 v11, 0xffff0000, v12
	v_ldexp_f32 v0, v0, v10
	v_lshlrev_b32_e32 v10, 16, v12
	v_lshlrev_b32_e32 v12, 16, v13
	v_and_b32_e32 v13, 0xffff0000, v13
	v_and_b32_e32 v9, 0xffff0000, v9
	ds_write_b128 v16, v[2:5]
	ds_write_b128 v16, v[6:9] offset:8192
	ds_write_b128 v16, v[10:13] offset:16384
	v_lshl_add_u32 v10, v139, 5, v138
	v_lshl_add_u32 v10, v10, 2, 0
	v_add_u32_e32 v11, 0x6000, v10
	v_mul_f32_e32 v6, v0, v6
	ds_write2_b32 v11, v2, v3 offset1:8
	v_mul_f32_e32 v2, v0, v7
	v_add_u32_e32 v3, 0x8000, v10
	ds_write2_b32 v3, v6, v2 offset1:8
	v_mul_f32_e32 v2, v0, v8
	v_mul_f32_e32 v0, v0, v9
	ds_write2_b32 v11, v4, v5 offset0:16 offset1:24
	ds_write2_b32 v3, v2, v0 offset0:16 offset1:24
	s_waitcnt lgkmcnt(0)
	s_barrier
	ds_read_b128 v[2:5], v16
	ds_read_b128 v[6:9], v18 offset:8192
	v_mul_lo_u32 v0, v138, s0
	v_cmp_eq_u32_e32 vcc, 0, v139
	v_add_u32_e32 v0, v14, v0
	s_waitcnt lgkmcnt(0)
	v_mul_f32_e32 v7, v3, v7
	v_fmac_f32_e32 v7, v2, v6
	v_fmac_f32_e32 v7, v4, v8
	v_fmac_f32_e32 v7, v5, v9
	s_nop 1
	v_add_f32_dpp v6, v7, v7 quad_perm:[1,0,3,2] row_mask:0xf bank_mask:0xf bound_ctrl:1
	s_nop 1
	v_add_f32_dpp v6, v6, v6 quad_perm:[2,3,0,1] row_mask:0xf bank_mask:0xf bound_ctrl:1
	s_nop 1
	v_add_f32_dpp v6, v6, v6 row_half_mirror row_mask:0xf bank_mask:0xf bound_ctrl:1
	s_nop 1
	v_add_f32_dpp v6, v6, v6 row_mirror row_mask:0xf bank_mask:0xf bound_ctrl:1
	s_nop 0
	v_readlane_b32 s6, v6, 0
	v_readlane_b32 s10, v6, 16
	v_readlane_b32 s7, v6, 32
	v_readlane_b32 s11, v6, 48
	s_and_saveexec_b64 s[0:1], vcc
	s_cbranch_execz .LBB0_525
	v_mov_b32_e32 v6, s10
	v_mov_b32_e32 v7, s11
	v_pk_add_f32 v[6:7], s[6:7], v[6:7]
	s_nop 0
	v_add_f32_e32 v6, v6, v7
	v_cvt_f32_i32_e32 v7, v138
	v_mul_f32_e32 v8, v145, v7
	v_cmp_gt_f32_e64 s[6:7], s75, v8
	s_nop 1
	v_cndmask_b32_e64 v9, 0, v237, s[6:7]
	v_fmac_f32_e32 v9, v145, v7
	v_exp_f32_e32 v7, v9
	v_cndmask_b32_e64 v8, 0, v240, s[6:7]
	v_cmp_lt_i32_e64 s[6:7], -1, v138
	v_ldexp_f32 v7, v7, v8
	v_mul_f32_e32 v6, v7, v6
	v_cndmask_b32_e64 v6, 0, v6, s[6:7]
	ds_write_b32 v0, v6 offset:40960

; #define LAS __attribute__((address_space(3)))
; __device__ __forceinline__ int launder(int v) { asm volatile("" : "+v"(v)); return v; }
; __device__ void sample_ret_unit(const Params& p, int l, int unit, LAS unsigned char* lds, const int tid_in) {
;     ...
;     const int e4 = lane * 4;
;     f32x4 vv[8], oacc[8];
; #pragma unroll
;     for (int j = 0; j < 8; ++j) { vv[j] = *(const LAS f32x4*)(sv + j * 256 + e4); oacc[j] = (f32x4){0.f, 0.f, 0.f, 0.f}; }
;     const float g8 = exp2f(lg * 8.0f);
;     const size_t sbase = (((size_t)l * 128 + b) * 8 + h) * 65536;
;     const float* Sin = p.state_ret + sbase; float* Sout = pout(p) + O_RS + sbase;
;     f32x4 S4[8], N4[8];
; #pragma unroll
;     for (int u = 0; u < 8; ++u) S4[u] = __builtin_nontemporal_load((const f32x4*)(Sin + (size_t)(wid * 32 + u) * 256 + e4));
; #pragma unroll
;     for (int dd = 0; dd < 32; dd += 8) {
;         const int d0 = launder(wid * 32 + dd);
;         const int dn = dd + 8 < 32 ? d0 + 8 : d0;
; #pragma unroll
;         for (int u = 0; u < 8; ++u) N4[u] = __builtin_nontemporal_load((const f32x4*)(Sin + (size_t)(dn + u) * 256 + e4));
;         asm volatile("" ::: "memory");
; #pragma unroll
;         for (int u = 0; u < 8; ++u) {
;             const f32x4 q0 = *(const LAS f32x4*)(sqT + (d0 + u) * 8), q1 = *(const LAS f32x4*)(sqT + (d0 + u) * 8 + 4);
;             const f32x4 k0 = *(const LAS f32x4*)(skdT + (d0 + u) * 8), k1 = *(const LAS f32x4*)(skdT + (d0 + u) * 8 + 4);
;             f32x4 sn = S4[u] * g8;
;             sn += vv[0] * k0[0]; sn += vv[1] * k0[1]; sn += vv[2] * k0[2]; sn += vv[3] * k0[3];
;             sn += vv[4] * k1[0]; sn += vv[5] * k1[1]; sn += vv[6] * k1[2]; sn += vv[7] * k1[3];
;             __builtin_nontemporal_store(sn, (f32x4*)(Sout + (size_t)(d0 + u) * 256 + e4));
;             oacc[0] += S4[u] * q0[0]; oacc[1] += S4[u] * q0[1]; oacc[2] += S4[u] * q0[2]; oacc[3] += S4[u] * q0[3];
;             oacc[4] += S4[u] * q1[0]; oacc[5] += S4[u] * q1[1]; oacc[6] += S4[u] * q1[2]; oacc[7] += S4[u] * q1[3];
;         }
.LBB0_539:
	s_or_b64 exec, exec, s[0:1]
	s_ashr_i32 s0, s38, 3
	s_ashr_i32 s1, s0, 31
	s_lshl_b64 s[0:1], s[0:1], 3
	s_add_u32 s0, s0, s26
	s_addc_u32 s1, s1, s27
	s_or_b32 s0, s0, s9
	s_lshl_b64 s[0:1], s[0:1], 18
	v_lshlrev_b32_e32 v180, 2, v139
	v_lshlrev_b32_e32 v142, 5, v138
	s_add_u32 s6, s50, s0
	s_addc_u32 s7, s51, s1
	v_lshlrev_b32_e32 v0, 2, v180
	v_ashrrev_i32_e32 v143, 31, v142
	v_lshl_add_u64 v[148:149], s[6:7], 0, v[0:1]
	ds_read_b128 v[14:17], v18 offset:16384
	ds_read_b128 v[10:13], v18 offset:17408
	ds_read_b128 v[6:9], v18 offset:18432
	ds_read_b128 v[2:5], v18 offset:19456
	ds_read_b128 v[30:33], v18 offset:20480
	ds_read_b128 v[26:29], v18 offset:21504
	ds_read_b128 v[22:25], v18 offset:22528
	ds_read_b128 v[18:21], v18 offset:23552
	v_mul_f32_e32 v103, 0x41000000, v145
	v_cmp_gt_f32_e32 vcc, s75, v103
	v_cndmask_b32_e32 v103, 0, v237, vcc
	v_fmac_f32_e32 v103, 0x41000000, v145
	v_exp_f32_e32 v103, v103
	s_and_b64 s[6:7], vcc, exec
	s_cselect_b32 s6, 0xffffffc0, 0
	v_mov_b32_e32 v150, v142
	v_ldexp_f32 v144, v103, s6
	v_readlane_b32 s6, v253, 45
	s_add_u32 s0, s6, s0
	v_ashrrev_i32_e32 v151, 31, v150
	v_readlane_b32 s6, v253, 46
	v_lshlrev_b64 v[114:115], 10, v[150:151]
	s_addc_u32 s1, s6, s1
	s_movk_i32 s6, 0x2000
	s_movk_i32 s7, 0x3000
	s_nop 0
	v_lshl_add_u32 v110, v150, 5, 0
	s_nop 0
	s_nop 0
	ds_read_b128 v[106:109], v110 offset:32768
	ds_read_b128 v[102:105], v110 offset:24576
	ds_read_b128 v[94:97], v110 offset:24592
	ds_read_b128 v[110:113], v110 offset:32784
	v_lshl_add_u64 v[146:147], s[0:1], 0, v[0:1]
	v_add_u32_e32 v124, 1, v150
	v_ashrrev_i32_e32 v125, 31, v124
	s_waitcnt lgkmcnt(3)
	v_pk_mul_f32 v[116:117], v[16:17], v[106:107] op_sel_hi:[1,0]
	v_pk_mul_f32 v[118:119], v[14:15], v[106:107] op_sel_hi:[1,0]
	v_add_u32_e32 v132, 2, v150
	v_ashrrev_i32_e32 v133, 31, v132
	v_add_u32_e32 v154, 3, v150
	v_ashrrev_i32_e32 v155, 31, v154
	v_add_u32_e32 v162, 4, v150
	v_ashrrev_i32_e32 v163, 31, v162
	v_add_u32_e32 v170, 5, v150
	v_ashrrev_i32_e32 v171, 31, v170
	v_add_u32_e32 v178, 6, v150
	s_waitcnt vmcnt(15)
	v_pk_fma_f32 v[116:117], v[144:145], v[88:89], v[116:117] op_sel_hi:[0,1,1]
	v_pk_fma_f32 v[118:119], v[144:145], v[86:87], v[118:119] op_sel_hi:[0,1,1]
	v_pk_fma_f32 v[116:117], v[12:13], v[106:107], v[116:117] op_sel:[0,1,0]
	v_pk_fma_f32 v[106:107], v[10:11], v[106:107], v[118:119] op_sel:[0,1,0]
	v_pk_fma_f32 v[116:117], v[8:9], v[108:109], v[116:117] op_sel_hi:[1,0,1]
	v_pk_fma_f32 v[106:107], v[6:7], v[108:109], v[106:107] op_sel_hi:[1,0,1]
	v_mov_b32_e32 v108, v109
	v_pk_fma_f32 v[116:117], v[4:5], v[108:109], v[116:117] op_sel_hi:[1,0,1]
	v_pk_fma_f32 v[106:107], v[2:3], v[108:109], v[106:107] op_sel_hi:[1,0,1]
	s_waitcnt lgkmcnt(0)
	v_pk_fma_f32 v[108:109], v[32:33], v[110:111], v[116:117] op_sel_hi:[1,0,1]
	v_pk_fma_f32 v[106:107], v[30:31], v[110:111], v[106:107] op_sel_hi:[1,0,1]
	v_pk_fma_f32 v[108:109], v[28:29], v[110:111], v[108:109] op_sel:[0,1,0]
	v_pk_fma_f32 v[106:107], v[26:27], v[110:111], v[106:107] op_sel:[0,1,0]
	v_pk_fma_f32 v[108:109], v[24:25], v[112:113], v[108:109] op_sel_hi:[1,0,1]
	v_pk_fma_f32 v[106:107], v[22:23], v[112:113], v[106:107] op_sel_hi:[1,0,1]
	v_mov_b32_e32 v110, v113
	v_pk_fma_f32 v[108:109], v[20:21], v[110:111], v[108:109] op_sel_hi:[1,0,1]
	v_pk_fma_f32 v[106:107], v[18:19], v[110:111], v[106:107] op_sel_hi:[1,0,1]
	v_lshl_add_u64 v[110:111], v[146:147], 0, v[114:115]
	global_store_dwordx4 v[110:111], v[106:109], off nt
	v_ashrrev_i32_e32 v179, 31, v178
	v_add_u32_e32 v188, 7, v150
	v_mov_b32_e32 v106, v97
	v_lshl_add_u32 v97, v124, 5, 0
	ds_read_b128 v[114:117], v97 offset:32768
	v_pk_fma_f32 v[122:123], v[88:89], v[106:107], 0 op_sel_hi:[1,0,0]
	v_pk_fma_f32 v[126:127], v[86:87], v[106:107], 0 op_sel_hi:[1,0,0]
	ds_read_b128 v[110:113], v97 offset:24576
	ds_read_b128 v[106:109], v97 offset:24592
	ds_read_b128 v[118:121], v97 offset:32784
	v_lshl_add_u32 v97, v132, 5, 0
	s_waitcnt lgkmcnt(3)
	v_pk_mul_f32 v[128:129], v[16:17], v[114:115] op_sel_hi:[1,0]
	v_pk_mul_f32 v[130:131], v[14:15], v[114:115] op_sel_hi:[1,0]
	s_waitcnt vmcnt(15)
	v_pk_fma_f32 v[128:129], v[144:145], v[80:81], v[128:129] op_sel_hi:[0,1,1]
	v_pk_fma_f32 v[130:131], v[144:145], v[78:79], v[130:131] op_sel_hi:[0,1,1]
	v_pk_fma_f32 v[128:129], v[12:13], v[114:115], v[128:129] op_sel:[0,1,0]
	v_pk_fma_f32 v[114:115], v[10:11], v[114:115], v[130:131] op_sel:[0,1,0]
	v_pk_fma_f32 v[128:129], v[8:9], v[116:117], v[128:129] op_sel_hi:[1,0,1]
	v_pk_fma_f32 v[114:115], v[6:7], v[116:117], v[114:115] op_sel_hi:[1,0,1]
	v_mov_b32_e32 v116, v117
	v_pk_fma_f32 v[128:129], v[4:5], v[116:117], v[128:129] op_sel_hi:[1,0,1]
	v_pk_fma_f32 v[114:115], v[2:3], v[116:117], v[114:115] op_sel_hi:[1,0,1]
	s_waitcnt lgkmcnt(0)
	v_pk_fma_f32 v[116:117], v[32:33], v[118:119], v[128:129] op_sel_hi:[1,0,1]
	v_pk_fma_f32 v[114:115], v[30:31], v[118:119], v[114:115] op_sel_hi:[1,0,1]
	v_pk_fma_f32 v[116:117], v[28:29], v[118:119], v[116:117] op_sel:[0,1,0]
	v_pk_fma_f32 v[114:115], v[26:27], v[118:119], v[114:115] op_sel:[0,1,0]
	v_pk_fma_f32 v[116:117], v[24:25], v[120:121], v[116:117] op_sel_hi:[1,0,1]
	v_pk_fma_f32 v[114:115], v[22:23], v[120:121], v[114:115] op_sel_hi:[1,0,1]
	v_mov_b32_e32 v118, v121
	v_pk_fma_f32 v[116:117], v[20:21], v[118:119], v[116:117] op_sel_hi:[1,0,1]
	v_pk_fma_f32 v[114:115], v[18:19], v[118:119], v[114:115] op_sel_hi:[1,0,1]
	v_lshlrev_b64 v[118:119], 10, v[124:125]
	v_lshl_add_u64 v[118:119], v[146:147], 0, v[118:119]
	global_store_dwordx4 v[118:119], v[114:117], off nt
	v_ashrrev_i32_e32 v189, 31, v188
	v_pk_fma_f32 v[198:199], v[86:87], v[94:95], 0 op_sel_hi:[1,0,0]
	v_mov_b32_e32 v114, v109
	v_pk_fma_f32 v[130:131], v[80:81], v[114:115], v[122:123] op_sel_hi:[1,0,1]
	ds_read_b128 v[122:125], v97 offset:32768
	v_pk_fma_f32 v[134:135], v[78:79], v[114:115], v[126:127] op_sel_hi:[1,0,1]
	ds_read_b128 v[118:121], v97 offset:24576
	ds_read_b128 v[114:117], v97 offset:24592
	ds_read_b128 v[126:129], v97 offset:32784
	v_lshl_add_u32 v97, v154, 5, 0
	v_pk_fma_f32 v[200:201], v[88:89], v[94:95], 0 op_sel:[0,1,0] op_sel_hi:[1,1,0]
	s_waitcnt lgkmcnt(3)
; #define LAS __attribute__((address_space(3)))
; __device__ void sample_ret_unit(const Params& p, int l, int unit, LAS unsigned char* lds, const int tid_in) {
;     ...
; #pragma unroll
;         for (int u = 0; u < 8; ++u) {
;             const f32x4 q0 = *(const LAS f32x4*)(sqT + (d0 + u) * 8), q1 = *(const LAS f32x4*)(sqT + (d0 + u) * 8 + 4);
;             const f32x4 k0 = *(const LAS f32x4*)(skdT + (d0 + u) * 8), k1 = *(const LAS f32x4*)(skdT + (d0 + u) * 8 + 4);
;             f32x4 sn = S4[u] * g8;
;             sn += vv[0] * k0[0]; sn += vv[1] * k0[1]; sn += vv[2] * k0[2]; sn += vv[3] * k0[3];
;             sn += vv[4] * k1[0]; sn += vv[5] * k1[1]; sn += vv[6] * k1[2]; sn += vv[7] * k1[3];
;             __builtin_nontemporal_store(sn, (f32x4*)(Sout + (size_t)(d0 + u) * 256 + e4));
;             oacc[0] += S4[u] * q0[0]; oacc[1] += S4[u] * q0[1]; oacc[2] += S4[u] * q0[2]; oacc[3] += S4[u] * q0[3];
;             oacc[4] += S4[u] * q1[0]; oacc[5] += S4[u] * q1[1]; oacc[6] += S4[u] * q1[2]; oacc[7] += S4[u] * q1[3];
;         }
	v_pk_mul_f32 v[136:137], v[16:17], v[122:123] op_sel_hi:[1,0]
	v_pk_mul_f32 v[152:153], v[14:15], v[122:123] op_sel_hi:[1,0]
	s_waitcnt vmcnt(15)
	v_pk_fma_f32 v[136:137], v[144:145], v[76:77], v[136:137] op_sel_hi:[0,1,1]
	v_pk_fma_f32 v[152:153], v[144:145], v[74:75], v[152:153] op_sel_hi:[0,1,1]
	v_pk_fma_f32 v[136:137], v[12:13], v[122:123], v[136:137] op_sel:[0,1,0]
	v_pk_fma_f32 v[122:123], v[10:11], v[122:123], v[152:153] op_sel:[0,1,0]
	v_pk_fma_f32 v[136:137], v[8:9], v[124:125], v[136:137] op_sel_hi:[1,0,1]
	v_pk_fma_f32 v[122:123], v[6:7], v[124:125], v[122:123] op_sel_hi:[1,0,1]
	v_mov_b32_e32 v124, v125
	v_pk_fma_f32 v[136:137], v[4:5], v[124:125], v[136:137] op_sel_hi:[1,0,1]
	v_pk_fma_f32 v[122:123], v[2:3], v[124:125], v[122:123] op_sel_hi:[1,0,1]
	s_waitcnt lgkmcnt(0)
	v_pk_fma_f32 v[124:125], v[32:33], v[126:127], v[136:137] op_sel_hi:[1,0,1]
	v_pk_fma_f32 v[122:123], v[30:31], v[126:127], v[122:123] op_sel_hi:[1,0,1]
	v_pk_fma_f32 v[124:125], v[28:29], v[126:127], v[124:125] op_sel:[0,1,0]
	v_pk_fma_f32 v[122:123], v[26:27], v[126:127], v[122:123] op_sel:[0,1,0]
	v_pk_fma_f32 v[124:125], v[24:25], v[128:129], v[124:125] op_sel_hi:[1,0,1]
	v_pk_fma_f32 v[122:123], v[22:23], v[128:129], v[122:123] op_sel_hi:[1,0,1]
	v_mov_b32_e32 v126, v129
	v_pk_fma_f32 v[124:125], v[20:21], v[126:127], v[124:125] op_sel_hi:[1,0,1]
	v_pk_fma_f32 v[122:123], v[18:19], v[126:127], v[122:123] op_sel_hi:[1,0,1]
	v_lshlrev_b64 v[126:127], 10, v[132:133]
	v_lshl_add_u64 v[126:127], v[146:147], 0, v[126:127]
	global_store_dwordx4 v[126:127], v[122:125], off nt
	s_nop 1
	v_mov_b32_e32 v122, v117
	v_pk_fma_f32 v[152:153], v[76:77], v[122:123], v[130:131] op_sel_hi:[1,0,1]
	ds_read_b128 v[130:133], v97 offset:32768
	v_pk_fma_f32 v[156:157], v[74:75], v[122:123], v[134:135] op_sel_hi:[1,0,1]
	ds_read_b128 v[126:129], v97 offset:24576
	ds_read_b128 v[122:125], v97 offset:24592
	ds_read_b128 v[134:137], v97 offset:32784
	v_lshl_add_u32 v97, v162, 5, 0
	s_waitcnt lgkmcnt(3)
	v_pk_mul_f32 v[158:159], v[16:17], v[130:131] op_sel_hi:[1,0]
	v_pk_mul_f32 v[160:161], v[14:15], v[130:131] op_sel_hi:[1,0]
	s_waitcnt vmcnt(15)
	v_pk_fma_f32 v[158:159], v[144:145], v[64:65], v[158:159] op_sel_hi:[0,1,1]
	v_pk_fma_f32 v[160:161], v[144:145], v[62:63], v[160:161] op_sel_hi:[0,1,1]
	v_pk_fma_f32 v[158:159], v[12:13], v[130:131], v[158:159] op_sel:[0,1,0]
	v_pk_fma_f32 v[130:131], v[10:11], v[130:131], v[160:161] op_sel:[0,1,0]
	v_pk_fma_f32 v[158:159], v[8:9], v[132:133], v[158:159] op_sel_hi:[1,0,1]
	v_pk_fma_f32 v[130:131], v[6:7], v[132:133], v[130:131] op_sel_hi:[1,0,1]
	v_mov_b32_e32 v132, v133
	v_pk_fma_f32 v[158:159], v[4:5], v[132:133], v[158:159] op_sel_hi:[1,0,1]
	v_pk_fma_f32 v[130:131], v[2:3], v[132:133], v[130:131] op_sel_hi:[1,0,1]
	s_waitcnt lgkmcnt(0)
	v_pk_fma_f32 v[132:133], v[32:33], v[134:135], v[158:159] op_sel_hi:[1,0,1]
	v_pk_fma_f32 v[130:131], v[30:31], v[134:135], v[130:131] op_sel_hi:[1,0,1]
	v_pk_fma_f32 v[132:133], v[28:29], v[134:135], v[132:133] op_sel:[0,1,0]
	v_pk_fma_f32 v[130:131], v[26:27], v[134:135], v[130:131] op_sel:[0,1,0]
	v_pk_fma_f32 v[132:133], v[24:25], v[136:137], v[132:133] op_sel_hi:[1,0,1]
	v_pk_fma_f32 v[130:131], v[22:23], v[136:137], v[130:131] op_sel_hi:[1,0,1]
	v_mov_b32_e32 v134, v137
	v_pk_fma_f32 v[132:133], v[20:21], v[134:135], v[132:133] op_sel_hi:[1,0,1]
	v_pk_fma_f32 v[130:131], v[18:19], v[134:135], v[130:131] op_sel_hi:[1,0,1]
	v_lshlrev_b64 v[134:135], 10, v[154:155]
	v_lshl_add_u64 v[134:135], v[146:147], 0, v[134:135]
	global_store_dwordx4 v[134:135], v[130:133], off nt
	s_nop 1
	v_mov_b32_e32 v130, v125
	v_pk_fma_f32 v[160:161], v[64:65], v[130:131], v[152:153] op_sel_hi:[1,0,1]
	ds_read_b128 v[152:155], v97 offset:32768
	v_pk_fma_f32 v[164:165], v[62:63], v[130:131], v[156:157] op_sel_hi:[1,0,1]
	ds_read_b128 v[134:137], v97 offset:24576
	ds_read_b128 v[130:133], v97 offset:24592
	ds_read_b128 v[156:159], v97 offset:32784
	v_lshl_add_u32 v97, v170, 5, 0
	s_waitcnt lgkmcnt(3)
	v_pk_mul_f32 v[166:167], v[16:17], v[152:153] op_sel_hi:[1,0]
	v_pk_mul_f32 v[168:169], v[14:15], v[152:153] op_sel_hi:[1,0]
	s_waitcnt vmcnt(15)
	v_pk_fma_f32 v[166:167], v[144:145], v[56:57], v[166:167] op_sel_hi:[0,1,1]
	v_pk_fma_f32 v[168:169], v[144:145], v[54:55], v[168:169] op_sel_hi:[0,1,1]
	v_pk_fma_f32 v[166:167], v[12:13], v[152:153], v[166:167] op_sel:[0,1,0]
	v_pk_fma_f32 v[152:153], v[10:11], v[152:153], v[168:169] op_sel:[0,1,0]
	v_pk_fma_f32 v[166:167], v[8:9], v[154:155], v[166:167] op_sel_hi:[1,0,1]
	v_pk_fma_f32 v[152:153], v[6:7], v[154:155], v[152:153] op_sel_hi:[1,0,1]
	v_mov_b32_e32 v154, v155
	v_pk_fma_f32 v[166:167], v[4:5], v[154:155], v[166:167] op_sel_hi:[1,0,1]
	v_pk_fma_f32 v[152:153], v[2:3], v[154:155], v[152:153] op_sel_hi:[1,0,1]
	s_waitcnt lgkmcnt(0)
	v_pk_fma_f32 v[154:155], v[32:33], v[156:157], v[166:167] op_sel_hi:[1,0,1]
	v_pk_fma_f32 v[152:153], v[30:31], v[156:157], v[152:153] op_sel_hi:[1,0,1]
	v_pk_fma_f32 v[154:155], v[28:29], v[156:157], v[154:155] op_sel:[0,1,0]
	v_pk_fma_f32 v[152:153], v[26:27], v[156:157], v[152:153] op_sel:[0,1,0]
	v_pk_fma_f32 v[154:155], v[24:25], v[158:159], v[154:155] op_sel_hi:[1,0,1]
	v_pk_fma_f32 v[152:153], v[22:23], v[158:159], v[152:153] op_sel_hi:[1,0,1]
	v_mov_b32_e32 v156, v159
	v_pk_fma_f32 v[154:155], v[20:21], v[156:157], v[154:155] op_sel_hi:[1,0,1]
	v_pk_fma_f32 v[152:153], v[18:19], v[156:157], v[152:153] op_sel_hi:[1,0,1]
	v_lshlrev_b64 v[156:157], 10, v[162:163]
	v_lshl_add_u64 v[156:157], v[146:147], 0, v[156:157]
	global_store_dwordx4 v[156:157], v[152:155], off nt
	ds_read_b128 v[152:155], v97 offset:32768
	v_mov_b32_e32 v156, v133
	v_pk_fma_f32 v[168:169], v[56:57], v[156:157], v[160:161] op_sel_hi:[1,0,1]
	v_pk_fma_f32 v[172:173], v[54:55], v[156:157], v[164:165] op_sel_hi:[1,0,1]
	ds_read_b128 v[156:159], v97 offset:24576
	ds_read_b128 v[160:163], v97 offset:24592
	ds_read_b128 v[164:167], v97 offset:32784
	s_waitcnt lgkmcnt(3)
; #define LAS __attribute__((address_space(3)))
; __device__ void sample_ret_unit(const Params& p, int l, int unit, LAS unsigned char* lds, const int tid_in) {
;     ...
; #pragma unroll
;         for (int u = 0; u < 8; ++u) {
;             const f32x4 q0 = *(const LAS f32x4*)(sqT + (d0 + u) * 8), q1 = *(const LAS f32x4*)(sqT + (d0 + u) * 8 + 4);
;             const f32x4 k0 = *(const LAS f32x4*)(skdT + (d0 + u) * 8), k1 = *(const LAS f32x4*)(skdT + (d0 + u) * 8 + 4);
;             f32x4 sn = S4[u] * g8;
;             sn += vv[0] * k0[0]; sn += vv[1] * k0[1]; sn += vv[2] * k0[2]; sn += vv[3] * k0[3];
;             sn += vv[4] * k1[0]; sn += vv[5] * k1[1]; sn += vv[6] * k1[2]; sn += vv[7] * k1[3];
;             __builtin_nontemporal_store(sn, (f32x4*)(Sout + (size_t)(d0 + u) * 256 + e4));
;             oacc[0] += S4[u] * q0[0]; oacc[1] += S4[u] * q0[1]; oacc[2] += S4[u] * q0[2]; oacc[3] += S4[u] * q0[3];
;             oacc[4] += S4[u] * q1[0]; oacc[5] += S4[u] * q1[1]; oacc[6] += S4[u] * q1[2]; oacc[7] += S4[u] * q1[3];
;         }
	v_pk_mul_f32 v[174:175], v[16:17], v[152:153] op_sel_hi:[1,0]
	v_pk_mul_f32 v[176:177], v[14:15], v[152:153] op_sel_hi:[1,0]
	s_waitcnt vmcnt(15)
	v_pk_fma_f32 v[174:175], v[144:145], v[40:41], v[174:175] op_sel_hi:[0,1,1]
	v_pk_fma_f32 v[176:177], v[144:145], v[38:39], v[176:177] op_sel_hi:[0,1,1]
	v_pk_fma_f32 v[174:175], v[12:13], v[152:153], v[174:175] op_sel:[0,1,0]
	v_pk_fma_f32 v[152:153], v[10:11], v[152:153], v[176:177] op_sel:[0,1,0]
	v_pk_fma_f32 v[174:175], v[8:9], v[154:155], v[174:175] op_sel_hi:[1,0,1]
	v_pk_fma_f32 v[152:153], v[6:7], v[154:155], v[152:153] op_sel_hi:[1,0,1]
	v_mov_b32_e32 v154, v155
	v_pk_fma_f32 v[174:175], v[4:5], v[154:155], v[174:175] op_sel_hi:[1,0,1]
	v_pk_fma_f32 v[152:153], v[2:3], v[154:155], v[152:153] op_sel_hi:[1,0,1]
	s_waitcnt lgkmcnt(0)
	v_pk_fma_f32 v[154:155], v[32:33], v[164:165], v[174:175] op_sel_hi:[1,0,1]
	v_pk_fma_f32 v[152:153], v[30:31], v[164:165], v[152:153] op_sel_hi:[1,0,1]
	v_pk_fma_f32 v[154:155], v[28:29], v[164:165], v[154:155] op_sel:[0,1,0]
	v_pk_fma_f32 v[152:153], v[26:27], v[164:165], v[152:153] op_sel:[0,1,0]
	v_pk_fma_f32 v[154:155], v[24:25], v[166:167], v[154:155] op_sel_hi:[1,0,1]
	v_pk_fma_f32 v[152:153], v[22:23], v[166:167], v[152:153] op_sel_hi:[1,0,1]
	v_mov_b32_e32 v164, v167
	v_pk_fma_f32 v[154:155], v[20:21], v[164:165], v[154:155] op_sel_hi:[1,0,1]
	v_pk_fma_f32 v[152:153], v[18:19], v[164:165], v[152:153] op_sel_hi:[1,0,1]
	v_lshlrev_b64 v[164:165], 10, v[170:171]
	v_lshl_add_u64 v[164:165], v[146:147], 0, v[164:165]
	v_lshl_add_u32 v97, v178, 5, 0
	global_store_dwordx4 v[164:165], v[152:155], off nt
	ds_read_b128 v[152:155], v97 offset:32768
	v_mov_b32_e32 v164, v163
	v_pk_fma_f32 v[176:177], v[40:41], v[164:165], v[168:169] op_sel_hi:[1,0,1]
	v_pk_fma_f32 v[182:183], v[38:39], v[164:165], v[172:173] op_sel_hi:[1,0,1]
	ds_read_b128 v[164:167], v97 offset:24576
	ds_read_b128 v[168:171], v97 offset:24592
	ds_read_b128 v[172:175], v97 offset:32784
	s_waitcnt lgkmcnt(3)
	v_pk_mul_f32 v[184:185], v[16:17], v[152:153] op_sel_hi:[1,0]
	v_pk_mul_f32 v[186:187], v[14:15], v[152:153] op_sel_hi:[1,0]
	s_waitcnt vmcnt(15)
	v_pk_fma_f32 v[184:185], v[144:145], v[48:49], v[184:185] op_sel_hi:[0,1,1]
	v_pk_fma_f32 v[186:187], v[144:145], v[46:47], v[186:187] op_sel_hi:[0,1,1]
	v_pk_fma_f32 v[184:185], v[12:13], v[152:153], v[184:185] op_sel:[0,1,0]
	v_pk_fma_f32 v[152:153], v[10:11], v[152:153], v[186:187] op_sel:[0,1,0]
	v_pk_fma_f32 v[184:185], v[8:9], v[154:155], v[184:185] op_sel_hi:[1,0,1]
	v_pk_fma_f32 v[152:153], v[6:7], v[154:155], v[152:153] op_sel_hi:[1,0,1]
	v_mov_b32_e32 v154, v155
	v_pk_fma_f32 v[184:185], v[4:5], v[154:155], v[184:185] op_sel_hi:[1,0,1]
	v_pk_fma_f32 v[152:153], v[2:3], v[154:155], v[152:153] op_sel_hi:[1,0,1]
	s_waitcnt lgkmcnt(0)
	v_pk_fma_f32 v[154:155], v[32:33], v[172:173], v[184:185] op_sel_hi:[1,0,1]
	v_pk_fma_f32 v[152:153], v[30:31], v[172:173], v[152:153] op_sel_hi:[1,0,1]
	v_pk_fma_f32 v[154:155], v[28:29], v[172:173], v[154:155] op_sel:[0,1,0]
	v_pk_fma_f32 v[152:153], v[26:27], v[172:173], v[152:153] op_sel:[0,1,0]
	v_pk_fma_f32 v[154:155], v[24:25], v[174:175], v[154:155] op_sel_hi:[1,0,1]
	v_pk_fma_f32 v[152:153], v[22:23], v[174:175], v[152:153] op_sel_hi:[1,0,1]
	v_mov_b32_e32 v172, v175
	v_pk_fma_f32 v[154:155], v[20:21], v[172:173], v[154:155] op_sel_hi:[1,0,1]
	v_pk_fma_f32 v[152:153], v[18:19], v[172:173], v[152:153] op_sel_hi:[1,0,1]
	v_lshlrev_b64 v[172:173], 10, v[178:179]
	v_lshl_add_u64 v[172:173], v[146:147], 0, v[172:173]
	v_lshl_add_u32 v97, v188, 5, 0
	global_store_dwordx4 v[172:173], v[152:155], off nt
	ds_read_b128 v[150:153], v97 offset:32768
	s_waitcnt lgkmcnt(0)
	v_pk_mul_f32 v[192:193], v[16:17], v[150:151] op_sel_hi:[1,0]
	v_mov_b32_e32 v154, v171
	v_pk_fma_f32 v[186:187], v[48:49], v[154:155], v[176:177] op_sel_hi:[1,0,1]
	v_pk_fma_f32 v[154:155], v[46:47], v[154:155], v[182:183] op_sel_hi:[1,0,1]
	ds_read_b128 v[172:175], v97 offset:24576
	ds_read_b128 v[182:185], v97 offset:24592
	ds_read_b128 v[176:179], v97 offset:32784
	v_pk_mul_f32 v[194:195], v[14:15], v[150:151] op_sel_hi:[1,0]
	s_waitcnt vmcnt(15)
	v_pk_fma_f32 v[192:193], v[144:145], v[100:101], v[192:193] op_sel_hi:[0,1,1]
	v_pk_fma_f32 v[194:195], v[144:145], v[98:99], v[194:195] op_sel_hi:[0,1,1]
	v_pk_fma_f32 v[192:193], v[12:13], v[150:151], v[192:193] op_sel:[0,1,0]
	v_pk_fma_f32 v[150:151], v[10:11], v[150:151], v[194:195] op_sel:[0,1,0]
	v_pk_fma_f32 v[192:193], v[8:9], v[152:153], v[192:193] op_sel_hi:[1,0,1]
	v_pk_fma_f32 v[150:151], v[6:7], v[152:153], v[150:151] op_sel_hi:[1,0,1]
	v_mov_b32_e32 v152, v153
	v_pk_fma_f32 v[192:193], v[4:5], v[152:153], v[192:193] op_sel_hi:[1,0,1]
	v_pk_fma_f32 v[150:151], v[2:3], v[152:153], v[150:151] op_sel_hi:[1,0,1]
	s_waitcnt lgkmcnt(0)
; #define LAS __attribute__((address_space(3)))
; __device__ void sample_ret_unit(const Params& p, int l, int unit, LAS unsigned char* lds, const int tid_in) {
;     ...
; #pragma unroll
;         for (int u = 0; u < 8; ++u) {
;             const f32x4 q0 = *(const LAS f32x4*)(sqT + (d0 + u) * 8), q1 = *(const LAS f32x4*)(sqT + (d0 + u) * 8 + 4);
;             const f32x4 k0 = *(const LAS f32x4*)(skdT + (d0 + u) * 8), k1 = *(const LAS f32x4*)(skdT + (d0 + u) * 8 + 4);
;             f32x4 sn = S4[u] * g8;
;             sn += vv[0] * k0[0]; sn += vv[1] * k0[1]; sn += vv[2] * k0[2]; sn += vv[3] * k0[3];
;             sn += vv[4] * k1[0]; sn += vv[5] * k1[1]; sn += vv[6] * k1[2]; sn += vv[7] * k1[3];
;             __builtin_nontemporal_store(sn, (f32x4*)(Sout + (size_t)(d0 + u) * 256 + e4));
;             oacc[0] += S4[u] * q0[0]; oacc[1] += S4[u] * q0[1]; oacc[2] += S4[u] * q0[2]; oacc[3] += S4[u] * q0[3];
;             oacc[4] += S4[u] * q1[0]; oacc[5] += S4[u] * q1[1]; oacc[6] += S4[u] * q1[2]; oacc[7] += S4[u] * q1[3];
;         }
	v_pk_fma_f32 v[152:153], v[32:33], v[176:177], v[192:193] op_sel_hi:[1,0,1]
	v_pk_fma_f32 v[150:151], v[30:31], v[176:177], v[150:151] op_sel_hi:[1,0,1]
	v_pk_fma_f32 v[152:153], v[28:29], v[176:177], v[152:153] op_sel:[0,1,0]
	v_pk_fma_f32 v[150:151], v[26:27], v[176:177], v[150:151] op_sel:[0,1,0]
	v_pk_fma_f32 v[152:153], v[24:25], v[178:179], v[152:153] op_sel_hi:[1,0,1]
	v_pk_fma_f32 v[150:151], v[22:23], v[178:179], v[150:151] op_sel_hi:[1,0,1]
	v_mov_b32_e32 v176, v179
	v_pk_fma_f32 v[152:153], v[20:21], v[176:177], v[152:153] op_sel_hi:[1,0,1]
	v_pk_fma_f32 v[150:151], v[18:19], v[176:177], v[150:151] op_sel_hi:[1,0,1]
	v_lshlrev_b64 v[176:177], 10, v[188:189]
	v_lshl_add_u64 v[176:177], v[146:147], 0, v[176:177]
	global_store_dwordx4 v[176:177], v[150:153], off nt
	v_pk_fma_f32 v[176:177], v[88:89], v[104:105], 0 op_sel_hi:[1,0,0]
	v_pk_fma_f32 v[178:179], v[86:87], v[104:105], 0 op_sel_hi:[1,0,0]
	v_mov_b32_e32 v150, v185
	v_pk_fma_f32 v[186:187], v[100:101], v[150:151], v[186:187] op_sel_hi:[1,0,1]
	v_pk_fma_f32 v[188:189], v[98:99], v[150:151], v[154:155] op_sel_hi:[1,0,1]
	v_pk_fma_f32 v[150:151], v[88:89], v[102:103], 0 op_sel_hi:[1,0,0]
	v_pk_fma_f32 v[152:153], v[86:87], v[102:103], 0 op_sel_hi:[1,0,0]
	v_pk_fma_f32 v[154:155], v[88:89], v[102:103], 0 op_sel:[0,1,0] op_sel_hi:[1,1,0]
	v_pk_fma_f32 v[102:103], v[86:87], v[102:103], 0 op_sel:[0,1,0] op_sel_hi:[1,1,0]
	v_mov_b32_e32 v104, v105
	v_pk_fma_f32 v[192:193], v[88:89], v[104:105], 0 op_sel_hi:[1,0,0]
	v_pk_fma_f32 v[104:105], v[86:87], v[104:105], 0 op_sel_hi:[1,0,0]
	v_pk_fma_f32 v[194:195], v[88:89], v[94:95], 0 op_sel_hi:[1,0,0]
	v_pk_fma_f32 v[94:95], v[86:87], v[94:95], 0 op_sel:[0,1,0] op_sel_hi:[1,1,0]
	v_pk_fma_f32 v[88:89], v[88:89], v[96:97], 0 op_sel_hi:[1,0,0]
	v_pk_fma_f32 v[86:87], v[86:87], v[96:97], 0 op_sel_hi:[1,0,0]
	v_pk_fma_f32 v[96:97], v[80:81], v[110:111], v[150:151] op_sel_hi:[1,0,1]
	v_pk_fma_f32 v[150:151], v[78:79], v[110:111], v[152:153] op_sel_hi:[1,0,1]
	v_pk_fma_f32 v[152:153], v[80:81], v[110:111], v[154:155] op_sel:[0,1,0]
	v_pk_fma_f32 v[102:103], v[78:79], v[110:111], v[102:103] op_sel:[0,1,0]
	v_pk_fma_f32 v[110:111], v[80:81], v[112:113], v[176:177] op_sel_hi:[1,0,1]
	v_pk_fma_f32 v[154:155], v[78:79], v[112:113], v[178:179] op_sel_hi:[1,0,1]
	v_mov_b32_e32 v112, v113
	v_pk_fma_f32 v[176:177], v[80:81], v[112:113], v[192:193] op_sel_hi:[1,0,1]
	v_pk_fma_f32 v[104:105], v[78:79], v[112:113], v[104:105] op_sel_hi:[1,0,1]
	v_pk_fma_f32 v[112:113], v[80:81], v[106:107], v[194:195] op_sel_hi:[1,0,1]
	v_pk_fma_f32 v[178:179], v[78:79], v[106:107], v[198:199] op_sel_hi:[1,0,1]
	v_pk_fma_f32 v[192:193], v[80:81], v[106:107], v[200:201] op_sel:[0,1,0]
	v_pk_fma_f32 v[94:95], v[78:79], v[106:107], v[94:95] op_sel:[0,1,0]
	v_pk_fma_f32 v[78:79], v[78:79], v[108:109], v[86:87] op_sel_hi:[1,0,1]
	v_pk_fma_f32 v[86:87], v[76:77], v[118:119], v[96:97] op_sel_hi:[1,0,1]
	v_pk_fma_f32 v[96:97], v[76:77], v[118:119], v[152:153] op_sel:[0,1,0]
	v_pk_fma_f32 v[106:107], v[76:77], v[120:121], v[110:111] op_sel_hi:[1,0,1]
	v_mov_b32_e32 v110, v121
	v_pk_fma_f32 v[80:81], v[80:81], v[108:109], v[88:89] op_sel_hi:[1,0,1]
	v_pk_fma_f32 v[88:89], v[74:75], v[118:119], v[150:151] op_sel_hi:[1,0,1]
	v_pk_fma_f32 v[102:103], v[74:75], v[118:119], v[102:103] op_sel:[0,1,0]
	v_pk_fma_f32 v[108:109], v[74:75], v[120:121], v[154:155] op_sel_hi:[1,0,1]
	v_pk_fma_f32 v[118:119], v[76:77], v[110:111], v[176:177] op_sel_hi:[1,0,1]
	v_pk_fma_f32 v[104:105], v[74:75], v[110:111], v[104:105] op_sel_hi:[1,0,1]
	v_pk_fma_f32 v[110:111], v[76:77], v[114:115], v[112:113] op_sel_hi:[1,0,1]
	v_pk_fma_f32 v[112:113], v[74:75], v[114:115], v[178:179] op_sel_hi:[1,0,1]
	v_pk_fma_f32 v[94:95], v[74:75], v[114:115], v[94:95] op_sel:[0,1,0]
	v_pk_fma_f32 v[74:75], v[74:75], v[116:117], v[78:79] op_sel_hi:[1,0,1]
	v_pk_fma_f32 v[78:79], v[64:65], v[126:127], v[86:87] op_sel_hi:[1,0,1]
	v_pk_fma_f32 v[86:87], v[64:65], v[126:127], v[96:97] op_sel:[0,1,0]
	v_pk_fma_f32 v[96:97], v[64:65], v[128:129], v[106:107] op_sel_hi:[1,0,1]
	v_mov_b32_e32 v106, v129
	v_pk_fma_f32 v[120:121], v[76:77], v[114:115], v[192:193] op_sel:[0,1,0]
	v_pk_fma_f32 v[76:77], v[76:77], v[116:117], v[80:81] op_sel_hi:[1,0,1]
	v_pk_fma_f32 v[80:81], v[62:63], v[126:127], v[88:89] op_sel_hi:[1,0,1]
	v_pk_fma_f32 v[88:89], v[62:63], v[126:127], v[102:103] op_sel:[0,1,0]
	v_pk_fma_f32 v[102:103], v[62:63], v[128:129], v[108:109] op_sel_hi:[1,0,1]
	v_pk_fma_f32 v[108:109], v[64:65], v[106:107], v[118:119] op_sel_hi:[1,0,1]
	v_pk_fma_f32 v[104:105], v[62:63], v[106:107], v[104:105] op_sel_hi:[1,0,1]
	v_pk_fma_f32 v[106:107], v[64:65], v[122:123], v[110:111] op_sel_hi:[1,0,1]
	v_pk_fma_f32 v[110:111], v[62:63], v[122:123], v[112:113] op_sel_hi:[1,0,1]
	v_pk_fma_f32 v[94:95], v[62:63], v[122:123], v[94:95] op_sel:[0,1,0]
	v_pk_fma_f32 v[62:63], v[62:63], v[124:125], v[74:75] op_sel_hi:[1,0,1]
	v_pk_fma_f32 v[74:75], v[56:57], v[134:135], v[78:79] op_sel_hi:[1,0,1]
	v_pk_fma_f32 v[78:79], v[56:57], v[134:135], v[86:87] op_sel:[0,1,0]
	v_pk_fma_f32 v[86:87], v[56:57], v[136:137], v[96:97] op_sel_hi:[1,0,1]
	v_mov_b32_e32 v96, v137
	v_pk_fma_f32 v[112:113], v[64:65], v[122:123], v[120:121] op_sel:[0,1,0]
	v_pk_fma_f32 v[64:65], v[64:65], v[124:125], v[76:77] op_sel_hi:[1,0,1]
	v_pk_fma_f32 v[76:77], v[54:55], v[134:135], v[80:81] op_sel_hi:[1,0,1]
	v_pk_fma_f32 v[80:81], v[54:55], v[134:135], v[88:89] op_sel:[0,1,0]
	v_pk_fma_f32 v[88:89], v[54:55], v[136:137], v[102:103] op_sel_hi:[1,0,1]
	v_pk_fma_f32 v[102:103], v[56:57], v[96:97], v[108:109] op_sel_hi:[1,0,1]
	v_pk_fma_f32 v[96:97], v[54:55], v[96:97], v[104:105] op_sel_hi:[1,0,1]
; #define LAS __attribute__((address_space(3)))
; __device__ __forceinline__ int launder(int v) { asm volatile("" : "+v"(v)); return v; }
; __device__ void sample_ret_unit(const Params& p, int l, int unit, LAS unsigned char* lds, const int tid_in) {
;     ...
;     for (int dd = 0; dd < 32; dd += 8) {
;         const int d0 = launder(wid * 32 + dd);
;         const int dn = dd + 8 < 32 ? d0 + 8 : d0;
; #pragma unroll
;         for (int u = 0; u < 8; ++u) N4[u] = __builtin_nontemporal_load((const f32x4*)(Sin + (size_t)(dn + u) * 256 + e4));
;         asm volatile("" ::: "memory");
; #pragma unroll
;         for (int u = 0; u < 8; ++u) {
;             const f32x4 q0 = *(const LAS f32x4*)(sqT + (d0 + u) * 8), q1 = *(const LAS f32x4*)(sqT + (d0 + u) * 8 + 4);
;             const f32x4 k0 = *(const LAS f32x4*)(skdT + (d0 + u) * 8), k1 = *(const LAS f32x4*)(skdT + (d0 + u) * 8 + 4);
;             f32x4 sn = S4[u] * g8;
;             sn += vv[0] * k0[0]; sn += vv[1] * k0[1]; sn += vv[2] * k0[2]; sn += vv[3] * k0[3];
;             sn += vv[4] * k1[0]; sn += vv[5] * k1[1]; sn += vv[6] * k1[2]; sn += vv[7] * k1[3];
;             __builtin_nontemporal_store(sn, (f32x4*)(Sout + (size_t)(d0 + u) * 256 + e4));
;             oacc[0] += S4[u] * q0[0]; oacc[1] += S4[u] * q0[1]; oacc[2] += S4[u] * q0[2]; oacc[3] += S4[u] * q0[3];
;             oacc[4] += S4[u] * q1[0]; oacc[5] += S4[u] * q1[1]; oacc[6] += S4[u] * q1[2]; oacc[7] += S4[u] * q1[3];
;         }
	v_pk_fma_f32 v[104:105], v[56:57], v[130:131], v[106:107] op_sel_hi:[1,0,1]
	v_pk_fma_f32 v[106:107], v[54:55], v[130:131], v[110:111] op_sel_hi:[1,0,1]
	v_pk_fma_f32 v[94:95], v[54:55], v[130:131], v[94:95] op_sel:[0,1,0]
	v_pk_fma_f32 v[54:55], v[54:55], v[132:133], v[62:63] op_sel_hi:[1,0,1]
	v_pk_fma_f32 v[62:63], v[40:41], v[156:157], v[74:75] op_sel_hi:[1,0,1]
	v_pk_fma_f32 v[74:75], v[40:41], v[156:157], v[78:79] op_sel:[0,1,0]
	v_pk_fma_f32 v[78:79], v[40:41], v[158:159], v[86:87] op_sel_hi:[1,0,1]
	v_mov_b32_e32 v86, v159
	v_or_b32_e32 v178, 8, v142
	v_pk_fma_f32 v[108:109], v[56:57], v[130:131], v[112:113] op_sel:[0,1,0]
	v_pk_fma_f32 v[56:57], v[56:57], v[132:133], v[64:65] op_sel_hi:[1,0,1]
	v_pk_fma_f32 v[64:65], v[38:39], v[156:157], v[76:77] op_sel_hi:[1,0,1]
	v_pk_fma_f32 v[76:77], v[38:39], v[156:157], v[80:81] op_sel:[0,1,0]
	v_pk_fma_f32 v[80:81], v[38:39], v[158:159], v[88:89] op_sel_hi:[1,0,1]
	v_pk_fma_f32 v[88:89], v[40:41], v[86:87], v[102:103] op_sel_hi:[1,0,1]
	v_pk_fma_f32 v[86:87], v[38:39], v[86:87], v[96:97] op_sel_hi:[1,0,1]
	v_pk_fma_f32 v[102:103], v[38:39], v[160:161], v[106:107] op_sel_hi:[1,0,1]
	v_pk_fma_f32 v[94:95], v[38:39], v[160:161], v[94:95] op_sel:[0,1,0]
	v_pk_fma_f32 v[38:39], v[38:39], v[162:163], v[54:55] op_sel_hi:[1,0,1]
	v_pk_fma_f32 v[54:55], v[48:49], v[164:165], v[62:63] op_sel_hi:[1,0,1]
	v_pk_fma_f32 v[62:63], v[48:49], v[164:165], v[74:75] op_sel:[0,1,0]
	v_pk_fma_f32 v[74:75], v[48:49], v[166:167], v[78:79] op_sel_hi:[1,0,1]
	v_mov_b32_e32 v78, v167
	v_pk_fma_f32 v[96:97], v[40:41], v[160:161], v[104:105] op_sel_hi:[1,0,1]
	v_ashrrev_i32_e32 v179, 31, v178
	v_pk_fma_f32 v[104:105], v[40:41], v[160:161], v[108:109] op_sel:[0,1,0]
	v_pk_fma_f32 v[40:41], v[40:41], v[162:163], v[56:57] op_sel_hi:[1,0,1]
	v_pk_fma_f32 v[56:57], v[46:47], v[164:165], v[64:65] op_sel_hi:[1,0,1]
	v_pk_fma_f32 v[64:65], v[46:47], v[164:165], v[76:77] op_sel:[0,1,0]
	v_pk_fma_f32 v[76:77], v[46:47], v[166:167], v[80:81] op_sel_hi:[1,0,1]
	v_pk_fma_f32 v[80:81], v[48:49], v[78:79], v[88:89] op_sel_hi:[1,0,1]
	v_pk_fma_f32 v[78:79], v[46:47], v[78:79], v[86:87] op_sel_hi:[1,0,1]
	v_pk_fma_f32 v[88:89], v[46:47], v[168:169], v[102:103] op_sel_hi:[1,0,1]
	v_pk_fma_f32 v[102:103], v[46:47], v[170:171], v[38:39] op_sel_hi:[1,0,1]
	v_mov_b32_e32 v38, v175
	v_lshlrev_b64 v[114:115], 10, v[178:179]
	v_pk_fma_f32 v[40:41], v[48:49], v[170:171], v[40:41] op_sel_hi:[1,0,1]
	v_pk_fma_f32 v[162:163], v[100:101], v[38:39], v[80:81] op_sel_hi:[1,0,1]
	v_pk_fma_f32 v[164:165], v[98:99], v[38:39], v[78:79] op_sel_hi:[1,0,1]
	v_lshl_add_u64 v[38:39], v[148:149], 0, v[114:115]
	v_pk_fma_f32 v[158:159], v[100:101], v[174:175], v[74:75] op_sel_hi:[1,0,1]
	v_pk_fma_f32 v[160:161], v[98:99], v[174:175], v[76:77] op_sel_hi:[1,0,1]
	v_pk_fma_f32 v[174:175], v[100:101], v[184:185], v[40:41] op_sel_hi:[1,0,1]
	v_add_co_u32_e32 v40, vcc, s6, v38
	v_pk_fma_f32 v[86:87], v[48:49], v[168:169], v[96:97] op_sel_hi:[1,0,1]
	s_nop 0
	v_addc_co_u32_e32 v41, vcc, 0, v39, vcc
	v_add_co_u32_e32 v38, vcc, s7, v38
	v_pk_fma_f32 v[96:97], v[48:49], v[168:169], v[104:105] op_sel:[0,1,0]
	v_pk_fma_f32 v[94:95], v[46:47], v[168:169], v[94:95] op_sel:[0,1,0]
	v_addc_co_u32_e32 v39, vcc, 0, v39, vcc
	v_pk_fma_f32 v[150:151], v[100:101], v[172:173], v[54:55] op_sel_hi:[1,0,1]
	v_pk_fma_f32 v[152:153], v[98:99], v[172:173], v[56:57] op_sel_hi:[1,0,1]
	v_pk_fma_f32 v[154:155], v[100:101], v[172:173], v[62:63] op_sel:[0,1,0]
	v_pk_fma_f32 v[156:157], v[98:99], v[172:173], v[64:65] op_sel:[0,1,0]
	v_pk_fma_f32 v[166:167], v[100:101], v[182:183], v[86:87] op_sel_hi:[1,0,1]
	v_pk_fma_f32 v[168:169], v[98:99], v[182:183], v[88:89] op_sel_hi:[1,0,1]
	v_pk_fma_f32 v[170:171], v[100:101], v[182:183], v[96:97] op_sel:[0,1,0]
	v_pk_fma_f32 v[172:173], v[98:99], v[182:183], v[94:95] op_sel:[0,1,0]
	global_load_dwordx4 v[86:89], v[40:41], off offset:1024 nt
	global_load_dwordx4 v[78:81], v[40:41], off offset:2048 nt
	global_load_dwordx4 v[94:97], v[38:39], off offset:-4096 nt
	global_load_dwordx4 v[74:77], v[40:41], off offset:3072 nt
	global_load_dwordx4 v[62:65], v[38:39], off nt
	global_load_dwordx4 v[54:57], v[38:39], off offset:1024 nt
	global_load_dwordx4 v[46:49], v[38:39], off offset:2048 nt
	s_nop 0
	global_load_dwordx4 v[38:41], v[38:39], off offset:3072 nt
	v_lshl_add_u32 v110, v178, 5, 0
	ds_read_b128 v[106:109], v110 offset:32768
	v_pk_fma_f32 v[176:177], v[98:99], v[184:185], v[102:103] op_sel_hi:[1,0,1]
	ds_read_b128 v[102:105], v110 offset:24576
	ds_read_b128 v[98:101], v110 offset:24592
	ds_read_b128 v[110:113], v110 offset:32784
	v_add_u32_e32 v124, 1, v178
	v_ashrrev_i32_e32 v125, 31, v124
	s_waitcnt lgkmcnt(3)
	v_pk_mul_f32 v[116:117], v[16:17], v[106:107] op_sel_hi:[1,0]
	v_pk_mul_f32 v[118:119], v[14:15], v[106:107] op_sel_hi:[1,0]
	s_waitcnt vmcnt(21)
	v_pk_fma_f32 v[116:117], v[144:145], v[92:93], v[116:117] op_sel_hi:[0,1,1]
	v_pk_fma_f32 v[118:119], v[144:145], v[90:91], v[118:119] op_sel_hi:[0,1,1]
	v_pk_fma_f32 v[116:117], v[12:13], v[106:107], v[116:117] op_sel:[0,1,0]
	v_pk_fma_f32 v[106:107], v[10:11], v[106:107], v[118:119] op_sel:[0,1,0]
	v_pk_fma_f32 v[116:117], v[8:9], v[108:109], v[116:117] op_sel_hi:[1,0,1]
	v_pk_fma_f32 v[106:107], v[6:7], v[108:109], v[106:107] op_sel_hi:[1,0,1]
	v_mov_b32_e32 v108, v109
	v_pk_fma_f32 v[116:117], v[4:5], v[108:109], v[116:117] op_sel_hi:[1,0,1]
	v_pk_fma_f32 v[106:107], v[2:3], v[108:109], v[106:107] op_sel_hi:[1,0,1]
	s_waitcnt lgkmcnt(0)
; #define LAS __attribute__((address_space(3)))
; __device__ void sample_ret_unit(const Params& p, int l, int unit, LAS unsigned char* lds, const int tid_in) {
;     ...
; #pragma unroll
;         for (int u = 0; u < 8; ++u) {
;             const f32x4 q0 = *(const LAS f32x4*)(sqT + (d0 + u) * 8), q1 = *(const LAS f32x4*)(sqT + (d0 + u) * 8 + 4);
;             const f32x4 k0 = *(const LAS f32x4*)(skdT + (d0 + u) * 8), k1 = *(const LAS f32x4*)(skdT + (d0 + u) * 8 + 4);
;             f32x4 sn = S4[u] * g8;
;             sn += vv[0] * k0[0]; sn += vv[1] * k0[1]; sn += vv[2] * k0[2]; sn += vv[3] * k0[3];
;             sn += vv[4] * k1[0]; sn += vv[5] * k1[1]; sn += vv[6] * k1[2]; sn += vv[7] * k1[3];
;             __builtin_nontemporal_store(sn, (f32x4*)(Sout + (size_t)(d0 + u) * 256 + e4));
;             oacc[0] += S4[u] * q0[0]; oacc[1] += S4[u] * q0[1]; oacc[2] += S4[u] * q0[2]; oacc[3] += S4[u] * q0[3];
;             oacc[4] += S4[u] * q1[0]; oacc[5] += S4[u] * q1[1]; oacc[6] += S4[u] * q1[2]; oacc[7] += S4[u] * q1[3];
;         }
	v_pk_fma_f32 v[108:109], v[32:33], v[110:111], v[116:117] op_sel_hi:[1,0,1]
	v_pk_fma_f32 v[106:107], v[30:31], v[110:111], v[106:107] op_sel_hi:[1,0,1]
	v_pk_fma_f32 v[108:109], v[28:29], v[110:111], v[108:109] op_sel:[0,1,0]
	v_pk_fma_f32 v[106:107], v[26:27], v[110:111], v[106:107] op_sel:[0,1,0]
	v_pk_fma_f32 v[108:109], v[24:25], v[112:113], v[108:109] op_sel_hi:[1,0,1]
	v_pk_fma_f32 v[106:107], v[22:23], v[112:113], v[106:107] op_sel_hi:[1,0,1]
	v_mov_b32_e32 v110, v113
	v_pk_fma_f32 v[108:109], v[20:21], v[110:111], v[108:109] op_sel_hi:[1,0,1]
	v_pk_fma_f32 v[106:107], v[18:19], v[110:111], v[106:107] op_sel_hi:[1,0,1]
	v_lshl_add_u64 v[110:111], v[146:147], 0, v[114:115]
	global_store_dwordx4 v[110:111], v[106:109], off nt
	v_add_u32_e32 v132, 2, v178
	v_ashrrev_i32_e32 v133, 31, v132
	v_mov_b32_e32 v106, v101
	v_lshl_add_u32 v101, v124, 5, 0
	ds_read_b128 v[114:117], v101 offset:32768
	v_pk_fma_f32 v[122:123], v[92:93], v[106:107], v[186:187] op_sel_hi:[1,0,1]
	v_pk_fma_f32 v[126:127], v[90:91], v[106:107], v[188:189] op_sel_hi:[1,0,1]
	ds_read_b128 v[110:113], v101 offset:24576
	ds_read_b128 v[106:109], v101 offset:24592
	ds_read_b128 v[118:121], v101 offset:32784
	v_lshl_add_u32 v101, v132, 5, 0
	s_waitcnt lgkmcnt(3)
	v_pk_mul_f32 v[128:129], v[16:17], v[114:115] op_sel_hi:[1,0]
	v_pk_mul_f32 v[130:131], v[14:15], v[114:115] op_sel_hi:[1,0]
	v_pk_fma_f32 v[128:129], v[144:145], v[84:85], v[128:129] op_sel_hi:[0,1,1]
	v_pk_fma_f32 v[130:131], v[144:145], v[82:83], v[130:131] op_sel_hi:[0,1,1]
	v_pk_fma_f32 v[128:129], v[12:13], v[114:115], v[128:129] op_sel:[0,1,0]
	v_pk_fma_f32 v[114:115], v[10:11], v[114:115], v[130:131] op_sel:[0,1,0]
	v_pk_fma_f32 v[128:129], v[8:9], v[116:117], v[128:129] op_sel_hi:[1,0,1]
	v_pk_fma_f32 v[114:115], v[6:7], v[116:117], v[114:115] op_sel_hi:[1,0,1]
	v_mov_b32_e32 v116, v117
	v_pk_fma_f32 v[128:129], v[4:5], v[116:117], v[128:129] op_sel_hi:[1,0,1]
	v_pk_fma_f32 v[114:115], v[2:3], v[116:117], v[114:115] op_sel_hi:[1,0,1]
	s_waitcnt lgkmcnt(0)
	v_pk_fma_f32 v[116:117], v[32:33], v[118:119], v[128:129] op_sel_hi:[1,0,1]
	v_pk_fma_f32 v[114:115], v[30:31], v[118:119], v[114:115] op_sel_hi:[1,0,1]
	v_pk_fma_f32 v[116:117], v[28:29], v[118:119], v[116:117] op_sel:[0,1,0]
	v_pk_fma_f32 v[114:115], v[26:27], v[118:119], v[114:115] op_sel:[0,1,0]
	v_pk_fma_f32 v[116:117], v[24:25], v[120:121], v[116:117] op_sel_hi:[1,0,1]
	v_pk_fma_f32 v[114:115], v[22:23], v[120:121], v[114:115] op_sel_hi:[1,0,1]
	v_mov_b32_e32 v118, v121
	v_pk_fma_f32 v[116:117], v[20:21], v[118:119], v[116:117] op_sel_hi:[1,0,1]
	v_pk_fma_f32 v[114:115], v[18:19], v[118:119], v[114:115] op_sel_hi:[1,0,1]
	v_lshlrev_b64 v[118:119], 10, v[124:125]
	v_lshl_add_u64 v[118:119], v[146:147], 0, v[118:119]
	global_store_dwordx4 v[118:119], v[114:117], off nt
	v_add_u32_e32 v184, 3, v178
	v_ashrrev_i32_e32 v185, 31, v184
	v_mov_b32_e32 v114, v109
	v_pk_fma_f32 v[130:131], v[84:85], v[114:115], v[122:123] op_sel_hi:[1,0,1]
	ds_read_b128 v[122:125], v101 offset:32768
	v_pk_fma_f32 v[134:135], v[82:83], v[114:115], v[126:127] op_sel_hi:[1,0,1]
	ds_read_b128 v[118:121], v101 offset:24576
	ds_read_b128 v[114:117], v101 offset:24592
	ds_read_b128 v[126:129], v101 offset:32784
	v_lshl_add_u32 v101, v184, 5, 0
	v_add_u32_e32 v194, 4, v178
	s_waitcnt lgkmcnt(3)
	v_pk_mul_f32 v[136:137], v[16:17], v[122:123] op_sel_hi:[1,0]
	v_pk_mul_f32 v[182:183], v[14:15], v[122:123] op_sel_hi:[1,0]
	v_pk_fma_f32 v[136:137], v[144:145], v[72:73], v[136:137] op_sel_hi:[0,1,1]
	v_pk_fma_f32 v[182:183], v[144:145], v[70:71], v[182:183] op_sel_hi:[0,1,1]
	v_pk_fma_f32 v[136:137], v[12:13], v[122:123], v[136:137] op_sel:[0,1,0]
	v_pk_fma_f32 v[122:123], v[10:11], v[122:123], v[182:183] op_sel:[0,1,0]
	v_pk_fma_f32 v[136:137], v[8:9], v[124:125], v[136:137] op_sel_hi:[1,0,1]
	v_pk_fma_f32 v[122:123], v[6:7], v[124:125], v[122:123] op_sel_hi:[1,0,1]
	v_mov_b32_e32 v124, v125
	v_pk_fma_f32 v[136:137], v[4:5], v[124:125], v[136:137] op_sel_hi:[1,0,1]
	v_pk_fma_f32 v[122:123], v[2:3], v[124:125], v[122:123] op_sel_hi:[1,0,1]
	s_waitcnt lgkmcnt(0)
	v_pk_fma_f32 v[124:125], v[32:33], v[126:127], v[136:137] op_sel_hi:[1,0,1]
	v_pk_fma_f32 v[122:123], v[30:31], v[126:127], v[122:123] op_sel_hi:[1,0,1]
	v_pk_fma_f32 v[124:125], v[28:29], v[126:127], v[124:125] op_sel:[0,1,0]
	v_pk_fma_f32 v[122:123], v[26:27], v[126:127], v[122:123] op_sel:[0,1,0]
	v_pk_fma_f32 v[124:125], v[24:25], v[128:129], v[124:125] op_sel_hi:[1,0,1]
	v_pk_fma_f32 v[122:123], v[22:23], v[128:129], v[122:123] op_sel_hi:[1,0,1]
	v_mov_b32_e32 v126, v129
	v_pk_fma_f32 v[124:125], v[20:21], v[126:127], v[124:125] op_sel_hi:[1,0,1]
	v_pk_fma_f32 v[122:123], v[18:19], v[126:127], v[122:123] op_sel_hi:[1,0,1]
	v_lshlrev_b64 v[126:127], 10, v[132:133]
	v_lshl_add_u64 v[126:127], v[146:147], 0, v[126:127]
	global_store_dwordx4 v[126:127], v[122:125], off nt
	v_ashrrev_i32_e32 v195, 31, v194
	v_add_u32_e32 v214, 6, v178
	v_mov_b32_e32 v122, v117
	v_pk_fma_f32 v[182:183], v[72:73], v[122:123], v[130:131] op_sel_hi:[1,0,1]
	ds_read_b128 v[130:133], v101 offset:32768
	v_pk_fma_f32 v[186:187], v[70:71], v[122:123], v[134:135] op_sel_hi:[1,0,1]
	ds_read_b128 v[126:129], v101 offset:24576
	ds_read_b128 v[122:125], v101 offset:24592
	ds_read_b128 v[134:137], v101 offset:32784
	v_lshl_add_u32 v101, v194, 5, 0
	v_ashrrev_i32_e32 v215, 31, v214
	s_waitcnt lgkmcnt(3)
	v_pk_mul_f32 v[188:189], v[16:17], v[130:131] op_sel_hi:[1,0]
	v_pk_mul_f32 v[192:193], v[14:15], v[130:131] op_sel_hi:[1,0]
	s_waitcnt vmcnt(23)
; #define LAS __attribute__((address_space(3)))
; __device__ void sample_ret_unit(const Params& p, int l, int unit, LAS unsigned char* lds, const int tid_in) {
;     ...
; #pragma unroll
;         for (int u = 0; u < 8; ++u) {
;             const f32x4 q0 = *(const LAS f32x4*)(sqT + (d0 + u) * 8), q1 = *(const LAS f32x4*)(sqT + (d0 + u) * 8 + 4);
;             const f32x4 k0 = *(const LAS f32x4*)(skdT + (d0 + u) * 8), k1 = *(const LAS f32x4*)(skdT + (d0 + u) * 8 + 4);
;             f32x4 sn = S4[u] * g8;
;             sn += vv[0] * k0[0]; sn += vv[1] * k0[1]; sn += vv[2] * k0[2]; sn += vv[3] * k0[3];
;             sn += vv[4] * k1[0]; sn += vv[5] * k1[1]; sn += vv[6] * k1[2]; sn += vv[7] * k1[3];
;             __builtin_nontemporal_store(sn, (f32x4*)(Sout + (size_t)(d0 + u) * 256 + e4));
;             oacc[0] += S4[u] * q0[0]; oacc[1] += S4[u] * q0[1]; oacc[2] += S4[u] * q0[2]; oacc[3] += S4[u] * q0[3];
;             oacc[4] += S4[u] * q1[0]; oacc[5] += S4[u] * q1[1]; oacc[6] += S4[u] * q1[2]; oacc[7] += S4[u] * q1[3];
;         }
	v_pk_fma_f32 v[188:189], v[144:145], v[68:69], v[188:189] op_sel_hi:[0,1,1]
	v_pk_fma_f32 v[192:193], v[144:145], v[66:67], v[192:193] op_sel_hi:[0,1,1]
	v_pk_fma_f32 v[188:189], v[12:13], v[130:131], v[188:189] op_sel:[0,1,0]
	v_pk_fma_f32 v[130:131], v[10:11], v[130:131], v[192:193] op_sel:[0,1,0]
	v_pk_fma_f32 v[188:189], v[8:9], v[132:133], v[188:189] op_sel_hi:[1,0,1]
	v_pk_fma_f32 v[130:131], v[6:7], v[132:133], v[130:131] op_sel_hi:[1,0,1]
	v_mov_b32_e32 v132, v133
	v_pk_fma_f32 v[188:189], v[4:5], v[132:133], v[188:189] op_sel_hi:[1,0,1]
	v_pk_fma_f32 v[130:131], v[2:3], v[132:133], v[130:131] op_sel_hi:[1,0,1]
	s_waitcnt lgkmcnt(0)
	v_pk_fma_f32 v[132:133], v[32:33], v[134:135], v[188:189] op_sel_hi:[1,0,1]
	v_pk_fma_f32 v[130:131], v[30:31], v[134:135], v[130:131] op_sel_hi:[1,0,1]
	v_pk_fma_f32 v[132:133], v[28:29], v[134:135], v[132:133] op_sel:[0,1,0]
	v_pk_fma_f32 v[130:131], v[26:27], v[134:135], v[130:131] op_sel:[0,1,0]
	v_pk_fma_f32 v[132:133], v[24:25], v[136:137], v[132:133] op_sel_hi:[1,0,1]
	v_pk_fma_f32 v[130:131], v[22:23], v[136:137], v[130:131] op_sel_hi:[1,0,1]
	v_mov_b32_e32 v134, v137
	v_pk_fma_f32 v[132:133], v[20:21], v[134:135], v[132:133] op_sel_hi:[1,0,1]
	v_pk_fma_f32 v[130:131], v[18:19], v[134:135], v[130:131] op_sel_hi:[1,0,1]
	v_lshlrev_b64 v[134:135], 10, v[184:185]
	v_lshl_add_u64 v[134:135], v[146:147], 0, v[134:135]
	global_store_dwordx4 v[134:135], v[130:133], off nt
	v_pk_fma_f32 v[150:151], v[92:93], v[102:103], v[150:151] op_sel_hi:[1,0,1]
	v_pk_fma_f32 v[152:153], v[90:91], v[102:103], v[152:153] op_sel_hi:[1,0,1]
	v_mov_b32_e32 v130, v125
	v_pk_fma_f32 v[192:193], v[68:69], v[130:131], v[182:183] op_sel_hi:[1,0,1]
	ds_read_b128 v[182:185], v101 offset:32768
	v_pk_fma_f32 v[198:199], v[66:67], v[130:131], v[186:187] op_sel_hi:[1,0,1]
	ds_read_b128 v[134:137], v101 offset:24576
	ds_read_b128 v[130:133], v101 offset:24592
	ds_read_b128 v[186:189], v101 offset:32784
	v_pk_fma_f32 v[154:155], v[92:93], v[102:103], v[154:155] op_sel:[0,1,0]
	v_pk_fma_f32 v[102:103], v[90:91], v[102:103], v[156:157] op_sel:[0,1,0]
	s_waitcnt lgkmcnt(3)
	v_pk_mul_f32 v[200:201], v[16:17], v[182:183] op_sel_hi:[1,0]
	v_pk_mul_f32 v[202:203], v[14:15], v[182:183] op_sel_hi:[1,0]
	s_waitcnt vmcnt(23)
	v_pk_fma_f32 v[200:201], v[144:145], v[60:61], v[200:201] op_sel_hi:[0,1,1]
	v_pk_fma_f32 v[202:203], v[144:145], v[58:59], v[202:203] op_sel_hi:[0,1,1]
	v_pk_fma_f32 v[200:201], v[12:13], v[182:183], v[200:201] op_sel:[0,1,0]
	v_pk_fma_f32 v[182:183], v[10:11], v[182:183], v[202:203] op_sel:[0,1,0]
	v_pk_fma_f32 v[200:201], v[8:9], v[184:185], v[200:201] op_sel_hi:[1,0,1]
	v_pk_fma_f32 v[182:183], v[6:7], v[184:185], v[182:183] op_sel_hi:[1,0,1]
	v_mov_b32_e32 v184, v185
	v_pk_fma_f32 v[200:201], v[4:5], v[184:185], v[200:201] op_sel_hi:[1,0,1]
	v_pk_fma_f32 v[182:183], v[2:3], v[184:185], v[182:183] op_sel_hi:[1,0,1]
	s_waitcnt lgkmcnt(0)
	v_pk_fma_f32 v[184:185], v[32:33], v[186:187], v[200:201] op_sel_hi:[1,0,1]
	v_pk_fma_f32 v[182:183], v[30:31], v[186:187], v[182:183] op_sel_hi:[1,0,1]
	v_pk_fma_f32 v[184:185], v[28:29], v[186:187], v[184:185] op_sel:[0,1,0]
	v_pk_fma_f32 v[182:183], v[26:27], v[186:187], v[182:183] op_sel:[0,1,0]
	v_pk_fma_f32 v[184:185], v[24:25], v[188:189], v[184:185] op_sel_hi:[1,0,1]
	v_pk_fma_f32 v[182:183], v[22:23], v[188:189], v[182:183] op_sel_hi:[1,0,1]
	v_mov_b32_e32 v186, v189
	v_pk_fma_f32 v[184:185], v[20:21], v[186:187], v[184:185] op_sel_hi:[1,0,1]
	v_pk_fma_f32 v[182:183], v[18:19], v[186:187], v[182:183] op_sel_hi:[1,0,1]
	v_lshlrev_b64 v[186:187], 10, v[194:195]
	v_add_u32_e32 v194, 5, v178
	v_lshl_add_u64 v[186:187], v[146:147], 0, v[186:187]
	v_lshl_add_u32 v101, v194, 5, 0
	global_store_dwordx4 v[186:187], v[182:185], off nt
	ds_read_b128 v[182:185], v101 offset:32768
	v_mov_b32_e32 v186, v133
	v_pk_fma_f32 v[192:193], v[60:61], v[186:187], v[192:193] op_sel_hi:[1,0,1]
	v_pk_fma_f32 v[206:207], v[58:59], v[186:187], v[198:199] op_sel_hi:[1,0,1]
	ds_read_b128 v[186:189], v101 offset:24576
	ds_read_b128 v[198:201], v101 offset:24592
	ds_read_b128 v[202:205], v101 offset:32784
	s_waitcnt lgkmcnt(3)
	v_pk_mul_f32 v[208:209], v[16:17], v[182:183] op_sel_hi:[1,0]
	v_pk_mul_f32 v[210:211], v[14:15], v[182:183] op_sel_hi:[1,0]
	s_waitcnt vmcnt(23)
	v_pk_fma_f32 v[208:209], v[144:145], v[52:53], v[208:209] op_sel_hi:[0,1,1]
	v_pk_fma_f32 v[210:211], v[144:145], v[50:51], v[210:211] op_sel_hi:[0,1,1]
	v_pk_fma_f32 v[208:209], v[12:13], v[182:183], v[208:209] op_sel:[0,1,0]
	v_pk_fma_f32 v[182:183], v[10:11], v[182:183], v[210:211] op_sel:[0,1,0]
	v_pk_fma_f32 v[208:209], v[8:9], v[184:185], v[208:209] op_sel_hi:[1,0,1]
	v_pk_fma_f32 v[182:183], v[6:7], v[184:185], v[182:183] op_sel_hi:[1,0,1]
	v_mov_b32_e32 v184, v185
	v_pk_fma_f32 v[208:209], v[4:5], v[184:185], v[208:209] op_sel_hi:[1,0,1]
	v_pk_fma_f32 v[182:183], v[2:3], v[184:185], v[182:183] op_sel_hi:[1,0,1]
	s_waitcnt lgkmcnt(0)
	v_pk_fma_f32 v[184:185], v[32:33], v[202:203], v[208:209] op_sel_hi:[1,0,1]
	v_pk_fma_f32 v[182:183], v[30:31], v[202:203], v[182:183] op_sel_hi:[1,0,1]
	v_pk_fma_f32 v[184:185], v[28:29], v[202:203], v[184:185] op_sel:[0,1,0]
	v_pk_fma_f32 v[182:183], v[26:27], v[202:203], v[182:183] op_sel:[0,1,0]
	v_ashrrev_i32_e32 v195, 31, v194
	v_pk_fma_f32 v[184:185], v[24:25], v[204:205], v[184:185] op_sel_hi:[1,0,1]
	v_pk_fma_f32 v[182:183], v[22:23], v[204:205], v[182:183] op_sel_hi:[1,0,1]
	v_mov_b32_e32 v202, v205
	v_lshlrev_b64 v[194:195], 10, v[194:195]
	v_pk_fma_f32 v[184:185], v[20:21], v[202:203], v[184:185] op_sel_hi:[1,0,1]
	v_pk_fma_f32 v[182:183], v[18:19], v[202:203], v[182:183] op_sel_hi:[1,0,1]
	v_lshl_add_u64 v[194:195], v[146:147], 0, v[194:195]
	v_lshl_add_u32 v101, v214, 5, 0
	global_store_dwordx4 v[194:195], v[182:185], off nt
	ds_read_b128 v[182:185], v101 offset:32768
	v_mov_b32_e32 v194, v201
	v_pk_fma_f32 v[192:193], v[52:53], v[194:195], v[192:193] op_sel_hi:[1,0,1]
	v_pk_fma_f32 v[194:195], v[50:51], v[194:195], v[206:207] op_sel_hi:[1,0,1]
	ds_read_b128 v[202:205], v101 offset:24576
	ds_read_b128 v[206:209], v101 offset:24592
	ds_read_b128 v[210:213], v101 offset:32784
	s_waitcnt lgkmcnt(3)
; #define LAS __attribute__((address_space(3)))
; __device__ void sample_ret_unit(const Params& p, int l, int unit, LAS unsigned char* lds, const int tid_in) {
;     ...
; #pragma unroll
;         for (int u = 0; u < 8; ++u) {
;             const f32x4 q0 = *(const LAS f32x4*)(sqT + (d0 + u) * 8), q1 = *(const LAS f32x4*)(sqT + (d0 + u) * 8 + 4);
;             const f32x4 k0 = *(const LAS f32x4*)(skdT + (d0 + u) * 8), k1 = *(const LAS f32x4*)(skdT + (d0 + u) * 8 + 4);
;             f32x4 sn = S4[u] * g8;
;             sn += vv[0] * k0[0]; sn += vv[1] * k0[1]; sn += vv[2] * k0[2]; sn += vv[3] * k0[3];
;             sn += vv[4] * k1[0]; sn += vv[5] * k1[1]; sn += vv[6] * k1[2]; sn += vv[7] * k1[3];
;             __builtin_nontemporal_store(sn, (f32x4*)(Sout + (size_t)(d0 + u) * 256 + e4));
;             oacc[0] += S4[u] * q0[0]; oacc[1] += S4[u] * q0[1]; oacc[2] += S4[u] * q0[2]; oacc[3] += S4[u] * q0[3];
;             oacc[4] += S4[u] * q1[0]; oacc[5] += S4[u] * q1[1]; oacc[6] += S4[u] * q1[2]; oacc[7] += S4[u] * q1[3];
;         }
	v_pk_mul_f32 v[216:217], v[16:17], v[182:183] op_sel_hi:[1,0]
	v_pk_mul_f32 v[218:219], v[14:15], v[182:183] op_sel_hi:[1,0]
	s_waitcnt vmcnt(23)
	v_pk_fma_f32 v[216:217], v[144:145], v[44:45], v[216:217] op_sel_hi:[0,1,1]
	v_pk_fma_f32 v[218:219], v[144:145], v[42:43], v[218:219] op_sel_hi:[0,1,1]
	v_pk_fma_f32 v[216:217], v[12:13], v[182:183], v[216:217] op_sel:[0,1,0]
	v_pk_fma_f32 v[182:183], v[10:11], v[182:183], v[218:219] op_sel:[0,1,0]
	v_pk_fma_f32 v[216:217], v[8:9], v[184:185], v[216:217] op_sel_hi:[1,0,1]
	v_pk_fma_f32 v[182:183], v[6:7], v[184:185], v[182:183] op_sel_hi:[1,0,1]
	v_mov_b32_e32 v184, v185
	v_pk_fma_f32 v[216:217], v[4:5], v[184:185], v[216:217] op_sel_hi:[1,0,1]
	v_pk_fma_f32 v[182:183], v[2:3], v[184:185], v[182:183] op_sel_hi:[1,0,1]
	s_waitcnt lgkmcnt(0)
	v_pk_fma_f32 v[184:185], v[32:33], v[210:211], v[216:217] op_sel_hi:[1,0,1]
	v_pk_fma_f32 v[182:183], v[30:31], v[210:211], v[182:183] op_sel_hi:[1,0,1]
	v_pk_fma_f32 v[184:185], v[28:29], v[210:211], v[184:185] op_sel:[0,1,0]
	v_pk_fma_f32 v[182:183], v[26:27], v[210:211], v[182:183] op_sel:[0,1,0]
	v_pk_fma_f32 v[184:185], v[24:25], v[212:213], v[184:185] op_sel_hi:[1,0,1]
	v_pk_fma_f32 v[182:183], v[22:23], v[212:213], v[182:183] op_sel_hi:[1,0,1]
	v_mov_b32_e32 v210, v213
	v_pk_fma_f32 v[184:185], v[20:21], v[210:211], v[184:185] op_sel_hi:[1,0,1]
	v_pk_fma_f32 v[182:183], v[18:19], v[210:211], v[182:183] op_sel_hi:[1,0,1]
	v_lshlrev_b64 v[210:211], 10, v[214:215]
	v_add_u32_e32 v178, 7, v178
	v_lshl_add_u64 v[210:211], v[146:147], 0, v[210:211]
	v_lshl_add_u32 v101, v178, 5, 0
	global_store_dwordx4 v[210:211], v[182:185], off nt
	ds_read_b128 v[182:185], v101 offset:32768
	v_mov_b32_e32 v210, v209
	v_pk_fma_f32 v[192:193], v[44:45], v[210:211], v[192:193] op_sel_hi:[1,0,1]
	v_pk_fma_f32 v[194:195], v[42:43], v[210:211], v[194:195] op_sel_hi:[1,0,1]
	ds_read_b128 v[210:213], v101 offset:24576
	ds_read_b128 v[214:217], v101 offset:24592
	ds_read_b128 v[218:221], v101 offset:32784
	s_waitcnt lgkmcnt(3)
	v_pk_mul_f32 v[222:223], v[16:17], v[182:183] op_sel_hi:[1,0]
	v_pk_mul_f32 v[224:225], v[14:15], v[182:183] op_sel_hi:[1,0]
	s_waitcnt vmcnt(23)
	v_pk_fma_f32 v[222:223], v[144:145], v[36:37], v[222:223] op_sel_hi:[0,1,1]
	v_pk_fma_f32 v[224:225], v[144:145], v[34:35], v[224:225] op_sel_hi:[0,1,1]
	v_pk_fma_f32 v[222:223], v[12:13], v[182:183], v[222:223] op_sel:[0,1,0]
	v_pk_fma_f32 v[182:183], v[10:11], v[182:183], v[224:225] op_sel:[0,1,0]
	v_pk_fma_f32 v[222:223], v[8:9], v[184:185], v[222:223] op_sel_hi:[1,0,1]
	v_pk_fma_f32 v[182:183], v[6:7], v[184:185], v[182:183] op_sel_hi:[1,0,1]
	v_mov_b32_e32 v184, v185
	v_pk_fma_f32 v[222:223], v[4:5], v[184:185], v[222:223] op_sel_hi:[1,0,1]
	v_pk_fma_f32 v[182:183], v[2:3], v[184:185], v[182:183] op_sel_hi:[1,0,1]
	v_pk_fma_f32 v[156:157], v[92:93], v[104:105], v[158:159] op_sel_hi:[1,0,1]
	v_pk_fma_f32 v[158:159], v[90:91], v[104:105], v[160:161] op_sel_hi:[1,0,1]
	v_mov_b32_e32 v104, v105
	s_waitcnt lgkmcnt(0)
	v_pk_fma_f32 v[184:185], v[32:33], v[218:219], v[222:223] op_sel_hi:[1,0,1]
	v_pk_fma_f32 v[182:183], v[30:31], v[218:219], v[182:183] op_sel_hi:[1,0,1]
	v_pk_fma_f32 v[160:161], v[92:93], v[104:105], v[162:163] op_sel_hi:[1,0,1]
	v_pk_fma_f32 v[104:105], v[90:91], v[104:105], v[164:165] op_sel_hi:[1,0,1]
	v_pk_fma_f32 v[162:163], v[92:93], v[98:99], v[166:167] op_sel_hi:[1,0,1]
	v_pk_fma_f32 v[164:165], v[90:91], v[98:99], v[168:169] op_sel_hi:[1,0,1]
	v_pk_fma_f32 v[166:167], v[92:93], v[98:99], v[170:171] op_sel:[0,1,0]
	v_pk_fma_f32 v[98:99], v[90:91], v[98:99], v[172:173] op_sel:[0,1,0]
	v_pk_fma_f32 v[92:93], v[92:93], v[100:101], v[174:175] op_sel_hi:[1,0,1]
	v_pk_fma_f32 v[90:91], v[90:91], v[100:101], v[176:177] op_sel_hi:[1,0,1]
	v_pk_fma_f32 v[100:101], v[84:85], v[110:111], v[150:151] op_sel_hi:[1,0,1]
	v_pk_fma_f32 v[150:151], v[82:83], v[110:111], v[152:153] op_sel_hi:[1,0,1]
	v_pk_fma_f32 v[152:153], v[84:85], v[110:111], v[154:155] op_sel:[0,1,0]
	v_pk_fma_f32 v[102:103], v[82:83], v[110:111], v[102:103] op_sel:[0,1,0]
	v_pk_fma_f32 v[110:111], v[84:85], v[112:113], v[156:157] op_sel_hi:[1,0,1]
	v_pk_fma_f32 v[154:155], v[82:83], v[112:113], v[158:159] op_sel_hi:[1,0,1]
	v_mov_b32_e32 v112, v113
	v_pk_fma_f32 v[184:185], v[28:29], v[218:219], v[184:185] op_sel:[0,1,0]
	v_pk_fma_f32 v[182:183], v[26:27], v[218:219], v[182:183] op_sel:[0,1,0]
	v_ashrrev_i32_e32 v179, 31, v178
	v_pk_fma_f32 v[156:157], v[84:85], v[112:113], v[160:161] op_sel_hi:[1,0,1]
	v_pk_fma_f32 v[104:105], v[82:83], v[112:113], v[104:105] op_sel_hi:[1,0,1]
	v_pk_fma_f32 v[112:113], v[84:85], v[106:107], v[162:163] op_sel_hi:[1,0,1]
	v_pk_fma_f32 v[158:159], v[82:83], v[106:107], v[164:165] op_sel_hi:[1,0,1]
	v_pk_fma_f32 v[160:161], v[84:85], v[106:107], v[166:167] op_sel:[0,1,0]
	v_pk_fma_f32 v[98:99], v[82:83], v[106:107], v[98:99] op_sel:[0,1,0]
	v_pk_fma_f32 v[84:85], v[84:85], v[108:109], v[92:93] op_sel_hi:[1,0,1]
	v_pk_fma_f32 v[82:83], v[82:83], v[108:109], v[90:91] op_sel_hi:[1,0,1]
	v_pk_fma_f32 v[90:91], v[72:73], v[118:119], v[100:101] op_sel_hi:[1,0,1]
	v_pk_fma_f32 v[100:101], v[72:73], v[118:119], v[152:153] op_sel:[0,1,0]
	v_pk_fma_f32 v[106:107], v[72:73], v[120:121], v[110:111] op_sel_hi:[1,0,1]
	v_mov_b32_e32 v110, v121
	v_pk_fma_f32 v[184:185], v[24:25], v[220:221], v[184:185] op_sel_hi:[1,0,1]
	v_pk_fma_f32 v[182:183], v[22:23], v[220:221], v[182:183] op_sel_hi:[1,0,1]
	v_mov_b32_e32 v218, v221
	v_lshlrev_b64 v[178:179], 10, v[178:179]
	v_pk_fma_f32 v[92:93], v[70:71], v[118:119], v[150:151] op_sel_hi:[1,0,1]
	v_pk_fma_f32 v[102:103], v[70:71], v[118:119], v[102:103] op_sel:[0,1,0]
; #define LAS __attribute__((address_space(3)))
; __device__ void sample_ret_unit(const Params& p, int l, int unit, LAS unsigned char* lds, const int tid_in) {
;     ...
; #pragma unroll
;         for (int u = 0; u < 8; ++u) {
;             const f32x4 q0 = *(const LAS f32x4*)(sqT + (d0 + u) * 8), q1 = *(const LAS f32x4*)(sqT + (d0 + u) * 8 + 4);
;             const f32x4 k0 = *(const LAS f32x4*)(skdT + (d0 + u) * 8), k1 = *(const LAS f32x4*)(skdT + (d0 + u) * 8 + 4);
;             f32x4 sn = S4[u] * g8;
;             sn += vv[0] * k0[0]; sn += vv[1] * k0[1]; sn += vv[2] * k0[2]; sn += vv[3] * k0[3];
;             sn += vv[4] * k1[0]; sn += vv[5] * k1[1]; sn += vv[6] * k1[2]; sn += vv[7] * k1[3];
;             __builtin_nontemporal_store(sn, (f32x4*)(Sout + (size_t)(d0 + u) * 256 + e4));
;             oacc[0] += S4[u] * q0[0]; oacc[1] += S4[u] * q0[1]; oacc[2] += S4[u] * q0[2]; oacc[3] += S4[u] * q0[3];
;             oacc[4] += S4[u] * q1[0]; oacc[5] += S4[u] * q1[1]; oacc[6] += S4[u] * q1[2]; oacc[7] += S4[u] * q1[3];
;         }
	v_pk_fma_f32 v[108:109], v[70:71], v[120:121], v[154:155] op_sel_hi:[1,0,1]
	v_pk_fma_f32 v[118:119], v[72:73], v[110:111], v[156:157] op_sel_hi:[1,0,1]
	v_pk_fma_f32 v[104:105], v[70:71], v[110:111], v[104:105] op_sel_hi:[1,0,1]
	v_pk_fma_f32 v[110:111], v[72:73], v[114:115], v[112:113] op_sel_hi:[1,0,1]
	v_pk_fma_f32 v[112:113], v[70:71], v[114:115], v[158:159] op_sel_hi:[1,0,1]
	v_pk_fma_f32 v[120:121], v[72:73], v[114:115], v[160:161] op_sel:[0,1,0]
	v_pk_fma_f32 v[98:99], v[70:71], v[114:115], v[98:99] op_sel:[0,1,0]
	v_pk_fma_f32 v[72:73], v[72:73], v[116:117], v[84:85] op_sel_hi:[1,0,1]
	v_pk_fma_f32 v[70:71], v[70:71], v[116:117], v[82:83] op_sel_hi:[1,0,1]
	v_pk_fma_f32 v[82:83], v[68:69], v[126:127], v[90:91] op_sel_hi:[1,0,1]
	v_pk_fma_f32 v[90:91], v[68:69], v[126:127], v[100:101] op_sel:[0,1,0]
	v_pk_fma_f32 v[100:101], v[68:69], v[128:129], v[106:107] op_sel_hi:[1,0,1]
	v_mov_b32_e32 v106, v129
	v_pk_fma_f32 v[184:185], v[20:21], v[218:219], v[184:185] op_sel_hi:[1,0,1]
	v_pk_fma_f32 v[182:183], v[18:19], v[218:219], v[182:183] op_sel_hi:[1,0,1]
	v_lshl_add_u64 v[178:179], v[146:147], 0, v[178:179]
	v_pk_fma_f32 v[84:85], v[66:67], v[126:127], v[92:93] op_sel_hi:[1,0,1]
	v_pk_fma_f32 v[92:93], v[66:67], v[126:127], v[102:103] op_sel:[0,1,0]
	v_pk_fma_f32 v[102:103], v[66:67], v[128:129], v[108:109] op_sel_hi:[1,0,1]
	v_pk_fma_f32 v[108:109], v[68:69], v[106:107], v[118:119] op_sel_hi:[1,0,1]
	v_pk_fma_f32 v[104:105], v[66:67], v[106:107], v[104:105] op_sel_hi:[1,0,1]
	v_pk_fma_f32 v[106:107], v[68:69], v[122:123], v[110:111] op_sel_hi:[1,0,1]
	v_pk_fma_f32 v[110:111], v[66:67], v[122:123], v[112:113] op_sel_hi:[1,0,1]
	v_pk_fma_f32 v[112:113], v[68:69], v[122:123], v[120:121] op_sel:[0,1,0]
	v_pk_fma_f32 v[98:99], v[66:67], v[122:123], v[98:99] op_sel:[0,1,0]
	v_pk_fma_f32 v[68:69], v[68:69], v[124:125], v[72:73] op_sel_hi:[1,0,1]
	v_pk_fma_f32 v[66:67], v[66:67], v[124:125], v[70:71] op_sel_hi:[1,0,1]
	v_pk_fma_f32 v[70:71], v[60:61], v[134:135], v[82:83] op_sel_hi:[1,0,1]
	v_pk_fma_f32 v[82:83], v[60:61], v[134:135], v[90:91] op_sel:[0,1,0]
	v_pk_fma_f32 v[90:91], v[60:61], v[136:137], v[100:101] op_sel_hi:[1,0,1]
	v_mov_b32_e32 v100, v137
	global_store_dwordx4 v[178:179], v[182:185], off nt
	v_pk_fma_f32 v[72:73], v[58:59], v[134:135], v[84:85] op_sel_hi:[1,0,1]
	v_pk_fma_f32 v[84:85], v[58:59], v[134:135], v[92:93] op_sel:[0,1,0]
	v_pk_fma_f32 v[92:93], v[58:59], v[136:137], v[102:103] op_sel_hi:[1,0,1]
	v_pk_fma_f32 v[102:103], v[60:61], v[100:101], v[108:109] op_sel_hi:[1,0,1]
	v_pk_fma_f32 v[100:101], v[58:59], v[100:101], v[104:105] op_sel_hi:[1,0,1]
	v_pk_fma_f32 v[104:105], v[60:61], v[130:131], v[106:107] op_sel_hi:[1,0,1]
	v_pk_fma_f32 v[106:107], v[58:59], v[130:131], v[110:111] op_sel_hi:[1,0,1]
	v_pk_fma_f32 v[108:109], v[60:61], v[130:131], v[112:113] op_sel:[0,1,0]
	v_pk_fma_f32 v[98:99], v[58:59], v[130:131], v[98:99] op_sel:[0,1,0]
	v_pk_fma_f32 v[60:61], v[60:61], v[132:133], v[68:69] op_sel_hi:[1,0,1]
	v_pk_fma_f32 v[58:59], v[58:59], v[132:133], v[66:67] op_sel_hi:[1,0,1]
	v_pk_fma_f32 v[66:67], v[52:53], v[186:187], v[70:71] op_sel_hi:[1,0,1]
	v_pk_fma_f32 v[70:71], v[52:53], v[186:187], v[82:83] op_sel:[0,1,0]
	v_pk_fma_f32 v[82:83], v[52:53], v[188:189], v[90:91] op_sel_hi:[1,0,1]
	v_mov_b32_e32 v90, v189
	v_or_b32_e32 v176, 16, v142
	v_pk_fma_f32 v[68:69], v[50:51], v[186:187], v[72:73] op_sel_hi:[1,0,1]
	v_pk_fma_f32 v[72:73], v[50:51], v[186:187], v[84:85] op_sel:[0,1,0]
	v_pk_fma_f32 v[84:85], v[50:51], v[188:189], v[92:93] op_sel_hi:[1,0,1]
	v_pk_fma_f32 v[92:93], v[52:53], v[90:91], v[102:103] op_sel_hi:[1,0,1]
	v_pk_fma_f32 v[90:91], v[50:51], v[90:91], v[100:101] op_sel_hi:[1,0,1]
	v_pk_fma_f32 v[100:101], v[52:53], v[198:199], v[104:105] op_sel_hi:[1,0,1]
	v_pk_fma_f32 v[102:103], v[50:51], v[198:199], v[106:107] op_sel_hi:[1,0,1]
	v_pk_fma_f32 v[104:105], v[52:53], v[198:199], v[108:109] op_sel:[0,1,0]
	v_pk_fma_f32 v[98:99], v[50:51], v[198:199], v[98:99] op_sel:[0,1,0]
	v_pk_fma_f32 v[52:53], v[52:53], v[200:201], v[60:61] op_sel_hi:[1,0,1]
	v_pk_fma_f32 v[50:51], v[50:51], v[200:201], v[58:59] op_sel_hi:[1,0,1]
	v_pk_fma_f32 v[58:59], v[44:45], v[202:203], v[66:67] op_sel_hi:[1,0,1]
	v_pk_fma_f32 v[66:67], v[44:45], v[202:203], v[70:71] op_sel:[0,1,0]
	v_pk_fma_f32 v[70:71], v[44:45], v[204:205], v[82:83] op_sel_hi:[1,0,1]
	v_mov_b32_e32 v82, v205
	v_mov_b32_e32 v178, v217
	v_ashrrev_i32_e32 v177, 31, v176
	v_pk_fma_f32 v[60:61], v[42:43], v[202:203], v[68:69] op_sel_hi:[1,0,1]
	v_pk_fma_f32 v[68:69], v[42:43], v[202:203], v[72:73] op_sel:[0,1,0]
	v_pk_fma_f32 v[72:73], v[42:43], v[204:205], v[84:85] op_sel_hi:[1,0,1]
	v_pk_fma_f32 v[84:85], v[44:45], v[82:83], v[92:93] op_sel_hi:[1,0,1]
	v_pk_fma_f32 v[82:83], v[42:43], v[82:83], v[90:91] op_sel_hi:[1,0,1]
	v_pk_fma_f32 v[90:91], v[44:45], v[206:207], v[100:101] op_sel_hi:[1,0,1]
	v_pk_fma_f32 v[92:93], v[42:43], v[206:207], v[102:103] op_sel_hi:[1,0,1]
	v_pk_fma_f32 v[100:101], v[44:45], v[206:207], v[104:105] op_sel:[0,1,0]
	v_pk_fma_f32 v[98:99], v[42:43], v[206:207], v[98:99] op_sel:[0,1,0]
	v_pk_fma_f32 v[44:45], v[44:45], v[208:209], v[52:53] op_sel_hi:[1,0,1]
	v_pk_fma_f32 v[102:103], v[42:43], v[208:209], v[50:51] op_sel_hi:[1,0,1]
	v_mov_b32_e32 v42, v213
	v_lshlrev_b64 v[114:115], 10, v[176:177]
	v_pk_fma_f32 v[182:183], v[36:37], v[178:179], v[192:193] op_sel_hi:[1,0,1]
	v_pk_fma_f32 v[150:151], v[36:37], v[210:211], v[58:59] op_sel_hi:[1,0,1]
	v_pk_fma_f32 v[154:155], v[36:37], v[210:211], v[66:67] op_sel:[0,1,0]
	v_pk_fma_f32 v[158:159], v[36:37], v[212:213], v[70:71] op_sel_hi:[1,0,1]
; #define LAS __attribute__((address_space(3)))
; __device__ __forceinline__ int launder(int v) { asm volatile("" : "+v"(v)); return v; }
; __device__ void sample_ret_unit(const Params& p, int l, int unit, LAS unsigned char* lds, const int tid_in) {
;     ...
;     for (int dd = 0; dd < 32; dd += 8) {
;         const int d0 = launder(wid * 32 + dd);
;         const int dn = dd + 8 < 32 ? d0 + 8 : d0;
; #pragma unroll
;         for (int u = 0; u < 8; ++u) N4[u] = __builtin_nontemporal_load((const f32x4*)(Sin + (size_t)(dn + u) * 256 + e4));
;         asm volatile("" ::: "memory");
; #pragma unroll
;         for (int u = 0; u < 8; ++u) {
;             const f32x4 q0 = *(const LAS f32x4*)(sqT + (d0 + u) * 8), q1 = *(const LAS f32x4*)(sqT + (d0 + u) * 8 + 4);
;             const f32x4 k0 = *(const LAS f32x4*)(skdT + (d0 + u) * 8), k1 = *(const LAS f32x4*)(skdT + (d0 + u) * 8 + 4);
;             f32x4 sn = S4[u] * g8;
;             sn += vv[0] * k0[0]; sn += vv[1] * k0[1]; sn += vv[2] * k0[2]; sn += vv[3] * k0[3];
;             sn += vv[4] * k1[0]; sn += vv[5] * k1[1]; sn += vv[6] * k1[2]; sn += vv[7] * k1[3];
;             __builtin_nontemporal_store(sn, (f32x4*)(Sout + (size_t)(d0 + u) * 256 + e4));
;             oacc[0] += S4[u] * q0[0]; oacc[1] += S4[u] * q0[1]; oacc[2] += S4[u] * q0[2]; oacc[3] += S4[u] * q0[3];
;             oacc[4] += S4[u] * q1[0]; oacc[5] += S4[u] * q1[1]; oacc[6] += S4[u] * q1[2]; oacc[7] += S4[u] * q1[3];
;         }
	v_pk_fma_f32 v[162:163], v[36:37], v[42:43], v[84:85] op_sel_hi:[1,0,1]
	v_pk_fma_f32 v[166:167], v[36:37], v[214:215], v[90:91] op_sel_hi:[1,0,1]
	v_pk_fma_f32 v[170:171], v[36:37], v[214:215], v[100:101] op_sel:[0,1,0]
	v_pk_fma_f32 v[174:175], v[36:37], v[216:217], v[44:45] op_sel_hi:[1,0,1]
	v_lshl_add_u64 v[36:37], v[148:149], 0, v[114:115]
	v_pk_fma_f32 v[164:165], v[34:35], v[42:43], v[82:83] op_sel_hi:[1,0,1]
	v_add_co_u32_e32 v42, vcc, s6, v36
	v_pk_fma_f32 v[152:153], v[34:35], v[210:211], v[60:61] op_sel_hi:[1,0,1]
	s_nop 0
	v_addc_co_u32_e32 v43, vcc, 0, v37, vcc
	v_add_co_u32_e32 v36, vcc, s7, v36
	v_pk_fma_f32 v[156:157], v[34:35], v[210:211], v[68:69] op_sel:[0,1,0]
	v_pk_fma_f32 v[160:161], v[34:35], v[212:213], v[72:73] op_sel_hi:[1,0,1]
	v_pk_fma_f32 v[168:169], v[34:35], v[214:215], v[92:93] op_sel_hi:[1,0,1]
	v_pk_fma_f32 v[172:173], v[34:35], v[214:215], v[98:99] op_sel:[0,1,0]
	v_addc_co_u32_e32 v37, vcc, 0, v37, vcc
	global_load_dwordx4 v[90:93], v[42:43], off offset:1024 nt
	global_load_dwordx4 v[82:85], v[42:43], off offset:2048 nt
	global_load_dwordx4 v[98:101], v[36:37], off offset:-4096 nt
	global_load_dwordx4 v[70:73], v[42:43], off offset:3072 nt
	global_load_dwordx4 v[66:69], v[36:37], off nt
	global_load_dwordx4 v[58:61], v[36:37], off offset:1024 nt
	global_load_dwordx4 v[50:53], v[36:37], off offset:2048 nt
	s_nop 0
	global_load_dwordx4 v[42:45], v[36:37], off offset:3072 nt
	v_lshl_add_u32 v110, v176, 5, 0
	ds_read_b128 v[106:109], v110 offset:32768
	v_pk_fma_f32 v[178:179], v[34:35], v[178:179], v[194:195] op_sel_hi:[1,0,1]
	v_pk_fma_f32 v[148:149], v[34:35], v[216:217], v[102:103] op_sel_hi:[1,0,1]
	ds_read_b128 v[102:105], v110 offset:24576
	ds_read_b128 v[34:37], v110 offset:24592
	ds_read_b128 v[110:113], v110 offset:32784
	v_add_u32_e32 v124, 1, v176
	s_waitcnt lgkmcnt(3)
	v_pk_mul_f32 v[116:117], v[16:17], v[106:107] op_sel_hi:[1,0]
	v_pk_mul_f32 v[118:119], v[14:15], v[106:107] op_sel_hi:[1,0]
	s_waitcnt vmcnt(21)
	v_pk_fma_f32 v[116:117], v[144:145], v[96:97], v[116:117] op_sel_hi:[0,1,1]
	v_pk_fma_f32 v[118:119], v[144:145], v[94:95], v[118:119] op_sel_hi:[0,1,1]
	v_pk_fma_f32 v[116:117], v[12:13], v[106:107], v[116:117] op_sel:[0,1,0]
	v_pk_fma_f32 v[106:107], v[10:11], v[106:107], v[118:119] op_sel:[0,1,0]
	v_pk_fma_f32 v[116:117], v[8:9], v[108:109], v[116:117] op_sel_hi:[1,0,1]
	v_pk_fma_f32 v[106:107], v[6:7], v[108:109], v[106:107] op_sel_hi:[1,0,1]
	v_mov_b32_e32 v108, v109
	v_pk_fma_f32 v[116:117], v[4:5], v[108:109], v[116:117] op_sel_hi:[1,0,1]
	v_pk_fma_f32 v[106:107], v[2:3], v[108:109], v[106:107] op_sel_hi:[1,0,1]
	s_waitcnt lgkmcnt(0)
	v_pk_fma_f32 v[108:109], v[32:33], v[110:111], v[116:117] op_sel_hi:[1,0,1]
	v_pk_fma_f32 v[106:107], v[30:31], v[110:111], v[106:107] op_sel_hi:[1,0,1]
	v_pk_fma_f32 v[108:109], v[28:29], v[110:111], v[108:109] op_sel:[0,1,0]
	v_pk_fma_f32 v[106:107], v[26:27], v[110:111], v[106:107] op_sel:[0,1,0]
	v_pk_fma_f32 v[108:109], v[24:25], v[112:113], v[108:109] op_sel_hi:[1,0,1]
	v_pk_fma_f32 v[106:107], v[22:23], v[112:113], v[106:107] op_sel_hi:[1,0,1]
	v_mov_b32_e32 v110, v113
	v_pk_fma_f32 v[108:109], v[20:21], v[110:111], v[108:109] op_sel_hi:[1,0,1]
	v_pk_fma_f32 v[106:107], v[18:19], v[110:111], v[106:107] op_sel_hi:[1,0,1]
	v_lshl_add_u64 v[110:111], v[146:147], 0, v[114:115]
	global_store_dwordx4 v[110:111], v[106:109], off nt
	v_ashrrev_i32_e32 v125, 31, v124
	v_add_u32_e32 v132, 2, v176
	v_mov_b32_e32 v106, v37
	v_lshl_add_u32 v37, v124, 5, 0
	ds_read_b128 v[114:117], v37 offset:32768
	v_pk_fma_f32 v[122:123], v[96:97], v[106:107], v[182:183] op_sel_hi:[1,0,1]
	v_pk_fma_f32 v[126:127], v[94:95], v[106:107], v[178:179] op_sel_hi:[1,0,1]
	ds_read_b128 v[110:113], v37 offset:24576
	ds_read_b128 v[106:109], v37 offset:24592
	ds_read_b128 v[118:121], v37 offset:32784
	v_lshl_add_u32 v37, v132, 5, 0
	s_waitcnt lgkmcnt(3)
	v_pk_mul_f32 v[128:129], v[16:17], v[114:115] op_sel_hi:[1,0]
	v_pk_mul_f32 v[130:131], v[14:15], v[114:115] op_sel_hi:[1,0]
	v_pk_fma_f32 v[128:129], v[144:145], v[88:89], v[128:129] op_sel_hi:[0,1,1]
	v_pk_fma_f32 v[130:131], v[144:145], v[86:87], v[130:131] op_sel_hi:[0,1,1]
	v_pk_fma_f32 v[128:129], v[12:13], v[114:115], v[128:129] op_sel:[0,1,0]
	v_pk_fma_f32 v[114:115], v[10:11], v[114:115], v[130:131] op_sel:[0,1,0]
	v_pk_fma_f32 v[128:129], v[8:9], v[116:117], v[128:129] op_sel_hi:[1,0,1]
	v_pk_fma_f32 v[114:115], v[6:7], v[116:117], v[114:115] op_sel_hi:[1,0,1]
	v_mov_b32_e32 v116, v117
	v_pk_fma_f32 v[128:129], v[4:5], v[116:117], v[128:129] op_sel_hi:[1,0,1]
	v_pk_fma_f32 v[114:115], v[2:3], v[116:117], v[114:115] op_sel_hi:[1,0,1]
	s_waitcnt lgkmcnt(0)
	v_pk_fma_f32 v[116:117], v[32:33], v[118:119], v[128:129] op_sel_hi:[1,0,1]
	v_pk_fma_f32 v[114:115], v[30:31], v[118:119], v[114:115] op_sel_hi:[1,0,1]
	v_pk_fma_f32 v[116:117], v[28:29], v[118:119], v[116:117] op_sel:[0,1,0]
	v_pk_fma_f32 v[114:115], v[26:27], v[118:119], v[114:115] op_sel:[0,1,0]
	v_pk_fma_f32 v[116:117], v[24:25], v[120:121], v[116:117] op_sel_hi:[1,0,1]
	v_pk_fma_f32 v[114:115], v[22:23], v[120:121], v[114:115] op_sel_hi:[1,0,1]
	v_mov_b32_e32 v118, v121
	v_pk_fma_f32 v[116:117], v[20:21], v[118:119], v[116:117] op_sel_hi:[1,0,1]
	v_pk_fma_f32 v[114:115], v[18:19], v[118:119], v[114:115] op_sel_hi:[1,0,1]
	v_lshlrev_b64 v[118:119], 10, v[124:125]
	v_lshl_add_u64 v[118:119], v[146:147], 0, v[118:119]
	global_store_dwordx4 v[118:119], v[114:117], off nt
	v_ashrrev_i32_e32 v133, 31, v132
	v_add_u32_e32 v182, 3, v176
	v_mov_b32_e32 v114, v109
	v_pk_fma_f32 v[130:131], v[88:89], v[114:115], v[122:123] op_sel_hi:[1,0,1]
	ds_read_b128 v[122:125], v37 offset:32768
	v_pk_fma_f32 v[134:135], v[86:87], v[114:115], v[126:127] op_sel_hi:[1,0,1]
	ds_read_b128 v[118:121], v37 offset:24576
	ds_read_b128 v[114:117], v37 offset:24592
	ds_read_b128 v[126:129], v37 offset:32784
	v_lshl_add_u32 v37, v182, 5, 0
	v_add_u32_e32 v192, 4, v176
	s_waitcnt lgkmcnt(3)
; #define LAS __attribute__((address_space(3)))
; __device__ void sample_ret_unit(const Params& p, int l, int unit, LAS unsigned char* lds, const int tid_in) {
;     ...
; #pragma unroll
;         for (int u = 0; u < 8; ++u) {
;             const f32x4 q0 = *(const LAS f32x4*)(sqT + (d0 + u) * 8), q1 = *(const LAS f32x4*)(sqT + (d0 + u) * 8 + 4);
;             const f32x4 k0 = *(const LAS f32x4*)(skdT + (d0 + u) * 8), k1 = *(const LAS f32x4*)(skdT + (d0 + u) * 8 + 4);
;             f32x4 sn = S4[u] * g8;
;             sn += vv[0] * k0[0]; sn += vv[1] * k0[1]; sn += vv[2] * k0[2]; sn += vv[3] * k0[3];
;             sn += vv[4] * k1[0]; sn += vv[5] * k1[1]; sn += vv[6] * k1[2]; sn += vv[7] * k1[3];
;             __builtin_nontemporal_store(sn, (f32x4*)(Sout + (size_t)(d0 + u) * 256 + e4));
;             oacc[0] += S4[u] * q0[0]; oacc[1] += S4[u] * q0[1]; oacc[2] += S4[u] * q0[2]; oacc[3] += S4[u] * q0[3];
;             oacc[4] += S4[u] * q1[0]; oacc[5] += S4[u] * q1[1]; oacc[6] += S4[u] * q1[2]; oacc[7] += S4[u] * q1[3];
;         }
	v_pk_mul_f32 v[136:137], v[16:17], v[122:123] op_sel_hi:[1,0]
	v_pk_mul_f32 v[178:179], v[14:15], v[122:123] op_sel_hi:[1,0]
	v_pk_fma_f32 v[136:137], v[144:145], v[80:81], v[136:137] op_sel_hi:[0,1,1]
	v_pk_fma_f32 v[178:179], v[144:145], v[78:79], v[178:179] op_sel_hi:[0,1,1]
	v_pk_fma_f32 v[136:137], v[12:13], v[122:123], v[136:137] op_sel:[0,1,0]
	v_pk_fma_f32 v[122:123], v[10:11], v[122:123], v[178:179] op_sel:[0,1,0]
	v_pk_fma_f32 v[136:137], v[8:9], v[124:125], v[136:137] op_sel_hi:[1,0,1]
	v_pk_fma_f32 v[122:123], v[6:7], v[124:125], v[122:123] op_sel_hi:[1,0,1]
	v_mov_b32_e32 v124, v125
	v_pk_fma_f32 v[136:137], v[4:5], v[124:125], v[136:137] op_sel_hi:[1,0,1]
	v_pk_fma_f32 v[122:123], v[2:3], v[124:125], v[122:123] op_sel_hi:[1,0,1]
	s_waitcnt lgkmcnt(0)
	v_pk_fma_f32 v[124:125], v[32:33], v[126:127], v[136:137] op_sel_hi:[1,0,1]
	v_pk_fma_f32 v[122:123], v[30:31], v[126:127], v[122:123] op_sel_hi:[1,0,1]
	v_pk_fma_f32 v[124:125], v[28:29], v[126:127], v[124:125] op_sel:[0,1,0]
	v_pk_fma_f32 v[122:123], v[26:27], v[126:127], v[122:123] op_sel:[0,1,0]
	v_pk_fma_f32 v[124:125], v[24:25], v[128:129], v[124:125] op_sel_hi:[1,0,1]
	v_pk_fma_f32 v[122:123], v[22:23], v[128:129], v[122:123] op_sel_hi:[1,0,1]
	v_mov_b32_e32 v126, v129
	v_pk_fma_f32 v[124:125], v[20:21], v[126:127], v[124:125] op_sel_hi:[1,0,1]
	v_pk_fma_f32 v[122:123], v[18:19], v[126:127], v[122:123] op_sel_hi:[1,0,1]
	v_lshlrev_b64 v[126:127], 10, v[132:133]
	v_lshl_add_u64 v[126:127], v[146:147], 0, v[126:127]
	global_store_dwordx4 v[126:127], v[122:125], off nt
	v_ashrrev_i32_e32 v183, 31, v182
	v_ashrrev_i32_e32 v193, 31, v192
	v_mov_b32_e32 v122, v117
	v_pk_fma_f32 v[178:179], v[80:81], v[122:123], v[130:131] op_sel_hi:[1,0,1]
	ds_read_b128 v[130:133], v37 offset:32768
	v_pk_fma_f32 v[186:187], v[78:79], v[122:123], v[134:135] op_sel_hi:[1,0,1]
	ds_read_b128 v[126:129], v37 offset:24576
	ds_read_b128 v[122:125], v37 offset:24592
	ds_read_b128 v[134:137], v37 offset:32784
	v_lshl_add_u32 v37, v192, 5, 0
	v_add_u32_e32 v214, 6, v176
	s_waitcnt lgkmcnt(3)
	v_pk_mul_f32 v[184:185], v[16:17], v[130:131] op_sel_hi:[1,0]
	v_pk_mul_f32 v[188:189], v[14:15], v[130:131] op_sel_hi:[1,0]
	s_waitcnt vmcnt(23)
	v_pk_fma_f32 v[184:185], v[144:145], v[76:77], v[184:185] op_sel_hi:[0,1,1]
	v_pk_fma_f32 v[188:189], v[144:145], v[74:75], v[188:189] op_sel_hi:[0,1,1]
	v_pk_fma_f32 v[184:185], v[12:13], v[130:131], v[184:185] op_sel:[0,1,0]
	v_pk_fma_f32 v[130:131], v[10:11], v[130:131], v[188:189] op_sel:[0,1,0]
	v_pk_fma_f32 v[184:185], v[8:9], v[132:133], v[184:185] op_sel_hi:[1,0,1]
	v_pk_fma_f32 v[130:131], v[6:7], v[132:133], v[130:131] op_sel_hi:[1,0,1]
	v_mov_b32_e32 v132, v133
	v_pk_fma_f32 v[184:185], v[4:5], v[132:133], v[184:185] op_sel_hi:[1,0,1]
	v_pk_fma_f32 v[130:131], v[2:3], v[132:133], v[130:131] op_sel_hi:[1,0,1]
	s_waitcnt lgkmcnt(0)
	v_pk_fma_f32 v[132:133], v[32:33], v[134:135], v[184:185] op_sel_hi:[1,0,1]
	v_pk_fma_f32 v[130:131], v[30:31], v[134:135], v[130:131] op_sel_hi:[1,0,1]
	v_pk_fma_f32 v[132:133], v[28:29], v[134:135], v[132:133] op_sel:[0,1,0]
	v_pk_fma_f32 v[130:131], v[26:27], v[134:135], v[130:131] op_sel:[0,1,0]
	v_pk_fma_f32 v[132:133], v[24:25], v[136:137], v[132:133] op_sel_hi:[1,0,1]
	v_pk_fma_f32 v[130:131], v[22:23], v[136:137], v[130:131] op_sel_hi:[1,0,1]
	v_mov_b32_e32 v134, v137
	v_pk_fma_f32 v[132:133], v[20:21], v[134:135], v[132:133] op_sel_hi:[1,0,1]
	v_pk_fma_f32 v[130:131], v[18:19], v[134:135], v[130:131] op_sel_hi:[1,0,1]
	v_lshlrev_b64 v[134:135], 10, v[182:183]
	ds_read_b128 v[182:185], v37 offset:32768
	v_lshl_add_u64 v[134:135], v[146:147], 0, v[134:135]
	global_store_dwordx4 v[134:135], v[130:133], off nt
	v_ashrrev_i32_e32 v215, 31, v214
	v_add_u32_e32 v218, 7, v176
	v_mov_b32_e32 v130, v125
	v_pk_fma_f32 v[178:179], v[76:77], v[130:131], v[178:179] op_sel_hi:[1,0,1]
	v_pk_fma_f32 v[194:195], v[74:75], v[130:131], v[186:187] op_sel_hi:[1,0,1]
	ds_read_b128 v[134:137], v37 offset:24576
	ds_read_b128 v[130:133], v37 offset:24592
	ds_read_b128 v[186:189], v37 offset:32784
	s_waitcnt lgkmcnt(3)
	v_pk_mul_f32 v[198:199], v[16:17], v[182:183] op_sel_hi:[1,0]
	v_pk_mul_f32 v[200:201], v[14:15], v[182:183] op_sel_hi:[1,0]
	s_waitcnt vmcnt(23)
	v_pk_fma_f32 v[198:199], v[144:145], v[64:65], v[198:199] op_sel_hi:[0,1,1]
	v_pk_fma_f32 v[200:201], v[144:145], v[62:63], v[200:201] op_sel_hi:[0,1,1]
	v_pk_fma_f32 v[198:199], v[12:13], v[182:183], v[198:199] op_sel:[0,1,0]
	v_pk_fma_f32 v[182:183], v[10:11], v[182:183], v[200:201] op_sel:[0,1,0]
	v_pk_fma_f32 v[198:199], v[8:9], v[184:185], v[198:199] op_sel_hi:[1,0,1]
	v_pk_fma_f32 v[182:183], v[6:7], v[184:185], v[182:183] op_sel_hi:[1,0,1]
	v_mov_b32_e32 v184, v185
	v_pk_fma_f32 v[198:199], v[4:5], v[184:185], v[198:199] op_sel_hi:[1,0,1]
	v_pk_fma_f32 v[182:183], v[2:3], v[184:185], v[182:183] op_sel_hi:[1,0,1]
	s_waitcnt lgkmcnt(0)
	v_pk_fma_f32 v[184:185], v[32:33], v[186:187], v[198:199] op_sel_hi:[1,0,1]
	v_pk_fma_f32 v[182:183], v[30:31], v[186:187], v[182:183] op_sel_hi:[1,0,1]
	v_pk_fma_f32 v[184:185], v[28:29], v[186:187], v[184:185] op_sel:[0,1,0]
	v_pk_fma_f32 v[182:183], v[26:27], v[186:187], v[182:183] op_sel:[0,1,0]
	v_pk_fma_f32 v[184:185], v[24:25], v[188:189], v[184:185] op_sel_hi:[1,0,1]
	v_pk_fma_f32 v[182:183], v[22:23], v[188:189], v[182:183] op_sel_hi:[1,0,1]
	v_mov_b32_e32 v186, v189
	v_pk_fma_f32 v[184:185], v[20:21], v[186:187], v[184:185] op_sel_hi:[1,0,1]
	v_pk_fma_f32 v[182:183], v[18:19], v[186:187], v[182:183] op_sel_hi:[1,0,1]
	v_lshlrev_b64 v[186:187], 10, v[192:193]
	v_add_u32_e32 v192, 5, v176
	v_lshl_add_u64 v[186:187], v[146:147], 0, v[186:187]
	v_lshl_add_u32 v37, v192, 5, 0
	global_store_dwordx4 v[186:187], v[182:185], off nt
	ds_read_b128 v[182:185], v37 offset:32768
	v_mov_b32_e32 v186, v133
	v_pk_fma_f32 v[178:179], v[64:65], v[186:187], v[178:179] op_sel_hi:[1,0,1]
	v_pk_fma_f32 v[194:195], v[62:63], v[186:187], v[194:195] op_sel_hi:[1,0,1]
	ds_read_b128 v[186:189], v37 offset:24576
	ds_read_b128 v[198:201], v37 offset:24592
	ds_read_b128 v[202:205], v37 offset:32784
	s_waitcnt lgkmcnt(3)
; #define LAS __attribute__((address_space(3)))
; __device__ void sample_ret_unit(const Params& p, int l, int unit, LAS unsigned char* lds, const int tid_in) {
;     ...
; #pragma unroll
;         for (int u = 0; u < 8; ++u) {
;             const f32x4 q0 = *(const LAS f32x4*)(sqT + (d0 + u) * 8), q1 = *(const LAS f32x4*)(sqT + (d0 + u) * 8 + 4);
;             const f32x4 k0 = *(const LAS f32x4*)(skdT + (d0 + u) * 8), k1 = *(const LAS f32x4*)(skdT + (d0 + u) * 8 + 4);
;             f32x4 sn = S4[u] * g8;
;             sn += vv[0] * k0[0]; sn += vv[1] * k0[1]; sn += vv[2] * k0[2]; sn += vv[3] * k0[3];
;             sn += vv[4] * k1[0]; sn += vv[5] * k1[1]; sn += vv[6] * k1[2]; sn += vv[7] * k1[3];
;             __builtin_nontemporal_store(sn, (f32x4*)(Sout + (size_t)(d0 + u) * 256 + e4));
;             oacc[0] += S4[u] * q0[0]; oacc[1] += S4[u] * q0[1]; oacc[2] += S4[u] * q0[2]; oacc[3] += S4[u] * q0[3];
;             oacc[4] += S4[u] * q1[0]; oacc[5] += S4[u] * q1[1]; oacc[6] += S4[u] * q1[2]; oacc[7] += S4[u] * q1[3];
;         }
	v_pk_mul_f32 v[206:207], v[16:17], v[182:183] op_sel_hi:[1,0]
	v_pk_mul_f32 v[208:209], v[14:15], v[182:183] op_sel_hi:[1,0]
	s_waitcnt vmcnt(23)
	v_pk_fma_f32 v[206:207], v[144:145], v[56:57], v[206:207] op_sel_hi:[0,1,1]
	v_pk_fma_f32 v[208:209], v[144:145], v[54:55], v[208:209] op_sel_hi:[0,1,1]
	v_pk_fma_f32 v[206:207], v[12:13], v[182:183], v[206:207] op_sel:[0,1,0]
	v_pk_fma_f32 v[182:183], v[10:11], v[182:183], v[208:209] op_sel:[0,1,0]
	v_pk_fma_f32 v[206:207], v[8:9], v[184:185], v[206:207] op_sel_hi:[1,0,1]
	v_pk_fma_f32 v[182:183], v[6:7], v[184:185], v[182:183] op_sel_hi:[1,0,1]
	v_mov_b32_e32 v184, v185
	v_pk_fma_f32 v[206:207], v[4:5], v[184:185], v[206:207] op_sel_hi:[1,0,1]
	v_pk_fma_f32 v[182:183], v[2:3], v[184:185], v[182:183] op_sel_hi:[1,0,1]
	s_waitcnt lgkmcnt(0)
	v_pk_fma_f32 v[184:185], v[32:33], v[202:203], v[206:207] op_sel_hi:[1,0,1]
	v_pk_fma_f32 v[182:183], v[30:31], v[202:203], v[182:183] op_sel_hi:[1,0,1]
	v_pk_fma_f32 v[184:185], v[28:29], v[202:203], v[184:185] op_sel:[0,1,0]
	v_pk_fma_f32 v[182:183], v[26:27], v[202:203], v[182:183] op_sel:[0,1,0]
	v_ashrrev_i32_e32 v193, 31, v192
	v_pk_fma_f32 v[184:185], v[24:25], v[204:205], v[184:185] op_sel_hi:[1,0,1]
	v_pk_fma_f32 v[182:183], v[22:23], v[204:205], v[182:183] op_sel_hi:[1,0,1]
	v_mov_b32_e32 v202, v205
	v_lshlrev_b64 v[192:193], 10, v[192:193]
	v_pk_fma_f32 v[184:185], v[20:21], v[202:203], v[184:185] op_sel_hi:[1,0,1]
	v_pk_fma_f32 v[182:183], v[18:19], v[202:203], v[182:183] op_sel_hi:[1,0,1]
	v_lshl_add_u64 v[192:193], v[146:147], 0, v[192:193]
	v_lshl_add_u32 v37, v214, 5, 0
	global_store_dwordx4 v[192:193], v[182:185], off nt
	ds_read_b128 v[182:185], v37 offset:32768
	v_mov_b32_e32 v192, v201
	v_pk_fma_f32 v[178:179], v[56:57], v[192:193], v[178:179] op_sel_hi:[1,0,1]
	v_pk_fma_f32 v[192:193], v[54:55], v[192:193], v[194:195] op_sel_hi:[1,0,1]
	ds_read_b128 v[202:205], v37 offset:24576
	ds_read_b128 v[206:209], v37 offset:24592
	ds_read_b128 v[210:213], v37 offset:32784
	s_waitcnt lgkmcnt(3)
	v_pk_mul_f32 v[194:195], v[16:17], v[182:183] op_sel_hi:[1,0]
	v_pk_mul_f32 v[216:217], v[14:15], v[182:183] op_sel_hi:[1,0]
	s_waitcnt vmcnt(23)
	v_pk_fma_f32 v[194:195], v[144:145], v[48:49], v[194:195] op_sel_hi:[0,1,1]
	v_pk_fma_f32 v[216:217], v[144:145], v[46:47], v[216:217] op_sel_hi:[0,1,1]
	v_pk_fma_f32 v[194:195], v[12:13], v[182:183], v[194:195] op_sel:[0,1,0]
	v_pk_fma_f32 v[182:183], v[10:11], v[182:183], v[216:217] op_sel:[0,1,0]
	v_pk_fma_f32 v[194:195], v[8:9], v[184:185], v[194:195] op_sel_hi:[1,0,1]
	v_pk_fma_f32 v[182:183], v[6:7], v[184:185], v[182:183] op_sel_hi:[1,0,1]
	v_mov_b32_e32 v184, v185
	v_pk_fma_f32 v[194:195], v[4:5], v[184:185], v[194:195] op_sel_hi:[1,0,1]
	v_pk_fma_f32 v[182:183], v[2:3], v[184:185], v[182:183] op_sel_hi:[1,0,1]
	s_waitcnt lgkmcnt(0)
	v_pk_fma_f32 v[184:185], v[32:33], v[210:211], v[194:195] op_sel_hi:[1,0,1]
	v_pk_fma_f32 v[182:183], v[30:31], v[210:211], v[182:183] op_sel_hi:[1,0,1]
	v_pk_fma_f32 v[184:185], v[28:29], v[210:211], v[184:185] op_sel:[0,1,0]
	v_pk_fma_f32 v[182:183], v[26:27], v[210:211], v[182:183] op_sel:[0,1,0]
	v_pk_fma_f32 v[184:185], v[24:25], v[212:213], v[184:185] op_sel_hi:[1,0,1]
	v_pk_fma_f32 v[182:183], v[22:23], v[212:213], v[182:183] op_sel_hi:[1,0,1]
	v_mov_b32_e32 v194, v213
	v_pk_fma_f32 v[184:185], v[20:21], v[194:195], v[184:185] op_sel_hi:[1,0,1]
	v_pk_fma_f32 v[182:183], v[18:19], v[194:195], v[182:183] op_sel_hi:[1,0,1]
	v_lshlrev_b64 v[194:195], 10, v[214:215]
	v_lshl_add_u64 v[194:195], v[146:147], 0, v[194:195]
	global_store_dwordx4 v[194:195], v[182:185], off nt
	v_lshl_add_u32 v37, v218, 5, 0
	v_pk_fma_f32 v[150:151], v[96:97], v[102:103], v[150:151] op_sel_hi:[1,0,1]
	v_mov_b32_e32 v182, v209
	v_pk_fma_f32 v[194:195], v[48:49], v[182:183], v[178:179] op_sel_hi:[1,0,1]
	ds_read_b128 v[176:179], v37 offset:32768
	v_pk_fma_f32 v[192:193], v[46:47], v[182:183], v[192:193] op_sel_hi:[1,0,1]
	ds_read_b128 v[182:185], v37 offset:24576
	ds_read_b128 v[210:213], v37 offset:24592
	ds_read_b128 v[214:217], v37 offset:32784
	v_pk_fma_f32 v[152:153], v[94:95], v[102:103], v[152:153] op_sel_hi:[1,0,1]
	v_pk_fma_f32 v[154:155], v[96:97], v[102:103], v[154:155] op_sel:[0,1,0]
	s_waitcnt lgkmcnt(3)
	v_pk_mul_f32 v[220:221], v[16:17], v[176:177] op_sel_hi:[1,0]
	v_pk_mul_f32 v[222:223], v[14:15], v[176:177] op_sel_hi:[1,0]
	s_waitcnt vmcnt(23)
	v_pk_fma_f32 v[220:221], v[144:145], v[40:41], v[220:221] op_sel_hi:[0,1,1]
	v_pk_fma_f32 v[222:223], v[144:145], v[38:39], v[222:223] op_sel_hi:[0,1,1]
	v_pk_fma_f32 v[220:221], v[12:13], v[176:177], v[220:221] op_sel:[0,1,0]
	v_pk_fma_f32 v[176:177], v[10:11], v[176:177], v[222:223] op_sel:[0,1,0]
	v_pk_fma_f32 v[220:221], v[8:9], v[178:179], v[220:221] op_sel_hi:[1,0,1]
	v_pk_fma_f32 v[176:177], v[6:7], v[178:179], v[176:177] op_sel_hi:[1,0,1]
	v_mov_b32_e32 v178, v179
	v_pk_fma_f32 v[220:221], v[4:5], v[178:179], v[220:221] op_sel_hi:[1,0,1]
	v_pk_fma_f32 v[176:177], v[2:3], v[178:179], v[176:177] op_sel_hi:[1,0,1]
	v_pk_fma_f32 v[102:103], v[94:95], v[102:103], v[156:157] op_sel:[0,1,0]
	v_pk_fma_f32 v[156:157], v[96:97], v[104:105], v[158:159] op_sel_hi:[1,0,1]
	v_pk_fma_f32 v[158:159], v[94:95], v[104:105], v[160:161] op_sel_hi:[1,0,1]
	v_mov_b32_e32 v104, v105
	s_waitcnt lgkmcnt(0)
; #define LAS __attribute__((address_space(3)))
; __device__ void sample_ret_unit(const Params& p, int l, int unit, LAS unsigned char* lds, const int tid_in) {
;     ...
; #pragma unroll
;         for (int u = 0; u < 8; ++u) {
;             const f32x4 q0 = *(const LAS f32x4*)(sqT + (d0 + u) * 8), q1 = *(const LAS f32x4*)(sqT + (d0 + u) * 8 + 4);
;             const f32x4 k0 = *(const LAS f32x4*)(skdT + (d0 + u) * 8), k1 = *(const LAS f32x4*)(skdT + (d0 + u) * 8 + 4);
;             f32x4 sn = S4[u] * g8;
;             sn += vv[0] * k0[0]; sn += vv[1] * k0[1]; sn += vv[2] * k0[2]; sn += vv[3] * k0[3];
;             sn += vv[4] * k1[0]; sn += vv[5] * k1[1]; sn += vv[6] * k1[2]; sn += vv[7] * k1[3];
;             __builtin_nontemporal_store(sn, (f32x4*)(Sout + (size_t)(d0 + u) * 256 + e4));
;             oacc[0] += S4[u] * q0[0]; oacc[1] += S4[u] * q0[1]; oacc[2] += S4[u] * q0[2]; oacc[3] += S4[u] * q0[3];
;             oacc[4] += S4[u] * q1[0]; oacc[5] += S4[u] * q1[1]; oacc[6] += S4[u] * q1[2]; oacc[7] += S4[u] * q1[3];
;         }
	v_pk_fma_f32 v[178:179], v[32:33], v[214:215], v[220:221] op_sel_hi:[1,0,1]
	v_pk_fma_f32 v[176:177], v[30:31], v[214:215], v[176:177] op_sel_hi:[1,0,1]
	v_pk_fma_f32 v[160:161], v[96:97], v[104:105], v[162:163] op_sel_hi:[1,0,1]
	v_pk_fma_f32 v[104:105], v[94:95], v[104:105], v[164:165] op_sel_hi:[1,0,1]
	v_pk_fma_f32 v[162:163], v[96:97], v[34:35], v[166:167] op_sel_hi:[1,0,1]
	v_pk_fma_f32 v[164:165], v[94:95], v[34:35], v[168:169] op_sel_hi:[1,0,1]
	v_pk_fma_f32 v[166:167], v[96:97], v[34:35], v[170:171] op_sel:[0,1,0]
	v_pk_fma_f32 v[34:35], v[94:95], v[34:35], v[172:173] op_sel:[0,1,0]
	v_pk_fma_f32 v[96:97], v[96:97], v[36:37], v[174:175] op_sel_hi:[1,0,1]
	v_pk_fma_f32 v[36:37], v[94:95], v[36:37], v[148:149] op_sel_hi:[1,0,1]
	v_pk_fma_f32 v[94:95], v[88:89], v[110:111], v[150:151] op_sel_hi:[1,0,1]
	v_pk_fma_f32 v[148:149], v[86:87], v[110:111], v[152:153] op_sel_hi:[1,0,1]
	v_pk_fma_f32 v[150:151], v[88:89], v[110:111], v[154:155] op_sel:[0,1,0]
	v_pk_fma_f32 v[102:103], v[86:87], v[110:111], v[102:103] op_sel:[0,1,0]
	v_pk_fma_f32 v[110:111], v[88:89], v[112:113], v[156:157] op_sel_hi:[1,0,1]
	v_pk_fma_f32 v[152:153], v[86:87], v[112:113], v[158:159] op_sel_hi:[1,0,1]
	v_mov_b32_e32 v112, v113
	v_pk_fma_f32 v[178:179], v[28:29], v[214:215], v[178:179] op_sel:[0,1,0]
	v_pk_fma_f32 v[176:177], v[26:27], v[214:215], v[176:177] op_sel:[0,1,0]
	v_pk_fma_f32 v[154:155], v[88:89], v[112:113], v[160:161] op_sel_hi:[1,0,1]
	v_pk_fma_f32 v[104:105], v[86:87], v[112:113], v[104:105] op_sel_hi:[1,0,1]
	v_pk_fma_f32 v[112:113], v[88:89], v[106:107], v[162:163] op_sel_hi:[1,0,1]
	v_pk_fma_f32 v[156:157], v[86:87], v[106:107], v[164:165] op_sel_hi:[1,0,1]
	v_pk_fma_f32 v[158:159], v[88:89], v[106:107], v[166:167] op_sel:[0,1,0]
	v_pk_fma_f32 v[34:35], v[86:87], v[106:107], v[34:35] op_sel:[0,1,0]
	v_pk_fma_f32 v[88:89], v[88:89], v[108:109], v[96:97] op_sel_hi:[1,0,1]
	v_pk_fma_f32 v[36:37], v[86:87], v[108:109], v[36:37] op_sel_hi:[1,0,1]
	v_pk_fma_f32 v[86:87], v[80:81], v[118:119], v[94:95] op_sel_hi:[1,0,1]
	v_pk_fma_f32 v[96:97], v[80:81], v[118:119], v[150:151] op_sel:[0,1,0]
	v_pk_fma_f32 v[106:107], v[80:81], v[120:121], v[110:111] op_sel_hi:[1,0,1]
	v_mov_b32_e32 v110, v121
	v_pk_fma_f32 v[178:179], v[24:25], v[216:217], v[178:179] op_sel_hi:[1,0,1]
	v_pk_fma_f32 v[176:177], v[22:23], v[216:217], v[176:177] op_sel_hi:[1,0,1]
	v_mov_b32_e32 v214, v217
	v_ashrrev_i32_e32 v219, 31, v218
	v_pk_fma_f32 v[94:95], v[78:79], v[118:119], v[148:149] op_sel_hi:[1,0,1]
	v_pk_fma_f32 v[102:103], v[78:79], v[118:119], v[102:103] op_sel:[0,1,0]
	v_pk_fma_f32 v[108:109], v[78:79], v[120:121], v[152:153] op_sel_hi:[1,0,1]
	v_pk_fma_f32 v[118:119], v[80:81], v[110:111], v[154:155] op_sel_hi:[1,0,1]
	v_pk_fma_f32 v[104:105], v[78:79], v[110:111], v[104:105] op_sel_hi:[1,0,1]
	v_pk_fma_f32 v[110:111], v[80:81], v[114:115], v[112:113] op_sel_hi:[1,0,1]
	v_pk_fma_f32 v[112:113], v[78:79], v[114:115], v[156:157] op_sel_hi:[1,0,1]
	v_pk_fma_f32 v[120:121], v[80:81], v[114:115], v[158:159] op_sel:[0,1,0]
	v_pk_fma_f32 v[34:35], v[78:79], v[114:115], v[34:35] op_sel:[0,1,0]
	v_pk_fma_f32 v[80:81], v[80:81], v[116:117], v[88:89] op_sel_hi:[1,0,1]
	v_pk_fma_f32 v[36:37], v[78:79], v[116:117], v[36:37] op_sel_hi:[1,0,1]
	v_pk_fma_f32 v[78:79], v[76:77], v[126:127], v[86:87] op_sel_hi:[1,0,1]
	v_pk_fma_f32 v[88:89], v[76:77], v[126:127], v[96:97] op_sel:[0,1,0]
	v_pk_fma_f32 v[96:97], v[76:77], v[128:129], v[106:107] op_sel_hi:[1,0,1]
	v_mov_b32_e32 v106, v129
	v_pk_fma_f32 v[178:179], v[20:21], v[214:215], v[178:179] op_sel_hi:[1,0,1]
	v_pk_fma_f32 v[176:177], v[18:19], v[214:215], v[176:177] op_sel_hi:[1,0,1]
	v_lshlrev_b64 v[214:215], 10, v[218:219]
	v_pk_fma_f32 v[86:87], v[74:75], v[126:127], v[94:95] op_sel_hi:[1,0,1]
	v_pk_fma_f32 v[94:95], v[74:75], v[126:127], v[102:103] op_sel:[0,1,0]
	v_pk_fma_f32 v[102:103], v[74:75], v[128:129], v[108:109] op_sel_hi:[1,0,1]
	v_pk_fma_f32 v[108:109], v[76:77], v[106:107], v[118:119] op_sel_hi:[1,0,1]
	v_pk_fma_f32 v[104:105], v[74:75], v[106:107], v[104:105] op_sel_hi:[1,0,1]
	v_pk_fma_f32 v[106:107], v[76:77], v[122:123], v[110:111] op_sel_hi:[1,0,1]
	v_pk_fma_f32 v[110:111], v[74:75], v[122:123], v[112:113] op_sel_hi:[1,0,1]
	v_pk_fma_f32 v[112:113], v[76:77], v[122:123], v[120:121] op_sel:[0,1,0]
	v_pk_fma_f32 v[34:35], v[74:75], v[122:123], v[34:35] op_sel:[0,1,0]
	v_pk_fma_f32 v[76:77], v[76:77], v[124:125], v[80:81] op_sel_hi:[1,0,1]
	v_pk_fma_f32 v[36:37], v[74:75], v[124:125], v[36:37] op_sel_hi:[1,0,1]
	v_pk_fma_f32 v[74:75], v[64:65], v[134:135], v[78:79] op_sel_hi:[1,0,1]
	v_pk_fma_f32 v[80:81], v[64:65], v[134:135], v[88:89] op_sel:[0,1,0]
	v_pk_fma_f32 v[88:89], v[64:65], v[136:137], v[96:97] op_sel_hi:[1,0,1]
	v_mov_b32_e32 v96, v137
	v_lshl_add_u64 v[214:215], v[146:147], 0, v[214:215]
	v_pk_fma_f32 v[78:79], v[62:63], v[134:135], v[86:87] op_sel_hi:[1,0,1]
	v_pk_fma_f32 v[86:87], v[62:63], v[134:135], v[94:95] op_sel:[0,1,0]
	v_pk_fma_f32 v[94:95], v[62:63], v[136:137], v[102:103] op_sel_hi:[1,0,1]
	v_pk_fma_f32 v[102:103], v[64:65], v[96:97], v[108:109] op_sel_hi:[1,0,1]
	v_pk_fma_f32 v[96:97], v[62:63], v[96:97], v[104:105] op_sel_hi:[1,0,1]
	v_pk_fma_f32 v[104:105], v[64:65], v[130:131], v[106:107] op_sel_hi:[1,0,1]
	v_pk_fma_f32 v[106:107], v[62:63], v[130:131], v[110:111] op_sel_hi:[1,0,1]
	v_pk_fma_f32 v[108:109], v[64:65], v[130:131], v[112:113] op_sel:[0,1,0]
	v_pk_fma_f32 v[34:35], v[62:63], v[130:131], v[34:35] op_sel:[0,1,0]
	v_pk_fma_f32 v[64:65], v[64:65], v[132:133], v[76:77] op_sel_hi:[1,0,1]
	v_pk_fma_f32 v[36:37], v[62:63], v[132:133], v[36:37] op_sel_hi:[1,0,1]
; #define LAS __attribute__((address_space(3)))
; __device__ void sample_ret_unit(const Params& p, int l, int unit, LAS unsigned char* lds, const int tid_in) {
;     ...
; #pragma unroll
;         for (int u = 0; u < 8; ++u) {
;             const f32x4 q0 = *(const LAS f32x4*)(sqT + (d0 + u) * 8), q1 = *(const LAS f32x4*)(sqT + (d0 + u) * 8 + 4);
;             const f32x4 k0 = *(const LAS f32x4*)(skdT + (d0 + u) * 8), k1 = *(const LAS f32x4*)(skdT + (d0 + u) * 8 + 4);
;             f32x4 sn = S4[u] * g8;
;             sn += vv[0] * k0[0]; sn += vv[1] * k0[1]; sn += vv[2] * k0[2]; sn += vv[3] * k0[3];
;             sn += vv[4] * k1[0]; sn += vv[5] * k1[1]; sn += vv[6] * k1[2]; sn += vv[7] * k1[3];
;             __builtin_nontemporal_store(sn, (f32x4*)(Sout + (size_t)(d0 + u) * 256 + e4));
;             oacc[0] += S4[u] * q0[0]; oacc[1] += S4[u] * q0[1]; oacc[2] += S4[u] * q0[2]; oacc[3] += S4[u] * q0[3];
;             oacc[4] += S4[u] * q1[0]; oacc[5] += S4[u] * q1[1]; oacc[6] += S4[u] * q1[2]; oacc[7] += S4[u] * q1[3];
;         }
	v_pk_fma_f32 v[62:63], v[56:57], v[186:187], v[74:75] op_sel_hi:[1,0,1]
	v_pk_fma_f32 v[76:77], v[56:57], v[186:187], v[80:81] op_sel:[0,1,0]
	v_pk_fma_f32 v[80:81], v[56:57], v[188:189], v[88:89] op_sel_hi:[1,0,1]
	v_mov_b32_e32 v88, v189
	global_store_dwordx4 v[214:215], v[176:179], off nt
	v_pk_fma_f32 v[74:75], v[54:55], v[186:187], v[78:79] op_sel_hi:[1,0,1]
	v_pk_fma_f32 v[78:79], v[54:55], v[186:187], v[86:87] op_sel:[0,1,0]
	v_pk_fma_f32 v[86:87], v[54:55], v[188:189], v[94:95] op_sel_hi:[1,0,1]
	v_pk_fma_f32 v[94:95], v[56:57], v[88:89], v[102:103] op_sel_hi:[1,0,1]
	v_pk_fma_f32 v[88:89], v[54:55], v[88:89], v[96:97] op_sel_hi:[1,0,1]
	v_pk_fma_f32 v[96:97], v[56:57], v[198:199], v[104:105] op_sel_hi:[1,0,1]
	v_pk_fma_f32 v[102:103], v[54:55], v[198:199], v[106:107] op_sel_hi:[1,0,1]
	v_pk_fma_f32 v[104:105], v[56:57], v[198:199], v[108:109] op_sel:[0,1,0]
	v_pk_fma_f32 v[34:35], v[54:55], v[198:199], v[34:35] op_sel:[0,1,0]
	v_pk_fma_f32 v[56:57], v[56:57], v[200:201], v[64:65] op_sel_hi:[1,0,1]
	v_pk_fma_f32 v[36:37], v[54:55], v[200:201], v[36:37] op_sel_hi:[1,0,1]
	v_pk_fma_f32 v[54:55], v[48:49], v[202:203], v[62:63] op_sel_hi:[1,0,1]
	v_pk_fma_f32 v[64:65], v[48:49], v[202:203], v[76:77] op_sel:[0,1,0]
	v_pk_fma_f32 v[76:77], v[48:49], v[204:205], v[80:81] op_sel_hi:[1,0,1]
	v_mov_b32_e32 v80, v205
	v_or_b32_e32 v134, 24, v142
	v_pk_fma_f32 v[62:63], v[46:47], v[202:203], v[74:75] op_sel_hi:[1,0,1]
	v_pk_fma_f32 v[74:75], v[46:47], v[202:203], v[78:79] op_sel:[0,1,0]
	v_pk_fma_f32 v[78:79], v[46:47], v[204:205], v[86:87] op_sel_hi:[1,0,1]
	v_pk_fma_f32 v[86:87], v[48:49], v[80:81], v[94:95] op_sel_hi:[1,0,1]
	v_pk_fma_f32 v[80:81], v[46:47], v[80:81], v[88:89] op_sel_hi:[1,0,1]
	v_pk_fma_f32 v[88:89], v[48:49], v[206:207], v[96:97] op_sel_hi:[1,0,1]
	v_pk_fma_f32 v[94:95], v[46:47], v[206:207], v[102:103] op_sel_hi:[1,0,1]
	v_pk_fma_f32 v[96:97], v[48:49], v[206:207], v[104:105] op_sel:[0,1,0]
	v_pk_fma_f32 v[34:35], v[46:47], v[206:207], v[34:35] op_sel:[0,1,0]
	v_pk_fma_f32 v[48:49], v[48:49], v[208:209], v[56:57] op_sel_hi:[1,0,1]
	v_pk_fma_f32 v[36:37], v[46:47], v[208:209], v[36:37] op_sel_hi:[1,0,1]
	v_pk_fma_f32 v[106:107], v[40:41], v[182:183], v[54:55] op_sel_hi:[1,0,1]
	v_mov_b32_e32 v46, v185
	v_pk_fma_f32 v[118:119], v[40:41], v[46:47], v[86:87] op_sel_hi:[1,0,1]
	v_lshl_add_u32 v54, v134, 5, 0
	v_pk_fma_f32 v[120:121], v[38:39], v[46:47], v[80:81] op_sel_hi:[1,0,1]
	v_pk_fma_f32 v[130:131], v[40:41], v[212:213], v[48:49] op_sel_hi:[1,0,1]
	ds_read_b128 v[46:49], v54 offset:32768
	v_mov_b32_e32 v176, v213
	v_pk_fma_f32 v[178:179], v[40:41], v[176:177], v[194:195] op_sel_hi:[1,0,1]
	v_pk_fma_f32 v[176:177], v[38:39], v[176:177], v[192:193] op_sel_hi:[1,0,1]
	v_pk_fma_f32 v[108:109], v[38:39], v[182:183], v[62:63] op_sel_hi:[1,0,1]
	v_pk_fma_f32 v[110:111], v[40:41], v[182:183], v[64:65] op_sel:[0,1,0]
	v_pk_fma_f32 v[112:113], v[38:39], v[182:183], v[74:75] op_sel:[0,1,0]
	v_pk_fma_f32 v[114:115], v[40:41], v[184:185], v[76:77] op_sel_hi:[1,0,1]
	v_pk_fma_f32 v[116:117], v[38:39], v[184:185], v[78:79] op_sel_hi:[1,0,1]
	v_pk_fma_f32 v[122:123], v[40:41], v[210:211], v[88:89] op_sel_hi:[1,0,1]
	v_pk_fma_f32 v[124:125], v[38:39], v[210:211], v[94:95] op_sel_hi:[1,0,1]
	v_pk_fma_f32 v[126:127], v[40:41], v[210:211], v[96:97] op_sel:[0,1,0]
	v_pk_fma_f32 v[128:129], v[38:39], v[210:211], v[34:35] op_sel:[0,1,0]
	v_pk_fma_f32 v[132:133], v[38:39], v[212:213], v[36:37] op_sel_hi:[1,0,1]
	ds_read_b128 v[38:41], v54 offset:24576
	ds_read_b128 v[34:37], v54 offset:24592
	ds_read_b128 v[54:57], v54 offset:32784
	s_waitcnt lgkmcnt(3)
	v_pk_mul_f32 v[62:63], v[16:17], v[46:47] op_sel_hi:[1,0]
	v_pk_mul_f32 v[64:65], v[14:15], v[46:47] op_sel_hi:[1,0]
	s_waitcnt vmcnt(13)
	v_pk_fma_f32 v[62:63], v[144:145], v[100:101], v[62:63] op_sel_hi:[0,1,1]
	v_pk_fma_f32 v[64:65], v[144:145], v[98:99], v[64:65] op_sel_hi:[0,1,1]
	v_pk_fma_f32 v[62:63], v[12:13], v[46:47], v[62:63] op_sel:[0,1,0]
	v_pk_fma_f32 v[46:47], v[10:11], v[46:47], v[64:65] op_sel:[0,1,0]
	v_pk_fma_f32 v[62:63], v[8:9], v[48:49], v[62:63] op_sel_hi:[1,0,1]
	v_pk_fma_f32 v[46:47], v[6:7], v[48:49], v[46:47] op_sel_hi:[1,0,1]
	v_mov_b32_e32 v48, v49
	v_pk_fma_f32 v[62:63], v[4:5], v[48:49], v[62:63] op_sel_hi:[1,0,1]
	v_pk_fma_f32 v[46:47], v[2:3], v[48:49], v[46:47] op_sel_hi:[1,0,1]
	s_waitcnt lgkmcnt(0)
	v_pk_fma_f32 v[48:49], v[32:33], v[54:55], v[62:63] op_sel_hi:[1,0,1]
	v_pk_fma_f32 v[46:47], v[30:31], v[54:55], v[46:47] op_sel_hi:[1,0,1]
	v_pk_fma_f32 v[48:49], v[28:29], v[54:55], v[48:49] op_sel:[0,1,0]
	v_pk_fma_f32 v[46:47], v[26:27], v[54:55], v[46:47] op_sel:[0,1,0]
	v_pk_fma_f32 v[48:49], v[24:25], v[56:57], v[48:49] op_sel_hi:[1,0,1]
	v_pk_fma_f32 v[46:47], v[22:23], v[56:57], v[46:47] op_sel_hi:[1,0,1]
	v_mov_b32_e32 v54, v57
	v_ashrrev_i32_e32 v135, 31, v134
	v_pk_fma_f32 v[48:49], v[20:21], v[54:55], v[48:49] op_sel_hi:[1,0,1]
	v_pk_fma_f32 v[46:47], v[18:19], v[54:55], v[46:47] op_sel_hi:[1,0,1]
	v_lshlrev_b64 v[54:55], 10, v[134:135]
	v_lshl_add_u64 v[54:55], v[146:147], 0, v[54:55]
	v_add_u32_e32 v80, 1, v134
	global_store_dwordx4 v[54:55], v[46:49], off nt
	v_ashrrev_i32_e32 v81, 31, v80
	v_add_u32_e32 v96, 2, v134
	v_mov_b32_e32 v46, v37
	v_lshl_add_u32 v37, v80, 5, 0
	ds_read_b128 v[62:65], v37 offset:32768
	v_pk_fma_f32 v[78:79], v[100:101], v[46:47], v[178:179] op_sel_hi:[1,0,1]
	v_pk_fma_f32 v[86:87], v[98:99], v[46:47], v[176:177] op_sel_hi:[1,0,1]
	ds_read_b128 v[54:57], v37 offset:24576
	ds_read_b128 v[46:49], v37 offset:24592
	ds_read_b128 v[74:77], v37 offset:32784
	v_lshl_add_u32 v37, v96, 5, 0
	s_waitcnt lgkmcnt(3)
; #define LAS __attribute__((address_space(3)))
; __device__ void sample_ret_unit(const Params& p, int l, int unit, LAS unsigned char* lds, const int tid_in) {
;     ...
; #pragma unroll
;         for (int u = 0; u < 8; ++u) {
;             const f32x4 q0 = *(const LAS f32x4*)(sqT + (d0 + u) * 8), q1 = *(const LAS f32x4*)(sqT + (d0 + u) * 8 + 4);
;             const f32x4 k0 = *(const LAS f32x4*)(skdT + (d0 + u) * 8), k1 = *(const LAS f32x4*)(skdT + (d0 + u) * 8 + 4);
;             f32x4 sn = S4[u] * g8;
;             sn += vv[0] * k0[0]; sn += vv[1] * k0[1]; sn += vv[2] * k0[2]; sn += vv[3] * k0[3];
;             sn += vv[4] * k1[0]; sn += vv[5] * k1[1]; sn += vv[6] * k1[2]; sn += vv[7] * k1[3];
;             __builtin_nontemporal_store(sn, (f32x4*)(Sout + (size_t)(d0 + u) * 256 + e4));
;             oacc[0] += S4[u] * q0[0]; oacc[1] += S4[u] * q0[1]; oacc[2] += S4[u] * q0[2]; oacc[3] += S4[u] * q0[3];
;             oacc[4] += S4[u] * q1[0]; oacc[5] += S4[u] * q1[1]; oacc[6] += S4[u] * q1[2]; oacc[7] += S4[u] * q1[3];
;         }
	v_pk_mul_f32 v[88:89], v[16:17], v[62:63] op_sel_hi:[1,0]
	v_pk_mul_f32 v[94:95], v[14:15], v[62:63] op_sel_hi:[1,0]
	v_pk_fma_f32 v[88:89], v[144:145], v[92:93], v[88:89] op_sel_hi:[0,1,1]
	v_pk_fma_f32 v[94:95], v[144:145], v[90:91], v[94:95] op_sel_hi:[0,1,1]
	v_pk_fma_f32 v[88:89], v[12:13], v[62:63], v[88:89] op_sel:[0,1,0]
	v_pk_fma_f32 v[62:63], v[10:11], v[62:63], v[94:95] op_sel:[0,1,0]
	v_pk_fma_f32 v[88:89], v[8:9], v[64:65], v[88:89] op_sel_hi:[1,0,1]
	v_pk_fma_f32 v[62:63], v[6:7], v[64:65], v[62:63] op_sel_hi:[1,0,1]
	v_mov_b32_e32 v64, v65
	v_pk_fma_f32 v[88:89], v[4:5], v[64:65], v[88:89] op_sel_hi:[1,0,1]
	v_pk_fma_f32 v[62:63], v[2:3], v[64:65], v[62:63] op_sel_hi:[1,0,1]
	s_waitcnt lgkmcnt(0)
	v_pk_fma_f32 v[64:65], v[32:33], v[74:75], v[88:89] op_sel_hi:[1,0,1]
	v_pk_fma_f32 v[62:63], v[30:31], v[74:75], v[62:63] op_sel_hi:[1,0,1]
	v_pk_fma_f32 v[64:65], v[28:29], v[74:75], v[64:65] op_sel:[0,1,0]
	v_pk_fma_f32 v[62:63], v[26:27], v[74:75], v[62:63] op_sel:[0,1,0]
	v_pk_fma_f32 v[64:65], v[24:25], v[76:77], v[64:65] op_sel_hi:[1,0,1]
	v_pk_fma_f32 v[62:63], v[22:23], v[76:77], v[62:63] op_sel_hi:[1,0,1]
	v_mov_b32_e32 v74, v77
	v_pk_fma_f32 v[64:65], v[20:21], v[74:75], v[64:65] op_sel_hi:[1,0,1]
	v_pk_fma_f32 v[62:63], v[18:19], v[74:75], v[62:63] op_sel_hi:[1,0,1]
	v_lshlrev_b64 v[74:75], 10, v[80:81]
	v_lshl_add_u64 v[74:75], v[146:147], 0, v[74:75]
	global_store_dwordx4 v[74:75], v[62:65], off nt
	v_ashrrev_i32_e32 v97, 31, v96
	v_add_u32_e32 v148, 3, v134
	v_mov_b32_e32 v62, v49
	v_pk_fma_f32 v[94:95], v[92:93], v[62:63], v[78:79] op_sel_hi:[1,0,1]
	ds_read_b128 v[78:81], v37 offset:32768
	v_pk_fma_f32 v[102:103], v[90:91], v[62:63], v[86:87] op_sel_hi:[1,0,1]
	ds_read_b128 v[74:77], v37 offset:24576
	ds_read_b128 v[62:65], v37 offset:24592
	ds_read_b128 v[86:89], v37 offset:32784
	v_lshl_add_u32 v37, v148, 5, 0
	v_add_u32_e32 v156, 4, v134
	s_waitcnt lgkmcnt(3)
	v_pk_mul_f32 v[104:105], v[16:17], v[78:79] op_sel_hi:[1,0]
	v_pk_mul_f32 v[136:137], v[14:15], v[78:79] op_sel_hi:[1,0]
	v_pk_fma_f32 v[104:105], v[144:145], v[84:85], v[104:105] op_sel_hi:[0,1,1]
	v_pk_fma_f32 v[136:137], v[144:145], v[82:83], v[136:137] op_sel_hi:[0,1,1]
	v_pk_fma_f32 v[104:105], v[12:13], v[78:79], v[104:105] op_sel:[0,1,0]
	v_pk_fma_f32 v[78:79], v[10:11], v[78:79], v[136:137] op_sel:[0,1,0]
	v_pk_fma_f32 v[104:105], v[8:9], v[80:81], v[104:105] op_sel_hi:[1,0,1]
	v_pk_fma_f32 v[78:79], v[6:7], v[80:81], v[78:79] op_sel_hi:[1,0,1]
	v_mov_b32_e32 v80, v81
	v_pk_fma_f32 v[104:105], v[4:5], v[80:81], v[104:105] op_sel_hi:[1,0,1]
	v_pk_fma_f32 v[78:79], v[2:3], v[80:81], v[78:79] op_sel_hi:[1,0,1]
	s_waitcnt lgkmcnt(0)
	v_pk_fma_f32 v[80:81], v[32:33], v[86:87], v[104:105] op_sel_hi:[1,0,1]
	v_pk_fma_f32 v[78:79], v[30:31], v[86:87], v[78:79] op_sel_hi:[1,0,1]
	v_pk_fma_f32 v[80:81], v[28:29], v[86:87], v[80:81] op_sel:[0,1,0]
	v_pk_fma_f32 v[78:79], v[26:27], v[86:87], v[78:79] op_sel:[0,1,0]
	v_pk_fma_f32 v[80:81], v[24:25], v[88:89], v[80:81] op_sel_hi:[1,0,1]
	v_pk_fma_f32 v[78:79], v[22:23], v[88:89], v[78:79] op_sel_hi:[1,0,1]
	v_mov_b32_e32 v86, v89
	v_pk_fma_f32 v[80:81], v[20:21], v[86:87], v[80:81] op_sel_hi:[1,0,1]
	v_pk_fma_f32 v[78:79], v[18:19], v[86:87], v[78:79] op_sel_hi:[1,0,1]
	v_lshlrev_b64 v[86:87], 10, v[96:97]
	v_lshl_add_u64 v[86:87], v[146:147], 0, v[86:87]
	global_store_dwordx4 v[86:87], v[78:81], off nt
	v_ashrrev_i32_e32 v149, 31, v148
	v_ashrrev_i32_e32 v157, 31, v156
	v_mov_b32_e32 v78, v65
	v_pk_fma_f32 v[136:137], v[84:85], v[78:79], v[94:95] op_sel_hi:[1,0,1]
	ds_read_b128 v[94:97], v37 offset:32768
	v_pk_fma_f32 v[152:153], v[82:83], v[78:79], v[102:103] op_sel_hi:[1,0,1]
	ds_read_b128 v[86:89], v37 offset:24576
	ds_read_b128 v[78:81], v37 offset:24592
	ds_read_b128 v[102:105], v37 offset:32784
	v_lshl_add_u32 v37, v156, 5, 0
	v_add_u32_e32 v164, 5, v134
	s_waitcnt lgkmcnt(3)
	v_pk_mul_f32 v[150:151], v[16:17], v[94:95] op_sel_hi:[1,0]
	v_pk_mul_f32 v[154:155], v[14:15], v[94:95] op_sel_hi:[1,0]
	s_waitcnt vmcnt(15)
	v_pk_fma_f32 v[150:151], v[144:145], v[72:73], v[150:151] op_sel_hi:[0,1,1]
	v_pk_fma_f32 v[154:155], v[144:145], v[70:71], v[154:155] op_sel_hi:[0,1,1]
	v_pk_fma_f32 v[150:151], v[12:13], v[94:95], v[150:151] op_sel:[0,1,0]
	v_pk_fma_f32 v[94:95], v[10:11], v[94:95], v[154:155] op_sel:[0,1,0]
	v_pk_fma_f32 v[150:151], v[8:9], v[96:97], v[150:151] op_sel_hi:[1,0,1]
	v_pk_fma_f32 v[94:95], v[6:7], v[96:97], v[94:95] op_sel_hi:[1,0,1]
	v_mov_b32_e32 v96, v97
	v_pk_fma_f32 v[150:151], v[4:5], v[96:97], v[150:151] op_sel_hi:[1,0,1]
	v_pk_fma_f32 v[94:95], v[2:3], v[96:97], v[94:95] op_sel_hi:[1,0,1]
	s_waitcnt lgkmcnt(0)
	v_pk_fma_f32 v[96:97], v[32:33], v[102:103], v[150:151] op_sel_hi:[1,0,1]
	v_pk_fma_f32 v[94:95], v[30:31], v[102:103], v[94:95] op_sel_hi:[1,0,1]
	v_pk_fma_f32 v[96:97], v[28:29], v[102:103], v[96:97] op_sel:[0,1,0]
	v_pk_fma_f32 v[94:95], v[26:27], v[102:103], v[94:95] op_sel:[0,1,0]
	v_pk_fma_f32 v[96:97], v[24:25], v[104:105], v[96:97] op_sel_hi:[1,0,1]
	v_pk_fma_f32 v[94:95], v[22:23], v[104:105], v[94:95] op_sel_hi:[1,0,1]
	v_mov_b32_e32 v102, v105
	v_pk_fma_f32 v[96:97], v[20:21], v[102:103], v[96:97] op_sel_hi:[1,0,1]
	v_pk_fma_f32 v[94:95], v[18:19], v[102:103], v[94:95] op_sel_hi:[1,0,1]
	v_lshlrev_b64 v[102:103], 10, v[148:149]
	ds_read_b128 v[148:151], v37 offset:32768
	v_lshl_add_u64 v[102:103], v[146:147], 0, v[102:103]
	global_store_dwordx4 v[102:103], v[94:97], off nt
	v_ashrrev_i32_e32 v165, 31, v164
	v_add_u32_e32 v172, 6, v134
	v_mov_b32_e32 v94, v81
	v_pk_fma_f32 v[136:137], v[72:73], v[94:95], v[136:137] op_sel_hi:[1,0,1]
	v_pk_fma_f32 v[158:159], v[70:71], v[94:95], v[152:153] op_sel_hi:[1,0,1]
	ds_read_b128 v[102:105], v37 offset:24576
	ds_read_b128 v[94:97], v37 offset:24592
	ds_read_b128 v[152:155], v37 offset:32784
	s_waitcnt lgkmcnt(3)
; #define LAS __attribute__((address_space(3)))
; __device__ void sample_ret_unit(const Params& p, int l, int unit, LAS unsigned char* lds, const int tid_in) {
;     ...
; #pragma unroll
;         for (int u = 0; u < 8; ++u) {
;             const f32x4 q0 = *(const LAS f32x4*)(sqT + (d0 + u) * 8), q1 = *(const LAS f32x4*)(sqT + (d0 + u) * 8 + 4);
;             const f32x4 k0 = *(const LAS f32x4*)(skdT + (d0 + u) * 8), k1 = *(const LAS f32x4*)(skdT + (d0 + u) * 8 + 4);
;             f32x4 sn = S4[u] * g8;
;             sn += vv[0] * k0[0]; sn += vv[1] * k0[1]; sn += vv[2] * k0[2]; sn += vv[3] * k0[3];
;             sn += vv[4] * k1[0]; sn += vv[5] * k1[1]; sn += vv[6] * k1[2]; sn += vv[7] * k1[3];
;             __builtin_nontemporal_store(sn, (f32x4*)(Sout + (size_t)(d0 + u) * 256 + e4));
;             oacc[0] += S4[u] * q0[0]; oacc[1] += S4[u] * q0[1]; oacc[2] += S4[u] * q0[2]; oacc[3] += S4[u] * q0[3];
;             oacc[4] += S4[u] * q1[0]; oacc[5] += S4[u] * q1[1]; oacc[6] += S4[u] * q1[2]; oacc[7] += S4[u] * q1[3];
;         }
	v_pk_mul_f32 v[160:161], v[16:17], v[148:149] op_sel_hi:[1,0]
	v_pk_mul_f32 v[162:163], v[14:15], v[148:149] op_sel_hi:[1,0]
	s_waitcnt vmcnt(15)
	v_pk_fma_f32 v[160:161], v[144:145], v[68:69], v[160:161] op_sel_hi:[0,1,1]
	v_pk_fma_f32 v[162:163], v[144:145], v[66:67], v[162:163] op_sel_hi:[0,1,1]
	v_pk_fma_f32 v[160:161], v[12:13], v[148:149], v[160:161] op_sel:[0,1,0]
	v_pk_fma_f32 v[148:149], v[10:11], v[148:149], v[162:163] op_sel:[0,1,0]
	v_pk_fma_f32 v[160:161], v[8:9], v[150:151], v[160:161] op_sel_hi:[1,0,1]
	v_pk_fma_f32 v[148:149], v[6:7], v[150:151], v[148:149] op_sel_hi:[1,0,1]
	v_mov_b32_e32 v150, v151
	v_pk_fma_f32 v[160:161], v[4:5], v[150:151], v[160:161] op_sel_hi:[1,0,1]
	v_pk_fma_f32 v[148:149], v[2:3], v[150:151], v[148:149] op_sel_hi:[1,0,1]
	s_waitcnt lgkmcnt(0)
	v_pk_fma_f32 v[150:151], v[32:33], v[152:153], v[160:161] op_sel_hi:[1,0,1]
	v_pk_fma_f32 v[148:149], v[30:31], v[152:153], v[148:149] op_sel_hi:[1,0,1]
	v_pk_fma_f32 v[150:151], v[28:29], v[152:153], v[150:151] op_sel:[0,1,0]
	v_pk_fma_f32 v[148:149], v[26:27], v[152:153], v[148:149] op_sel:[0,1,0]
	v_pk_fma_f32 v[150:151], v[24:25], v[154:155], v[150:151] op_sel_hi:[1,0,1]
	v_pk_fma_f32 v[148:149], v[22:23], v[154:155], v[148:149] op_sel_hi:[1,0,1]
	v_mov_b32_e32 v152, v155
	v_pk_fma_f32 v[150:151], v[20:21], v[152:153], v[150:151] op_sel_hi:[1,0,1]
	v_pk_fma_f32 v[148:149], v[18:19], v[152:153], v[148:149] op_sel_hi:[1,0,1]
	v_lshlrev_b64 v[152:153], 10, v[156:157]
	v_lshl_add_u64 v[152:153], v[146:147], 0, v[152:153]
	v_lshl_add_u32 v37, v164, 5, 0
	global_store_dwordx4 v[152:153], v[148:151], off nt
	ds_read_b128 v[148:151], v37 offset:32768
	v_mov_b32_e32 v152, v97
	v_pk_fma_f32 v[136:137], v[68:69], v[152:153], v[136:137] op_sel_hi:[1,0,1]
	v_pk_fma_f32 v[166:167], v[66:67], v[152:153], v[158:159] op_sel_hi:[1,0,1]
	ds_read_b128 v[152:155], v37 offset:24576
	ds_read_b128 v[156:159], v37 offset:24592
	ds_read_b128 v[160:163], v37 offset:32784
	s_waitcnt lgkmcnt(3)
	v_pk_mul_f32 v[168:169], v[16:17], v[148:149] op_sel_hi:[1,0]
	v_pk_mul_f32 v[170:171], v[14:15], v[148:149] op_sel_hi:[1,0]
	s_waitcnt vmcnt(15)
	v_pk_fma_f32 v[168:169], v[144:145], v[60:61], v[168:169] op_sel_hi:[0,1,1]
	v_pk_fma_f32 v[170:171], v[144:145], v[58:59], v[170:171] op_sel_hi:[0,1,1]
	v_pk_fma_f32 v[168:169], v[12:13], v[148:149], v[168:169] op_sel:[0,1,0]
	v_pk_fma_f32 v[148:149], v[10:11], v[148:149], v[170:171] op_sel:[0,1,0]
	v_pk_fma_f32 v[168:169], v[8:9], v[150:151], v[168:169] op_sel_hi:[1,0,1]
	v_pk_fma_f32 v[148:149], v[6:7], v[150:151], v[148:149] op_sel_hi:[1,0,1]
	v_mov_b32_e32 v150, v151
	v_pk_fma_f32 v[168:169], v[4:5], v[150:151], v[168:169] op_sel_hi:[1,0,1]
	v_pk_fma_f32 v[148:149], v[2:3], v[150:151], v[148:149] op_sel_hi:[1,0,1]
	s_waitcnt lgkmcnt(0)
	v_pk_fma_f32 v[150:151], v[32:33], v[160:161], v[168:169] op_sel_hi:[1,0,1]
	v_pk_fma_f32 v[148:149], v[30:31], v[160:161], v[148:149] op_sel_hi:[1,0,1]
	v_pk_fma_f32 v[150:151], v[28:29], v[160:161], v[150:151] op_sel:[0,1,0]
	v_pk_fma_f32 v[148:149], v[26:27], v[160:161], v[148:149] op_sel:[0,1,0]
	v_pk_fma_f32 v[150:151], v[24:25], v[162:163], v[150:151] op_sel_hi:[1,0,1]
	v_pk_fma_f32 v[148:149], v[22:23], v[162:163], v[148:149] op_sel_hi:[1,0,1]
	v_mov_b32_e32 v160, v163
	v_pk_fma_f32 v[150:151], v[20:21], v[160:161], v[150:151] op_sel_hi:[1,0,1]
	v_pk_fma_f32 v[148:149], v[18:19], v[160:161], v[148:149] op_sel_hi:[1,0,1]
	v_lshlrev_b64 v[160:161], 10, v[164:165]
	v_lshl_add_u64 v[160:161], v[146:147], 0, v[160:161]
	v_lshl_add_u32 v37, v172, 5, 0
	global_store_dwordx4 v[160:161], v[148:151], off nt
	ds_read_b128 v[148:151], v37 offset:32768
	v_mov_b32_e32 v160, v159
	v_pk_fma_f32 v[136:137], v[60:61], v[160:161], v[136:137] op_sel_hi:[1,0,1]
	v_pk_fma_f32 v[174:175], v[58:59], v[160:161], v[166:167] op_sel_hi:[1,0,1]
	ds_read_b128 v[160:163], v37 offset:24576
	ds_read_b128 v[164:167], v37 offset:24592
	ds_read_b128 v[168:171], v37 offset:32784
	s_waitcnt lgkmcnt(3)
	v_pk_mul_f32 v[176:177], v[16:17], v[148:149] op_sel_hi:[1,0]
	v_pk_mul_f32 v[178:179], v[14:15], v[148:149] op_sel_hi:[1,0]
	s_waitcnt vmcnt(15)
	v_pk_fma_f32 v[176:177], v[144:145], v[52:53], v[176:177] op_sel_hi:[0,1,1]
	v_pk_fma_f32 v[178:179], v[144:145], v[50:51], v[178:179] op_sel_hi:[0,1,1]
	v_pk_fma_f32 v[176:177], v[12:13], v[148:149], v[176:177] op_sel:[0,1,0]
	v_pk_fma_f32 v[148:149], v[10:11], v[148:149], v[178:179] op_sel:[0,1,0]
	v_pk_fma_f32 v[176:177], v[8:9], v[150:151], v[176:177] op_sel_hi:[1,0,1]
	v_pk_fma_f32 v[148:149], v[6:7], v[150:151], v[148:149] op_sel_hi:[1,0,1]
	v_mov_b32_e32 v150, v151
	v_pk_fma_f32 v[176:177], v[4:5], v[150:151], v[176:177] op_sel_hi:[1,0,1]
	v_pk_fma_f32 v[148:149], v[2:3], v[150:151], v[148:149] op_sel_hi:[1,0,1]
	s_waitcnt lgkmcnt(0)
	v_pk_fma_f32 v[150:151], v[32:33], v[168:169], v[176:177] op_sel_hi:[1,0,1]
	v_pk_fma_f32 v[148:149], v[30:31], v[168:169], v[148:149] op_sel_hi:[1,0,1]
	v_pk_fma_f32 v[150:151], v[28:29], v[168:169], v[150:151] op_sel:[0,1,0]
	v_pk_fma_f32 v[148:149], v[26:27], v[168:169], v[148:149] op_sel:[0,1,0]
	v_pk_fma_f32 v[150:151], v[24:25], v[170:171], v[150:151] op_sel_hi:[1,0,1]
	v_pk_fma_f32 v[148:149], v[22:23], v[170:171], v[148:149] op_sel_hi:[1,0,1]
	v_mov_b32_e32 v168, v171
	v_ashrrev_i32_e32 v173, 31, v172
	v_pk_fma_f32 v[150:151], v[20:21], v[168:169], v[150:151] op_sel_hi:[1,0,1]
	v_pk_fma_f32 v[148:149], v[18:19], v[168:169], v[148:149] op_sel_hi:[1,0,1]
	v_lshlrev_b64 v[168:169], 10, v[172:173]
	v_lshl_add_u64 v[168:169], v[146:147], 0, v[168:169]
	v_add_u32_e32 v178, 7, v134
	global_store_dwordx4 v[168:169], v[148:151], off nt
	v_lshl_add_u32 v37, v178, 5, 0
	v_ashrrev_i32_e32 v179, 31, v178
	v_mov_b32_e32 v148, v167
	v_pk_fma_f32 v[176:177], v[52:53], v[148:149], v[136:137] op_sel_hi:[1,0,1]
	ds_read_b128 v[134:137], v37 offset:32768
	v_pk_fma_f32 v[182:183], v[50:51], v[148:149], v[174:175] op_sel_hi:[1,0,1]
	ds_read_b128 v[148:151], v37 offset:24576
	ds_read_b128 v[168:171], v37 offset:24592
	ds_read_b128 v[172:175], v37 offset:32784
	s_waitcnt lgkmcnt(3)
; #define LAS __attribute__((address_space(3)))
; __device__ void sample_ret_unit(const Params& p, int l, int unit, LAS unsigned char* lds, const int tid_in) {
;     ...
; #pragma unroll
;         for (int u = 0; u < 8; ++u) {
;             const f32x4 q0 = *(const LAS f32x4*)(sqT + (d0 + u) * 8), q1 = *(const LAS f32x4*)(sqT + (d0 + u) * 8 + 4);
;             const f32x4 k0 = *(const LAS f32x4*)(skdT + (d0 + u) * 8), k1 = *(const LAS f32x4*)(skdT + (d0 + u) * 8 + 4);
;             f32x4 sn = S4[u] * g8;
;             sn += vv[0] * k0[0]; sn += vv[1] * k0[1]; sn += vv[2] * k0[2]; sn += vv[3] * k0[3];
;             sn += vv[4] * k1[0]; sn += vv[5] * k1[1]; sn += vv[6] * k1[2]; sn += vv[7] * k1[3];
;             __builtin_nontemporal_store(sn, (f32x4*)(Sout + (size_t)(d0 + u) * 256 + e4));
;             oacc[0] += S4[u] * q0[0]; oacc[1] += S4[u] * q0[1]; oacc[2] += S4[u] * q0[2]; oacc[3] += S4[u] * q0[3];
;             oacc[4] += S4[u] * q1[0]; oacc[5] += S4[u] * q1[1]; oacc[6] += S4[u] * q1[2]; oacc[7] += S4[u] * q1[3];
;         }
	v_pk_mul_f32 v[16:17], v[16:17], v[134:135] op_sel_hi:[1,0]
	v_pk_mul_f32 v[14:15], v[14:15], v[134:135] op_sel_hi:[1,0]
	s_waitcnt vmcnt(15)
	v_pk_fma_f32 v[16:17], v[144:145], v[44:45], v[16:17] op_sel_hi:[0,1,1]
	v_pk_fma_f32 v[14:15], v[144:145], v[42:43], v[14:15] op_sel_hi:[0,1,1]
	v_pk_fma_f32 v[12:13], v[12:13], v[134:135], v[16:17] op_sel:[0,1,0]
	v_pk_fma_f32 v[10:11], v[10:11], v[134:135], v[14:15] op_sel:[0,1,0]
	v_pk_fma_f32 v[8:9], v[8:9], v[136:137], v[12:13] op_sel_hi:[1,0,1]
	v_pk_fma_f32 v[6:7], v[6:7], v[136:137], v[10:11] op_sel_hi:[1,0,1]
	v_mov_b32_e32 v10, v137
	v_pk_fma_f32 v[4:5], v[4:5], v[10:11], v[8:9] op_sel_hi:[1,0,1]
	v_pk_fma_f32 v[2:3], v[2:3], v[10:11], v[6:7] op_sel_hi:[1,0,1]
	s_waitcnt lgkmcnt(0)
	v_pk_fma_f32 v[4:5], v[32:33], v[172:173], v[4:5] op_sel_hi:[1,0,1]
	v_pk_fma_f32 v[2:3], v[30:31], v[172:173], v[2:3] op_sel_hi:[1,0,1]
	v_pk_fma_f32 v[4:5], v[28:29], v[172:173], v[4:5] op_sel:[0,1,0]
	v_pk_fma_f32 v[2:3], v[26:27], v[172:173], v[2:3] op_sel:[0,1,0]
	v_pk_fma_f32 v[4:5], v[24:25], v[174:175], v[4:5] op_sel_hi:[1,0,1]
	v_pk_fma_f32 v[2:3], v[22:23], v[174:175], v[2:3] op_sel_hi:[1,0,1]
	v_mov_b32_e32 v6, v175
	v_pk_fma_f32 v[4:5], v[20:21], v[6:7], v[4:5] op_sel_hi:[1,0,1]
	v_pk_fma_f32 v[2:3], v[18:19], v[6:7], v[2:3] op_sel_hi:[1,0,1]
	v_lshlrev_b64 v[6:7], 10, v[178:179]
	v_lshl_add_u64 v[6:7], v[146:147], 0, v[6:7]
	global_store_dwordx4 v[6:7], v[2:5], off nt
	v_pk_fma_f32 v[6:7], v[100:101], v[38:39], v[106:107] op_sel_hi:[1,0,1]
	v_pk_fma_f32 v[8:9], v[98:99], v[38:39], v[108:109] op_sel_hi:[1,0,1]
	v_mov_b32_e32 v18, v41
	v_pk_fma_f32 v[20:21], v[100:101], v[18:19], v[118:119] op_sel_hi:[1,0,1]
	v_pk_fma_f32 v[18:19], v[98:99], v[18:19], v[120:121] op_sel_hi:[1,0,1]
	v_pk_fma_f32 v[22:23], v[100:101], v[34:35], v[122:123] op_sel_hi:[1,0,1]
	v_pk_fma_f32 v[24:25], v[98:99], v[34:35], v[124:125] op_sel_hi:[1,0,1]
	v_pk_fma_f32 v[26:27], v[100:101], v[34:35], v[126:127] op_sel:[0,1,0]
	v_pk_fma_f32 v[28:29], v[98:99], v[34:35], v[128:129] op_sel:[0,1,0]
	v_pk_fma_f32 v[6:7], v[92:93], v[54:55], v[6:7] op_sel_hi:[1,0,1]
	v_pk_fma_f32 v[8:9], v[90:91], v[54:55], v[8:9] op_sel_hi:[1,0,1]
	v_mov_b32_e32 v34, v57
	v_pk_fma_f32 v[10:11], v[100:101], v[38:39], v[110:111] op_sel:[0,1,0]
	v_pk_fma_f32 v[12:13], v[98:99], v[38:39], v[112:113] op_sel:[0,1,0]
	v_pk_fma_f32 v[14:15], v[100:101], v[40:41], v[114:115] op_sel_hi:[1,0,1]
	v_pk_fma_f32 v[16:17], v[98:99], v[40:41], v[116:117] op_sel_hi:[1,0,1]
	v_pk_fma_f32 v[30:31], v[100:101], v[36:37], v[130:131] op_sel_hi:[1,0,1]
	v_pk_fma_f32 v[32:33], v[98:99], v[36:37], v[132:133] op_sel_hi:[1,0,1]
	v_pk_fma_f32 v[20:21], v[92:93], v[34:35], v[20:21] op_sel_hi:[1,0,1]
	v_pk_fma_f32 v[18:19], v[90:91], v[34:35], v[18:19] op_sel_hi:[1,0,1]
	v_pk_fma_f32 v[6:7], v[84:85], v[74:75], v[6:7] op_sel_hi:[1,0,1]
	v_pk_fma_f32 v[8:9], v[82:83], v[74:75], v[8:9] op_sel_hi:[1,0,1]
	v_mov_b32_e32 v34, v77
	v_pk_fma_f32 v[10:11], v[92:93], v[54:55], v[10:11] op_sel:[0,1,0]
	v_pk_fma_f32 v[12:13], v[90:91], v[54:55], v[12:13] op_sel:[0,1,0]
	v_pk_fma_f32 v[14:15], v[92:93], v[56:57], v[14:15] op_sel_hi:[1,0,1]
	v_pk_fma_f32 v[16:17], v[90:91], v[56:57], v[16:17] op_sel_hi:[1,0,1]
	v_pk_fma_f32 v[22:23], v[92:93], v[46:47], v[22:23] op_sel_hi:[1,0,1]
	v_pk_fma_f32 v[24:25], v[90:91], v[46:47], v[24:25] op_sel_hi:[1,0,1]
	v_pk_fma_f32 v[26:27], v[92:93], v[46:47], v[26:27] op_sel:[0,1,0]
	v_pk_fma_f32 v[28:29], v[90:91], v[46:47], v[28:29] op_sel:[0,1,0]
	v_pk_fma_f32 v[30:31], v[92:93], v[48:49], v[30:31] op_sel_hi:[1,0,1]
	v_pk_fma_f32 v[32:33], v[90:91], v[48:49], v[32:33] op_sel_hi:[1,0,1]
	v_pk_fma_f32 v[20:21], v[84:85], v[34:35], v[20:21] op_sel_hi:[1,0,1]
	v_pk_fma_f32 v[18:19], v[82:83], v[34:35], v[18:19] op_sel_hi:[1,0,1]
	v_pk_fma_f32 v[6:7], v[72:73], v[86:87], v[6:7] op_sel_hi:[1,0,1]
	v_pk_fma_f32 v[8:9], v[70:71], v[86:87], v[8:9] op_sel_hi:[1,0,1]
	v_mov_b32_e32 v34, v89
	v_pk_fma_f32 v[10:11], v[84:85], v[74:75], v[10:11] op_sel:[0,1,0]
	v_pk_fma_f32 v[12:13], v[82:83], v[74:75], v[12:13] op_sel:[0,1,0]
	v_pk_fma_f32 v[14:15], v[84:85], v[76:77], v[14:15] op_sel_hi:[1,0,1]
	v_pk_fma_f32 v[16:17], v[82:83], v[76:77], v[16:17] op_sel_hi:[1,0,1]
	v_pk_fma_f32 v[22:23], v[84:85], v[62:63], v[22:23] op_sel_hi:[1,0,1]
	v_pk_fma_f32 v[24:25], v[82:83], v[62:63], v[24:25] op_sel_hi:[1,0,1]
	v_pk_fma_f32 v[26:27], v[84:85], v[62:63], v[26:27] op_sel:[0,1,0]
	v_pk_fma_f32 v[28:29], v[82:83], v[62:63], v[28:29] op_sel:[0,1,0]
	v_pk_fma_f32 v[30:31], v[84:85], v[64:65], v[30:31] op_sel_hi:[1,0,1]
	v_pk_fma_f32 v[32:33], v[82:83], v[64:65], v[32:33] op_sel_hi:[1,0,1]
	v_pk_fma_f32 v[20:21], v[72:73], v[34:35], v[20:21] op_sel_hi:[1,0,1]
	v_pk_fma_f32 v[18:19], v[70:71], v[34:35], v[18:19] op_sel_hi:[1,0,1]
	v_pk_fma_f32 v[6:7], v[68:69], v[102:103], v[6:7] op_sel_hi:[1,0,1]
	v_pk_fma_f32 v[8:9], v[66:67], v[102:103], v[8:9] op_sel_hi:[1,0,1]
	v_mov_b32_e32 v34, v105
	v_pk_fma_f32 v[10:11], v[72:73], v[86:87], v[10:11] op_sel:[0,1,0]
	v_pk_fma_f32 v[12:13], v[70:71], v[86:87], v[12:13] op_sel:[0,1,0]
	v_pk_fma_f32 v[14:15], v[72:73], v[88:89], v[14:15] op_sel_hi:[1,0,1]
	v_pk_fma_f32 v[16:17], v[70:71], v[88:89], v[16:17] op_sel_hi:[1,0,1]
	v_pk_fma_f32 v[22:23], v[72:73], v[78:79], v[22:23] op_sel_hi:[1,0,1]
	v_pk_fma_f32 v[24:25], v[70:71], v[78:79], v[24:25] op_sel_hi:[1,0,1]
	v_pk_fma_f32 v[26:27], v[72:73], v[78:79], v[26:27] op_sel:[0,1,0]
	v_pk_fma_f32 v[28:29], v[70:71], v[78:79], v[28:29] op_sel:[0,1,0]
	v_pk_fma_f32 v[30:31], v[72:73], v[80:81], v[30:31] op_sel_hi:[1,0,1]
	v_pk_fma_f32 v[32:33], v[70:71], v[80:81], v[32:33] op_sel_hi:[1,0,1]
; #define LAS __attribute__((address_space(3)))
; __device__ void sample_ret_unit(const Params& p, int l, int unit, LAS unsigned char* lds, const int tid_in) {
;     ...
;             oacc[0] += S4[u] * q0[0]; oacc[1] += S4[u] * q0[1]; oacc[2] += S4[u] * q0[2]; oacc[3] += S4[u] * q0[3];
;             oacc[4] += S4[u] * q1[0]; oacc[5] += S4[u] * q1[1]; oacc[6] += S4[u] * q1[2]; oacc[7] += S4[u] * q1[3];
;         }
;         asm volatile("" ::: "memory");
; #pragma unroll
;         for (int u = 0; u < 8; ++u) S4[u] = N4[u];
;     }
; #pragma unroll
;     for (int i = 0; i < 8; ++i) *(LAS f32x4*)(red + (wid * 8 + i) * 256 + e4) = oacc[i];
;     __syncthreads();
;     { const int i = wid;
;         f32x4 o = (f32x4){0.f, 0.f, 0.f, 0.f};
; #pragma unroll
;         for (int w = 0; w < 8; ++w) o += *(const LAS f32x4*)(red + (w * 8 + i) * 256 + e4);
;         o *= exp2f(lg * (float)(i + 1));
;         for (int j = 0; j <= i; ++j) o += *(const LAS f32x4*)(sv + j * 256 + e4) * sc[i * 8 + j];
	v_pk_fma_f32 v[20:21], v[68:69], v[34:35], v[20:21] op_sel_hi:[1,0,1]
	v_pk_fma_f32 v[18:19], v[66:67], v[34:35], v[18:19] op_sel_hi:[1,0,1]
	v_pk_fma_f32 v[6:7], v[60:61], v[152:153], v[6:7] op_sel_hi:[1,0,1]
	v_pk_fma_f32 v[8:9], v[58:59], v[152:153], v[8:9] op_sel_hi:[1,0,1]
	v_mov_b32_e32 v34, v155
	v_pk_fma_f32 v[10:11], v[68:69], v[102:103], v[10:11] op_sel:[0,1,0]
	v_pk_fma_f32 v[12:13], v[66:67], v[102:103], v[12:13] op_sel:[0,1,0]
	v_pk_fma_f32 v[14:15], v[68:69], v[104:105], v[14:15] op_sel_hi:[1,0,1]
	v_pk_fma_f32 v[16:17], v[66:67], v[104:105], v[16:17] op_sel_hi:[1,0,1]
	v_pk_fma_f32 v[22:23], v[68:69], v[94:95], v[22:23] op_sel_hi:[1,0,1]
	v_pk_fma_f32 v[24:25], v[66:67], v[94:95], v[24:25] op_sel_hi:[1,0,1]
	v_pk_fma_f32 v[26:27], v[68:69], v[94:95], v[26:27] op_sel:[0,1,0]
	v_pk_fma_f32 v[28:29], v[66:67], v[94:95], v[28:29] op_sel:[0,1,0]
	v_pk_fma_f32 v[30:31], v[68:69], v[96:97], v[30:31] op_sel_hi:[1,0,1]
	v_pk_fma_f32 v[32:33], v[66:67], v[96:97], v[32:33] op_sel_hi:[1,0,1]
	v_pk_fma_f32 v[20:21], v[60:61], v[34:35], v[20:21] op_sel_hi:[1,0,1]
	v_pk_fma_f32 v[18:19], v[58:59], v[34:35], v[18:19] op_sel_hi:[1,0,1]
	v_pk_fma_f32 v[6:7], v[52:53], v[160:161], v[6:7] op_sel_hi:[1,0,1]
	v_pk_fma_f32 v[34:35], v[50:51], v[160:161], v[8:9] op_sel_hi:[1,0,1]
	v_mov_b32_e32 v8, v163
	v_mov_b32_e32 v2, v171
	v_pk_fma_f32 v[10:11], v[60:61], v[152:153], v[10:11] op_sel:[0,1,0]
	v_pk_fma_f32 v[12:13], v[58:59], v[152:153], v[12:13] op_sel:[0,1,0]
	v_pk_fma_f32 v[14:15], v[60:61], v[154:155], v[14:15] op_sel_hi:[1,0,1]
	v_pk_fma_f32 v[16:17], v[58:59], v[154:155], v[16:17] op_sel_hi:[1,0,1]
	v_pk_fma_f32 v[22:23], v[60:61], v[156:157], v[22:23] op_sel_hi:[1,0,1]
	v_pk_fma_f32 v[24:25], v[58:59], v[156:157], v[24:25] op_sel_hi:[1,0,1]
	v_pk_fma_f32 v[26:27], v[60:61], v[156:157], v[26:27] op_sel:[0,1,0]
	v_pk_fma_f32 v[28:29], v[58:59], v[156:157], v[28:29] op_sel:[0,1,0]
	v_pk_fma_f32 v[30:31], v[60:61], v[158:159], v[30:31] op_sel_hi:[1,0,1]
	v_pk_fma_f32 v[32:33], v[58:59], v[158:159], v[32:33] op_sel_hi:[1,0,1]
	v_pk_fma_f32 v[20:21], v[52:53], v[8:9], v[20:21] op_sel_hi:[1,0,1]
	v_pk_fma_f32 v[18:19], v[50:51], v[8:9], v[18:19] op_sel_hi:[1,0,1]
	v_pk_fma_f32 v[8:9], v[44:45], v[148:149], v[6:7] op_sel_hi:[1,0,1]
	v_pk_fma_f32 v[6:7], v[42:43], v[148:149], v[34:35] op_sel_hi:[1,0,1]
	v_lshlrev_b32_e32 v34, 13, v138
	v_pk_fma_f32 v[4:5], v[44:45], v[2:3], v[176:177] op_sel_hi:[1,0,1]
	v_pk_fma_f32 v[2:3], v[42:43], v[2:3], v[182:183] op_sel_hi:[1,0,1]
	v_pk_fma_f32 v[10:11], v[52:53], v[160:161], v[10:11] op_sel:[0,1,0]
	v_pk_fma_f32 v[36:37], v[50:51], v[160:161], v[12:13] op_sel:[0,1,0]
	v_pk_fma_f32 v[14:15], v[52:53], v[162:163], v[14:15] op_sel_hi:[1,0,1]
	v_pk_fma_f32 v[38:39], v[50:51], v[162:163], v[16:17] op_sel_hi:[1,0,1]
	v_pk_fma_f32 v[22:23], v[52:53], v[164:165], v[22:23] op_sel_hi:[1,0,1]
	v_pk_fma_f32 v[40:41], v[50:51], v[164:165], v[24:25] op_sel_hi:[1,0,1]
	v_pk_fma_f32 v[26:27], v[52:53], v[164:165], v[26:27] op_sel:[0,1,0]
	v_pk_fma_f32 v[46:47], v[50:51], v[164:165], v[28:29] op_sel:[0,1,0]
	v_pk_fma_f32 v[30:31], v[52:53], v[166:167], v[30:31] op_sel_hi:[1,0,1]
	v_pk_fma_f32 v[48:49], v[50:51], v[166:167], v[32:33] op_sel_hi:[1,0,1]
	v_mov_b32_e32 v24, v151
	v_add3_u32 v34, 0, v34, v0
	v_pk_fma_f32 v[12:13], v[44:45], v[148:149], v[10:11] op_sel:[0,1,0]
	v_pk_fma_f32 v[10:11], v[42:43], v[148:149], v[36:37] op_sel:[0,1,0]
	v_pk_fma_f32 v[16:17], v[44:45], v[150:151], v[14:15] op_sel_hi:[1,0,1]
	v_pk_fma_f32 v[14:15], v[42:43], v[150:151], v[38:39] op_sel_hi:[1,0,1]
	v_pk_fma_f32 v[20:21], v[44:45], v[24:25], v[20:21] op_sel_hi:[1,0,1]
	v_pk_fma_f32 v[18:19], v[42:43], v[24:25], v[18:19] op_sel_hi:[1,0,1]
	v_pk_fma_f32 v[24:25], v[44:45], v[168:169], v[22:23] op_sel_hi:[1,0,1]
	v_pk_fma_f32 v[22:23], v[42:43], v[168:169], v[40:41] op_sel_hi:[1,0,1]
	v_pk_fma_f32 v[28:29], v[44:45], v[168:169], v[26:27] op_sel:[0,1,0]
	v_pk_fma_f32 v[26:27], v[42:43], v[168:169], v[46:47] op_sel:[0,1,0]
	v_pk_fma_f32 v[32:33], v[44:45], v[170:171], v[30:31] op_sel_hi:[1,0,1]
	v_pk_fma_f32 v[30:31], v[42:43], v[170:171], v[48:49] op_sel_hi:[1,0,1]
	ds_write_b128 v34, v[6:9] offset:49152
	ds_write_b128 v34, v[10:13] offset:50176
	ds_write_b128 v34, v[14:17] offset:51200
	ds_write_b128 v34, v[18:21] offset:52224
	ds_write_b128 v34, v[22:25] offset:53248
	ds_write_b128 v34, v[26:29] offset:54272
	ds_write_b128 v34, v[30:33] offset:55296
	ds_write_b128 v34, v[2:5] offset:56320
	v_lshlrev_b32_e32 v2, 10, v138
	v_add3_u32 v10, 0, v2, v0
	s_waitcnt lgkmcnt(0)
	s_barrier
	ds_read_b128 v[2:5], v10 offset:49152
	ds_read_b128 v[6:9], v10 offset:57344
	v_add_u32_e32 v18, 0xc000, v10
	ds_read_b128 v[10:13], v18 offset:16384
	s_waitcnt lgkmcnt(2)
	v_pk_add_f32 v[4:5], v[4:5], 0 op_sel_hi:[1,0]
	v_pk_add_f32 v[2:3], v[2:3], 0 op_sel_hi:[1,0]
	s_waitcnt lgkmcnt(1)
	v_pk_add_f32 v[8:9], v[4:5], v[8:9]
	v_pk_add_f32 v[14:15], v[2:3], v[6:7]
	ds_read_b128 v[2:5], v18 offset:24576
	s_waitcnt lgkmcnt(1)
	v_pk_add_f32 v[16:17], v[8:9], v[12:13]
	ds_read_b128 v[6:9], v18 offset:32768
	v_pk_add_f32 v[14:15], v[14:15], v[10:11]
	ds_read_b128 v[10:13], v18 offset:40960
	s_waitcnt lgkmcnt(2)
	v_pk_add_f32 v[4:5], v[16:17], v[4:5]
	v_pk_add_f32 v[2:3], v[14:15], v[2:3]
	s_waitcnt lgkmcnt(1)
	v_pk_add_f32 v[4:5], v[4:5], v[8:9]
	v_pk_add_f32 v[6:7], v[2:3], v[6:7]
	s_waitcnt lgkmcnt(0)
	v_pk_add_f32 v[12:13], v[4:5], v[12:13]
	ds_read_b128 v[2:5], v18 offset:49152
	v_pk_add_f32 v[14:15], v[6:7], v[10:11]
	v_add_u32_e32 v6, 1, v138
	v_cvt_f32_i32_e32 v7, v6
	ds_read_b128 v[8:11], v18 offset:57344
	s_waitcnt lgkmcnt(1)
	v_pk_add_f32 v[4:5], v[12:13], v[4:5]
	v_pk_add_f32 v[2:3], v[14:15], v[2:3]
	v_mul_f32_e32 v12, v145, v7
	v_cmp_gt_f32_e32 vcc, s75, v12
	s_waitcnt lgkmcnt(0)
	v_pk_add_f32 v[2:3], v[2:3], v[8:9]
	v_pk_add_f32 v[4:5], v[4:5], v[10:11]
	v_cndmask_b32_e32 v12, 0, v237, vcc
	v_fmac_f32_e32 v12, v145, v7
	v_exp_f32_e32 v7, v12
	v_cndmask_b32_e32 v8, 0, v240, vcc
	v_cmp_lt_i32_e32 vcc, -1, v138
	v_ldexp_f32 v8, v7, v8
	v_pk_mul_f32 v[4:5], v[8:9], v[4:5] op_sel_hi:[0,1]
	v_pk_mul_f32 v[2:3], v[8:9], v[2:3] op_sel_hi:[0,1]
	s_and_saveexec_b64 s[0:1], vcc
	s_cbranch_execz .LBB0_543
	s_add_i32 s6, 0, 0xa000
	v_add_u32_e32 v7, s6, v142
	s_add_i32 s6, 0, 0x4000
	v_lshl_add_u32 v8, v139, 4, s6
	s_mov_b64 s[6:7], 0
